# every MFMA block starts 8-byte aligned (s_nop padding before misaligned blocks), on top of v42
# speedup vs baseline: 1.0021x; 1.0021x over previous
.LBB0_221:
	s_waitcnt lgkmcnt(0)
	s_add_i32 s2, s58, 0x100
	s_add_i32 s3, s57, 0x100
	s_barrier
	s_setprio 1
	s_waitcnt lgkmcnt(7)
	s_nop 0
	v_mfma_f32_16x16x32_bf16 v[114:117], v[158:161], v[186:189], 0
	v_mfma_f32_16x16x32_bf16 v[110:113], v[150:153], v[186:189], 0
	s_waitcnt lgkmcnt(6)
	s_nop 0
	v_mfma_f32_16x16x32_bf16 v[106:109], v[158:161], v[178:181], 0
	v_mfma_f32_16x16x32_bf16 v[102:105], v[150:153], v[178:181], 0
	s_waitcnt lgkmcnt(3)
	s_nop 0
	v_mfma_f32_16x16x32_bf16 v[98:101], v[158:161], v[170:173], 0
	v_mfma_f32_16x16x32_bf16 v[94:97], v[150:153], v[170:173], 0
	s_waitcnt lgkmcnt(2)
	s_nop 0
	v_mfma_f32_16x16x32_bf16 v[90:93], v[158:161], v[162:165], 0
	v_mfma_f32_16x16x32_bf16 v[86:89], v[150:153], v[162:165], 0
	v_mfma_f32_16x16x32_bf16 v[114:117], v[154:157], v[190:193], v[114:117]
	v_mfma_f32_16x16x32_bf16 v[110:113], v[146:149], v[190:193], v[110:113]
	v_mfma_f32_16x16x32_bf16 v[106:109], v[154:157], v[182:185], v[106:109]
	v_mfma_f32_16x16x32_bf16 v[102:105], v[146:149], v[182:185], v[102:105]
	s_waitcnt lgkmcnt(1)
	s_nop 0
	v_mfma_f32_16x16x32_bf16 v[98:101], v[154:157], v[174:177], v[98:101]
	v_mfma_f32_16x16x32_bf16 v[94:97], v[146:149], v[174:177], v[94:97]
	s_waitcnt lgkmcnt(0)
	s_nop 0
	v_mfma_f32_16x16x32_bf16 v[90:93], v[154:157], v[166:169], v[90:93]
	v_mfma_f32_16x16x32_bf16 v[86:89], v[146:149], v[166:169], v[86:89]
	s_setprio 0
	s_setprio 1
	v_mfma_f32_16x16x32_bf16 v[82:85], v[142:145], v[186:189], 0
	v_mfma_f32_16x16x32_bf16 v[74:77], v[134:137], v[186:189], 0
	v_mfma_f32_16x16x32_bf16 v[70:73], v[142:145], v[178:181], 0
	v_mfma_f32_16x16x32_bf16 v[66:69], v[134:137], v[178:181], 0
	v_mfma_f32_16x16x32_bf16 v[62:65], v[142:145], v[170:173], 0
	v_mfma_f32_16x16x32_bf16 v[58:61], v[134:137], v[170:173], 0
	v_mfma_f32_16x16x32_bf16 v[54:57], v[142:145], v[162:165], 0
	v_mfma_f32_16x16x32_bf16 v[50:53], v[134:137], v[162:165], 0
	s_nop 0
	s_nop 0
	v_mfma_f32_16x16x32_bf16 v[82:85], v[138:141], v[190:193], v[82:85]
	v_mfma_f32_16x16x32_bf16 v[74:77], v[130:133], v[190:193], v[74:77]
	v_mfma_f32_16x16x32_bf16 v[70:73], v[138:141], v[182:185], v[70:73]
	v_mfma_f32_16x16x32_bf16 v[66:69], v[130:133], v[182:185], v[66:69]
	v_mfma_f32_16x16x32_bf16 v[62:65], v[138:141], v[174:177], v[62:65]
	v_mfma_f32_16x16x32_bf16 v[58:61], v[130:133], v[174:177], v[58:61]
	v_mfma_f32_16x16x32_bf16 v[54:57], v[138:141], v[166:169], v[54:57]
	v_mfma_f32_16x16x32_bf16 v[50:53], v[130:133], v[166:169], v[50:53]
	s_setprio 0
	s_barrier
	s_mov_b32 m0, s21
	ds_read_b128 v[186:189], v221 offset:16384
	ds_read_b128 v[178:181], v221 offset:18432
	ds_read_b128 v[190:193], v222 offset:16384
	ds_read_b128 v[182:185], v222 offset:18432
	ds_read_b128 v[170:173], v221 offset:20480
	ds_read_b128 v[162:165], v221 offset:22528
	ds_read_b128 v[174:177], v222 offset:20480
	ds_read_b128 v[166:169], v222 offset:22528
	buffer_load_dwordx4 v208, s[8:11], s3 offen lds
	s_mov_b32 m0, s22
	v_cndmask_b32_e64 v194, 0, 1, s[18:19]
	buffer_load_dwordx4 v210, s[8:11], s3 offen lds
	s_add_i32 s3, s57, 0x40100
	s_mov_b32 m0, s23
	s_andn2_b64 vcc, exec, s[18:19]
	buffer_load_dwordx4 v208, s[8:11], s3 offen lds
	s_mov_b32 m0, s24
	s_nop 0
	buffer_load_dwordx4 v210, s[8:11], s3 offen lds
	s_mov_b32 m0, s20
	s_nop 0
	buffer_load_dwordx4 v207, s[8:11], s2 offen lds
	s_mov_b32 m0, s25
	s_nop 0
	buffer_load_dwordx4 v209, s[8:11], s2 offen lds
	v_cmp_ne_u32_e64 s[2:3], 1, v194
	s_cbranch_vccnz .LBB0_250
	s_waitcnt vmcnt(14)
	s_cbranch_execnz .LBB0_224

.LBB0_224:
	s_waitcnt lgkmcnt(0)
	s_barrier
	s_setprio 1
	s_waitcnt lgkmcnt(7)
	v_mfma_f32_16x16x32_bf16 v[78:81], v[158:161], v[186:189], 0
	v_mfma_f32_16x16x32_bf16 v[46:49], v[150:153], v[186:189], 0
	s_waitcnt lgkmcnt(6)
	s_nop 0
	v_mfma_f32_16x16x32_bf16 v[42:45], v[158:161], v[178:181], 0
	v_mfma_f32_16x16x32_bf16 v[38:41], v[150:153], v[178:181], 0
	s_waitcnt lgkmcnt(3)
	s_nop 0
	v_mfma_f32_16x16x32_bf16 v[34:37], v[158:161], v[170:173], 0
	v_mfma_f32_16x16x32_bf16 v[30:33], v[150:153], v[170:173], 0
	s_waitcnt lgkmcnt(2)
	s_nop 0
	v_mfma_f32_16x16x32_bf16 v[26:29], v[158:161], v[162:165], 0
	v_mfma_f32_16x16x32_bf16 v[22:25], v[150:153], v[162:165], 0
	v_mfma_f32_16x16x32_bf16 v[78:81], v[154:157], v[190:193], v[78:81]
	v_mfma_f32_16x16x32_bf16 v[46:49], v[146:149], v[190:193], v[46:49]
	v_mfma_f32_16x16x32_bf16 v[42:45], v[154:157], v[182:185], v[42:45]
	v_mfma_f32_16x16x32_bf16 v[38:41], v[146:149], v[182:185], v[38:41]
	s_waitcnt lgkmcnt(1)
	s_nop 0
	v_mfma_f32_16x16x32_bf16 v[34:37], v[154:157], v[174:177], v[34:37]
	v_mfma_f32_16x16x32_bf16 v[30:33], v[146:149], v[174:177], v[30:33]
	s_waitcnt lgkmcnt(0)
	s_nop 0
	v_mfma_f32_16x16x32_bf16 v[26:29], v[154:157], v[166:169], v[26:29]
	v_mfma_f32_16x16x32_bf16 v[22:25], v[146:149], v[166:169], v[22:25]
	s_setprio 0
	s_setprio 1
	v_mfma_f32_16x16x32_bf16 v[18:21], v[142:145], v[186:189], 0
	v_mfma_f32_16x16x32_bf16 v[14:17], v[134:137], v[186:189], 0
	v_mfma_f32_16x16x32_bf16 v[10:13], v[142:145], v[178:181], 0
	v_mfma_f32_16x16x32_bf16 v[6:9], v[134:137], v[178:181], 0
	v_mfma_f32_16x16x32_bf16 v[2:5], v[142:145], v[170:173], 0
	v_mfma_f32_16x16x32_bf16 v[126:129], v[134:137], v[170:173], 0
	v_mfma_f32_16x16x32_bf16 v[122:125], v[142:145], v[162:165], 0
	v_mfma_f32_16x16x32_bf16 v[118:121], v[134:137], v[162:165], 0
	s_nop 0
	s_nop 0
	v_mfma_f32_16x16x32_bf16 v[18:21], v[138:141], v[190:193], v[18:21]
	v_mfma_f32_16x16x32_bf16 v[14:17], v[130:133], v[190:193], v[14:17]
	v_mfma_f32_16x16x32_bf16 v[10:13], v[138:141], v[182:185], v[10:13]
	v_mfma_f32_16x16x32_bf16 v[6:9], v[130:133], v[182:185], v[6:9]
	v_mfma_f32_16x16x32_bf16 v[2:5], v[138:141], v[174:177], v[2:5]
	v_mfma_f32_16x16x32_bf16 v[126:129], v[130:133], v[174:177], v[126:129]
	v_mfma_f32_16x16x32_bf16 v[122:125], v[138:141], v[166:169], v[122:125]
	v_mfma_f32_16x16x32_bf16 v[118:121], v[130:133], v[166:169], v[118:121]
	s_setprio 0
	s_barrier
	v_add_u32_e32 v194, s45, v211
	v_add_u32_e32 v225, s46, v211
	v_add_u32_e32 v229, s47, v211
	v_add_u32_e32 v231, s48, v211
	v_add_u32_e32 v224, s45, v212
	ds_read_b128 v[146:149], v194
	ds_read_b128 v[150:153], v224
	v_add_u32_e32 v228, s46, v212
	ds_read_b128 v[154:157], v225
	ds_read_b128 v[158:161], v228
	v_add_u32_e32 v230, s47, v212
	ds_read_b128 v[130:133], v229
	ds_read_b128 v[134:137], v230
	v_add_u32_e32 v233, s48, v212
	ds_read_b128 v[138:141], v231
	ds_read_b128 v[142:145], v233
	s_mov_b32 m0, s26
	s_add_i32 s4, s58, 0x2100
	ds_read_b128 v[186:189], v221 offset:32768
	ds_read_b128 v[174:177], v221 offset:34816
	ds_read_b128 v[190:193], v222 offset:32768
	ds_read_b128 v[178:181], v222 offset:34816
	ds_read_b128 v[170:173], v221 offset:36864
	ds_read_b128 v[162:165], v221 offset:38912
	ds_read_b128 v[182:185], v222 offset:36864
	ds_read_b128 v[166:169], v222 offset:38912
	buffer_load_dwordx4 v207, s[8:11], s4 offen lds
	s_mov_b32 m0, s27
	s_and_b64 vcc, exec, s[2:3]
	buffer_load_dwordx4 v209, s[8:11], s4 offen lds
	s_cbranch_vccnz .LBB0_251
	s_waitcnt vmcnt(16)
	s_cbranch_execnz .LBB0_227

.LBB0_227:
	s_waitcnt lgkmcnt(0)
	s_add_i32 s18, s58, 0x180
	s_add_i32 s19, s57, 0x180
	s_barrier
	s_setprio 1
	s_waitcnt lgkmcnt(7)
	s_nop 0
	v_mfma_f32_16x16x32_bf16 v[114:117], v[146:149], v[186:189], v[114:117]
	v_mfma_f32_16x16x32_bf16 v[110:113], v[154:157], v[186:189], v[110:113]
	s_waitcnt lgkmcnt(6)
	s_nop 0
	v_mfma_f32_16x16x32_bf16 v[106:109], v[146:149], v[174:177], v[106:109]
	v_mfma_f32_16x16x32_bf16 v[102:105], v[154:157], v[174:177], v[102:105]
	s_waitcnt lgkmcnt(3)
	s_nop 0
	v_mfma_f32_16x16x32_bf16 v[98:101], v[146:149], v[170:173], v[98:101]
	v_mfma_f32_16x16x32_bf16 v[94:97], v[154:157], v[170:173], v[94:97]
	s_waitcnt lgkmcnt(2)
	s_nop 0
	v_mfma_f32_16x16x32_bf16 v[90:93], v[146:149], v[162:165], v[90:93]
	v_mfma_f32_16x16x32_bf16 v[86:89], v[154:157], v[162:165], v[86:89]
	v_mfma_f32_16x16x32_bf16 v[114:117], v[150:153], v[190:193], v[114:117]
	v_mfma_f32_16x16x32_bf16 v[110:113], v[158:161], v[190:193], v[110:113]
	v_mfma_f32_16x16x32_bf16 v[106:109], v[150:153], v[178:181], v[106:109]
	v_mfma_f32_16x16x32_bf16 v[102:105], v[158:161], v[178:181], v[102:105]
	s_waitcnt lgkmcnt(1)
	s_nop 0
	v_mfma_f32_16x16x32_bf16 v[98:101], v[150:153], v[182:185], v[98:101]
	v_mfma_f32_16x16x32_bf16 v[94:97], v[158:161], v[182:185], v[94:97]
	s_waitcnt lgkmcnt(0)
	s_nop 0
	v_mfma_f32_16x16x32_bf16 v[90:93], v[150:153], v[166:169], v[90:93]
	v_mfma_f32_16x16x32_bf16 v[86:89], v[158:161], v[166:169], v[86:89]
	s_setprio 0
	s_setprio 1
	v_mfma_f32_16x16x32_bf16 v[82:85], v[130:133], v[186:189], v[82:85]
	v_mfma_f32_16x16x32_bf16 v[74:77], v[138:141], v[186:189], v[74:77]
	v_mfma_f32_16x16x32_bf16 v[70:73], v[130:133], v[174:177], v[70:73]
	v_mfma_f32_16x16x32_bf16 v[66:69], v[138:141], v[174:177], v[66:69]
	v_mfma_f32_16x16x32_bf16 v[62:65], v[130:133], v[170:173], v[62:65]
	v_mfma_f32_16x16x32_bf16 v[58:61], v[138:141], v[170:173], v[58:61]
	v_mfma_f32_16x16x32_bf16 v[54:57], v[130:133], v[162:165], v[54:57]
	v_mfma_f32_16x16x32_bf16 v[50:53], v[138:141], v[162:165], v[50:53]
	v_mfma_f32_16x16x32_bf16 v[82:85], v[134:137], v[190:193], v[82:85]
	v_mfma_f32_16x16x32_bf16 v[74:77], v[142:145], v[190:193], v[74:77]
	v_mfma_f32_16x16x32_bf16 v[70:73], v[134:137], v[178:181], v[70:73]
	v_mfma_f32_16x16x32_bf16 v[66:69], v[142:145], v[178:181], v[66:69]
	v_mfma_f32_16x16x32_bf16 v[62:65], v[134:137], v[182:185], v[62:65]
	v_mfma_f32_16x16x32_bf16 v[58:61], v[142:145], v[182:185], v[58:61]
	v_mfma_f32_16x16x32_bf16 v[54:57], v[134:137], v[166:169], v[54:57]
	v_mfma_f32_16x16x32_bf16 v[50:53], v[142:145], v[166:169], v[50:53]
	s_setprio 0
	s_barrier
	s_mov_b32 m0, s29
	s_mov_b32 s4, s70
	ds_read_b128 v[186:189], v221 offset:49152
	ds_read_b128 v[174:177], v221 offset:51200
	ds_read_b128 v[190:193], v222 offset:49152
	ds_read_b128 v[178:181], v222 offset:51200
	ds_read_b128 v[170:173], v221 offset:53248
	ds_read_b128 v[162:165], v221 offset:55296
	ds_read_b128 v[182:185], v222 offset:53248
	ds_read_b128 v[166:169], v222 offset:55296
	buffer_load_dwordx4 v208, s[4:7], s19 offen lds
	s_mov_b32 m0, s30
	s_and_b64 vcc, exec, s[2:3]
	buffer_load_dwordx4 v210, s[4:7], s19 offen lds
	s_add_i32 s19, s57, 0x40180
	s_mov_b32 m0, s35
	s_nop 0
	buffer_load_dwordx4 v208, s[4:7], s19 offen lds
	s_mov_b32 m0, s36
	s_nop 0
	buffer_load_dwordx4 v210, s[4:7], s19 offen lds
	s_mov_b32 m0, s31
	s_nop 0
	buffer_load_dwordx4 v207, s[4:7], s18 offen lds
	s_mov_b32 m0, s34
	s_nop 0
	buffer_load_dwordx4 v209, s[4:7], s18 offen lds
	s_cbranch_vccnz .LBB0_252
	s_waitcnt vmcnt(22)
	s_cbranch_execnz .LBB0_230

.LBB0_230:
	s_waitcnt lgkmcnt(0)
	s_barrier
	s_setprio 1
	s_waitcnt lgkmcnt(7)
	v_mfma_f32_16x16x32_bf16 v[78:81], v[146:149], v[186:189], v[78:81]
	v_mfma_f32_16x16x32_bf16 v[46:49], v[154:157], v[186:189], v[46:49]
	s_waitcnt lgkmcnt(6)
	s_nop 0
	v_mfma_f32_16x16x32_bf16 v[42:45], v[146:149], v[174:177], v[42:45]
	v_mfma_f32_16x16x32_bf16 v[38:41], v[154:157], v[174:177], v[38:41]
	s_waitcnt lgkmcnt(3)
	s_nop 0
	v_mfma_f32_16x16x32_bf16 v[34:37], v[146:149], v[170:173], v[34:37]
	v_mfma_f32_16x16x32_bf16 v[30:33], v[154:157], v[170:173], v[30:33]
	s_waitcnt lgkmcnt(2)
	s_nop 0
	v_mfma_f32_16x16x32_bf16 v[26:29], v[146:149], v[162:165], v[26:29]
	v_mfma_f32_16x16x32_bf16 v[22:25], v[154:157], v[162:165], v[22:25]
	v_mfma_f32_16x16x32_bf16 v[78:81], v[150:153], v[190:193], v[78:81]
	v_mfma_f32_16x16x32_bf16 v[46:49], v[158:161], v[190:193], v[46:49]
	v_mfma_f32_16x16x32_bf16 v[42:45], v[150:153], v[178:181], v[42:45]
	v_mfma_f32_16x16x32_bf16 v[38:41], v[158:161], v[178:181], v[38:41]
	s_waitcnt lgkmcnt(1)
	s_nop 0
	v_mfma_f32_16x16x32_bf16 v[34:37], v[150:153], v[182:185], v[34:37]
	v_mfma_f32_16x16x32_bf16 v[30:33], v[158:161], v[182:185], v[30:33]
	s_waitcnt lgkmcnt(0)
	s_nop 0
	v_mfma_f32_16x16x32_bf16 v[26:29], v[150:153], v[166:169], v[26:29]
	v_mfma_f32_16x16x32_bf16 v[22:25], v[158:161], v[166:169], v[22:25]
	s_setprio 0
	s_setprio 1
	v_mfma_f32_16x16x32_bf16 v[18:21], v[130:133], v[186:189], v[18:21]
	v_mfma_f32_16x16x32_bf16 v[14:17], v[138:141], v[186:189], v[14:17]
	v_mfma_f32_16x16x32_bf16 v[10:13], v[130:133], v[174:177], v[10:13]
	v_mfma_f32_16x16x32_bf16 v[6:9], v[138:141], v[174:177], v[6:9]
	v_mfma_f32_16x16x32_bf16 v[2:5], v[130:133], v[170:173], v[2:5]
	v_mfma_f32_16x16x32_bf16 v[126:129], v[138:141], v[170:173], v[126:129]
	v_mfma_f32_16x16x32_bf16 v[122:125], v[130:133], v[162:165], v[122:125]
	v_mfma_f32_16x16x32_bf16 v[118:121], v[138:141], v[162:165], v[118:121]
	v_mfma_f32_16x16x32_bf16 v[18:21], v[134:137], v[190:193], v[18:21]
	v_mfma_f32_16x16x32_bf16 v[14:17], v[142:145], v[190:193], v[14:17]
	v_mfma_f32_16x16x32_bf16 v[10:13], v[134:137], v[178:181], v[10:13]
	v_mfma_f32_16x16x32_bf16 v[6:9], v[142:145], v[178:181], v[6:9]
	v_mfma_f32_16x16x32_bf16 v[2:5], v[134:137], v[182:185], v[2:5]
	v_mfma_f32_16x16x32_bf16 v[126:129], v[142:145], v[182:185], v[126:129]
	v_mfma_f32_16x16x32_bf16 v[122:125], v[134:137], v[166:169], v[122:125]
	v_mfma_f32_16x16x32_bf16 v[118:121], v[142:145], v[166:169], v[118:121]
	s_setprio 0
	s_barrier
	s_add_i32 s28, s28, 1
	s_mul_i32 s2, s28, s43
	s_mul_hi_u32 s3, s28, s94
	s_add_i32 s3, s3, s2
	s_mul_i32 s2, s28, s94
	s_add_u32 s18, s2, s95
	s_addc_u32 s19, s3, s44
	v_cmp_gt_i64_e32 vcc, s[18:19], v[198:199]
	v_cmp_lt_i64_e64 s[2:3], s[18:19], v[196:197]
	s_cbranch_vccnz .LBB0_232
	s_ashr_i32 s4, s18, 31
	s_lshr_b32 s4, s4, 29
	s_add_i32 s4, s18, s4
	s_ashr_i32 s19, s4, 3
	s_and_b32 s4, s4, -8
	s_sub_i32 s4, s18, s4
	s_cmp_lt_i32 s4, 0
	s_cselect_b32 s18, s49, 0x240
	s_mul_i32 s4, s4, s18
	s_add_i32 s4, s4, s19
	s_mul_hi_i32 s18, s4, 0x38e38e39
	s_lshr_b32 s19, s18, 31
	s_ashr_i32 s18, s18, 5
	s_add_i32 s18, s18, s19
	s_lshl_b32 s19, s18, 3
	s_sub_i32 s33, 0x100, s19
	s_min_i32 s33, s33, 8
	s_abs_i32 s51, s33
	v_cvt_f32_u32_e32 v130, s51
	s_sub_i32 s53, 0, s51
	s_mulk_i32 s18, 0x90
	s_sub_i32 s4, s4, s18
	v_rcp_iflag_f32_e32 v130, v130
	s_abs_i32 s18, s4
	s_xor_b32 s52, s4, s33
	s_ashr_i32 s52, s52, 31
	v_mul_f32_e32 v130, 0x4f7ffffe, v130
	v_cvt_u32_f32_e32 v130, v130
	s_nop 0
	v_readfirstlane_b32 s54, v130
	s_mul_i32 s53, s53, s54
	s_mul_hi_u32 s53, s54, s53
	s_add_i32 s54, s54, s53
	s_mul_hi_u32 s53, s18, s54
	s_mul_i32 s54, s53, s51
	s_sub_i32 s18, s18, s54
	s_add_i32 s59, s53, 1
	s_sub_i32 s54, s18, s51
	s_cmp_ge_u32 s18, s51
	s_cselect_b32 s53, s59, s53
	s_cselect_b32 s18, s54, s18
	s_add_i32 s54, s53, 1
	s_cmp_ge_u32 s18, s51
	s_cselect_b32 s18, s54, s53
	s_xor_b32 s18, s18, s52
	s_sub_i32 s51, s18, s52
	s_mul_i32 s18, s51, s33
	s_sub_i32 s4, s4, s18
	s_add_i32 s52, s19, s4

.LBB0_233:
	ds_read_b128 v[130:133], v213
	ds_read_b128 v[134:137], v214
	ds_read_b128 v[138:141], v215
	ds_read_b128 v[142:145], v216
	ds_read_b128 v[146:149], v217
	ds_read_b128 v[150:153], v218
	ds_read_b128 v[154:157], v219
	ds_read_b128 v[158:161], v220
	s_add_i32 s4, s33, 0xffffe080
	s_cmp_eq_u32 s58, 12
	s_cselect_b32 s61, s18, s4
	s_cselect_b32 s60, s19, s57
	s_add_i32 s59, s61, 0x80
	s_mov_b32 s4, s70
	s_mov_b32 m0, s38
	ds_read_b128 v[162:165], v221
	ds_read_b128 v[166:169], v221 offset:2048
	ds_read_b128 v[170:173], v222
	ds_read_b128 v[174:177], v222 offset:2048
	ds_read_b128 v[178:181], v221 offset:4096
	ds_read_b128 v[182:185], v221 offset:6144
	ds_read_b128 v[186:189], v222 offset:4096
	ds_read_b128 v[190:193], v222 offset:6144
	buffer_load_dwordx4 v207, s[4:7], s33 offen lds
	s_mov_b32 m0, s41
	s_nop 0
	buffer_load_dwordx4 v209, s[4:7], s33 offen lds
	s_waitcnt vmcnt(8)
	s_waitcnt lgkmcnt(0)
	s_barrier
	s_setprio 1
	s_waitcnt lgkmcnt(7)
	v_mfma_f32_16x16x32_bf16 v[114:117], v[130:133], v[162:165], v[114:117]
	v_mfma_f32_16x16x32_bf16 v[110:113], v[138:141], v[162:165], v[110:113]
	s_waitcnt lgkmcnt(6)
	s_nop 0
	v_mfma_f32_16x16x32_bf16 v[106:109], v[130:133], v[166:169], v[106:109]
	v_mfma_f32_16x16x32_bf16 v[102:105], v[138:141], v[166:169], v[102:105]
	s_waitcnt lgkmcnt(3)
	s_nop 0
	v_mfma_f32_16x16x32_bf16 v[98:101], v[130:133], v[178:181], v[98:101]
	v_mfma_f32_16x16x32_bf16 v[94:97], v[138:141], v[178:181], v[94:97]
	s_waitcnt lgkmcnt(2)
	s_nop 0
	v_mfma_f32_16x16x32_bf16 v[90:93], v[130:133], v[182:185], v[90:93]
	v_mfma_f32_16x16x32_bf16 v[86:89], v[138:141], v[182:185], v[86:89]
	v_mfma_f32_16x16x32_bf16 v[114:117], v[134:137], v[170:173], v[114:117]
	v_mfma_f32_16x16x32_bf16 v[110:113], v[142:145], v[170:173], v[110:113]
	v_mfma_f32_16x16x32_bf16 v[106:109], v[134:137], v[174:177], v[106:109]
	v_mfma_f32_16x16x32_bf16 v[102:105], v[142:145], v[174:177], v[102:105]
	s_waitcnt lgkmcnt(1)
	s_nop 0
	v_mfma_f32_16x16x32_bf16 v[98:101], v[134:137], v[186:189], v[98:101]
	v_mfma_f32_16x16x32_bf16 v[94:97], v[142:145], v[186:189], v[94:97]
	s_waitcnt lgkmcnt(0)
	s_nop 0
	v_mfma_f32_16x16x32_bf16 v[90:93], v[134:137], v[190:193], v[90:93]
	v_mfma_f32_16x16x32_bf16 v[86:89], v[142:145], v[190:193], v[86:89]
	s_setprio 0
	s_setprio 1
	v_mfma_f32_16x16x32_bf16 v[82:85], v[146:149], v[162:165], v[82:85]
	v_mfma_f32_16x16x32_bf16 v[74:77], v[154:157], v[162:165], v[74:77]
	v_mfma_f32_16x16x32_bf16 v[70:73], v[146:149], v[166:169], v[70:73]
	v_mfma_f32_16x16x32_bf16 v[66:69], v[154:157], v[166:169], v[66:69]
	v_mfma_f32_16x16x32_bf16 v[62:65], v[146:149], v[178:181], v[62:65]
	v_mfma_f32_16x16x32_bf16 v[58:61], v[154:157], v[178:181], v[58:61]
	v_mfma_f32_16x16x32_bf16 v[54:57], v[146:149], v[182:185], v[54:57]
	v_mfma_f32_16x16x32_bf16 v[50:53], v[154:157], v[182:185], v[50:53]
	v_mfma_f32_16x16x32_bf16 v[82:85], v[150:153], v[170:173], v[82:85]
	v_mfma_f32_16x16x32_bf16 v[74:77], v[158:161], v[170:173], v[74:77]
	v_mfma_f32_16x16x32_bf16 v[70:73], v[150:153], v[174:177], v[70:73]
	v_mfma_f32_16x16x32_bf16 v[66:69], v[158:161], v[174:177], v[66:69]
	v_mfma_f32_16x16x32_bf16 v[62:65], v[150:153], v[186:189], v[62:65]
	v_mfma_f32_16x16x32_bf16 v[58:61], v[158:161], v[186:189], v[58:61]
	v_mfma_f32_16x16x32_bf16 v[54:57], v[150:153], v[190:193], v[54:57]
	v_mfma_f32_16x16x32_bf16 v[50:53], v[158:161], v[190:193], v[50:53]
	s_setprio 0
	s_barrier
	s_mov_b32 m0, s21
	ds_read_b128 v[162:165], v221 offset:16384
	ds_read_b128 v[166:169], v221 offset:18432
	ds_read_b128 v[170:173], v222 offset:16384
	ds_read_b128 v[174:177], v222 offset:18432
	ds_read_b128 v[178:181], v221 offset:20480
	ds_read_b128 v[182:185], v221 offset:22528
	ds_read_b128 v[186:189], v222 offset:20480
	ds_read_b128 v[190:193], v222 offset:22528
	buffer_load_dwordx4 v208, s[4:7], s60 offen lds
	s_mov_b32 m0, s22
	s_add_i32 s62, s60, 0x40000
	buffer_load_dwordx4 v210, s[4:7], s60 offen lds
	s_mov_b32 m0, s23
	s_nop 0
	buffer_load_dwordx4 v208, s[4:7], s62 offen lds
	s_mov_b32 m0, s24
	s_nop 0
	buffer_load_dwordx4 v210, s[4:7], s62 offen lds
	s_mov_b32 m0, s20
	s_nop 0
	buffer_load_dwordx4 v207, s[4:7], s61 offen lds
	s_mov_b32 m0, s25
	s_nop 0
	buffer_load_dwordx4 v209, s[4:7], s61 offen lds
	s_waitcnt vmcnt(8)
	s_waitcnt lgkmcnt(0)
	s_barrier
	s_setprio 1
	s_waitcnt lgkmcnt(7)
	s_nop 0
	v_mfma_f32_16x16x32_bf16 v[78:81], v[130:133], v[162:165], v[78:81]
	v_mfma_f32_16x16x32_bf16 v[46:49], v[138:141], v[162:165], v[46:49]
	s_waitcnt lgkmcnt(6)
	s_nop 0
	v_mfma_f32_16x16x32_bf16 v[42:45], v[130:133], v[166:169], v[42:45]
	v_mfma_f32_16x16x32_bf16 v[38:41], v[138:141], v[166:169], v[38:41]
	s_waitcnt lgkmcnt(3)
	s_nop 0
	v_mfma_f32_16x16x32_bf16 v[34:37], v[130:133], v[178:181], v[34:37]
	v_mfma_f32_16x16x32_bf16 v[30:33], v[138:141], v[178:181], v[30:33]
	s_waitcnt lgkmcnt(2)
	s_nop 0
	v_mfma_f32_16x16x32_bf16 v[26:29], v[130:133], v[182:185], v[26:29]
	v_mfma_f32_16x16x32_bf16 v[22:25], v[138:141], v[182:185], v[22:25]
	v_mfma_f32_16x16x32_bf16 v[78:81], v[134:137], v[170:173], v[78:81]
	v_mfma_f32_16x16x32_bf16 v[46:49], v[142:145], v[170:173], v[46:49]
	v_mfma_f32_16x16x32_bf16 v[42:45], v[134:137], v[174:177], v[42:45]
	v_mfma_f32_16x16x32_bf16 v[38:41], v[142:145], v[174:177], v[38:41]
	s_waitcnt lgkmcnt(1)
	s_nop 0
	v_mfma_f32_16x16x32_bf16 v[34:37], v[134:137], v[186:189], v[34:37]
	v_mfma_f32_16x16x32_bf16 v[30:33], v[142:145], v[186:189], v[30:33]
	s_waitcnt lgkmcnt(0)
	s_nop 0
	v_mfma_f32_16x16x32_bf16 v[26:29], v[134:137], v[190:193], v[26:29]
	v_mfma_f32_16x16x32_bf16 v[22:25], v[142:145], v[190:193], v[22:25]
	s_setprio 0
	s_setprio 1
	v_mfma_f32_16x16x32_bf16 v[18:21], v[146:149], v[162:165], v[18:21]
	v_mfma_f32_16x16x32_bf16 v[14:17], v[154:157], v[162:165], v[14:17]
	v_mfma_f32_16x16x32_bf16 v[10:13], v[146:149], v[166:169], v[10:13]
	v_mfma_f32_16x16x32_bf16 v[6:9], v[154:157], v[166:169], v[6:9]
	v_mfma_f32_16x16x32_bf16 v[2:5], v[146:149], v[178:181], v[2:5]
	v_mfma_f32_16x16x32_bf16 v[126:129], v[154:157], v[178:181], v[126:129]
	v_mfma_f32_16x16x32_bf16 v[122:125], v[146:149], v[182:185], v[122:125]
	v_mfma_f32_16x16x32_bf16 v[118:121], v[154:157], v[182:185], v[118:121]
	v_mfma_f32_16x16x32_bf16 v[18:21], v[150:153], v[170:173], v[18:21]
	v_mfma_f32_16x16x32_bf16 v[14:17], v[158:161], v[170:173], v[14:17]
	v_mfma_f32_16x16x32_bf16 v[10:13], v[150:153], v[174:177], v[10:13]
	v_mfma_f32_16x16x32_bf16 v[6:9], v[158:161], v[174:177], v[6:9]
	v_mfma_f32_16x16x32_bf16 v[2:5], v[150:153], v[186:189], v[2:5]
	v_mfma_f32_16x16x32_bf16 v[126:129], v[158:161], v[186:189], v[126:129]
	v_mfma_f32_16x16x32_bf16 v[122:125], v[150:153], v[190:193], v[122:125]
	v_mfma_f32_16x16x32_bf16 v[118:121], v[158:161], v[190:193], v[118:121]
	s_setprio 0
	s_barrier
	ds_read_b128 v[130:133], v194
	ds_read_b128 v[134:137], v224
	ds_read_b128 v[138:141], v225
	ds_read_b128 v[142:145], v228
	ds_read_b128 v[146:149], v229
	ds_read_b128 v[150:153], v230
	ds_read_b128 v[154:157], v231
	ds_read_b128 v[158:161], v233
	s_addk_i32 s61, 0x2000
	s_mov_b32 m0, s26
	ds_read_b128 v[162:165], v221 offset:32768
	ds_read_b128 v[166:169], v221 offset:34816
	ds_read_b128 v[170:173], v222 offset:32768
	ds_read_b128 v[174:177], v222 offset:34816
	ds_read_b128 v[178:181], v221 offset:36864
	ds_read_b128 v[182:185], v221 offset:38912
	ds_read_b128 v[186:189], v222 offset:36864
	ds_read_b128 v[190:193], v222 offset:38912
	buffer_load_dwordx4 v207, s[4:7], s61 offen lds
	s_mov_b32 m0, s27
	s_nop 0
	buffer_load_dwordx4 v209, s[4:7], s61 offen lds
	s_waitcnt vmcnt(8)
	s_waitcnt lgkmcnt(0)
	s_barrier
	s_setprio 1
	s_waitcnt lgkmcnt(7)
	s_nop 0
	v_mfma_f32_16x16x32_bf16 v[114:117], v[130:133], v[162:165], v[114:117]
	v_mfma_f32_16x16x32_bf16 v[110:113], v[138:141], v[162:165], v[110:113]
	s_waitcnt lgkmcnt(6)
	s_nop 0
	v_mfma_f32_16x16x32_bf16 v[106:109], v[130:133], v[166:169], v[106:109]
	v_mfma_f32_16x16x32_bf16 v[102:105], v[138:141], v[166:169], v[102:105]
	s_waitcnt lgkmcnt(3)
	s_nop 0
	v_mfma_f32_16x16x32_bf16 v[98:101], v[130:133], v[178:181], v[98:101]
	v_mfma_f32_16x16x32_bf16 v[94:97], v[138:141], v[178:181], v[94:97]
	s_waitcnt lgkmcnt(2)
	s_nop 0
	v_mfma_f32_16x16x32_bf16 v[90:93], v[130:133], v[182:185], v[90:93]
	v_mfma_f32_16x16x32_bf16 v[86:89], v[138:141], v[182:185], v[86:89]
	v_mfma_f32_16x16x32_bf16 v[114:117], v[134:137], v[170:173], v[114:117]
	v_mfma_f32_16x16x32_bf16 v[110:113], v[142:145], v[170:173], v[110:113]
	v_mfma_f32_16x16x32_bf16 v[106:109], v[134:137], v[174:177], v[106:109]
	v_mfma_f32_16x16x32_bf16 v[102:105], v[142:145], v[174:177], v[102:105]
	s_waitcnt lgkmcnt(1)
	s_nop 0
	v_mfma_f32_16x16x32_bf16 v[98:101], v[134:137], v[186:189], v[98:101]
	v_mfma_f32_16x16x32_bf16 v[94:97], v[142:145], v[186:189], v[94:97]
	s_waitcnt lgkmcnt(0)
	s_nop 0
	v_mfma_f32_16x16x32_bf16 v[90:93], v[134:137], v[190:193], v[90:93]
	v_mfma_f32_16x16x32_bf16 v[86:89], v[142:145], v[190:193], v[86:89]
	s_setprio 0
	s_setprio 1
	v_mfma_f32_16x16x32_bf16 v[82:85], v[146:149], v[162:165], v[82:85]
	v_mfma_f32_16x16x32_bf16 v[74:77], v[154:157], v[162:165], v[74:77]
	v_mfma_f32_16x16x32_bf16 v[70:73], v[146:149], v[166:169], v[70:73]
	v_mfma_f32_16x16x32_bf16 v[66:69], v[154:157], v[166:169], v[66:69]
	v_mfma_f32_16x16x32_bf16 v[62:65], v[146:149], v[178:181], v[62:65]
	v_mfma_f32_16x16x32_bf16 v[58:61], v[154:157], v[178:181], v[58:61]
	v_mfma_f32_16x16x32_bf16 v[54:57], v[146:149], v[182:185], v[54:57]
	v_mfma_f32_16x16x32_bf16 v[50:53], v[154:157], v[182:185], v[50:53]
	v_mfma_f32_16x16x32_bf16 v[82:85], v[150:153], v[170:173], v[82:85]
	v_mfma_f32_16x16x32_bf16 v[74:77], v[158:161], v[170:173], v[74:77]
	v_mfma_f32_16x16x32_bf16 v[70:73], v[150:153], v[174:177], v[70:73]
	v_mfma_f32_16x16x32_bf16 v[66:69], v[158:161], v[174:177], v[66:69]
	v_mfma_f32_16x16x32_bf16 v[62:65], v[150:153], v[186:189], v[62:65]
	v_mfma_f32_16x16x32_bf16 v[58:61], v[158:161], v[186:189], v[58:61]
	v_mfma_f32_16x16x32_bf16 v[54:57], v[150:153], v[190:193], v[54:57]
	v_mfma_f32_16x16x32_bf16 v[50:53], v[158:161], v[190:193], v[50:53]
	s_setprio 0
	s_barrier
	s_mov_b32 m0, s29
	s_add_i32 s61, s60, 0x80
	ds_read_b128 v[162:165], v221 offset:49152
	ds_read_b128 v[166:169], v221 offset:51200
	ds_read_b128 v[170:173], v222 offset:49152
	ds_read_b128 v[174:177], v222 offset:51200
	ds_read_b128 v[178:181], v221 offset:53248
	ds_read_b128 v[182:185], v221 offset:55296
	ds_read_b128 v[186:189], v222 offset:53248
	ds_read_b128 v[190:193], v222 offset:55296
	buffer_load_dwordx4 v208, s[4:7], s61 offen lds
	s_mov_b32 m0, s30
	s_add_i32 s60, s60, 0x40080
	buffer_load_dwordx4 v210, s[4:7], s61 offen lds
	s_mov_b32 m0, s35
	s_nop 0
	buffer_load_dwordx4 v208, s[4:7], s60 offen lds
	s_mov_b32 m0, s36
	s_nop 0
	buffer_load_dwordx4 v210, s[4:7], s60 offen lds
	s_mov_b32 m0, s31
	s_nop 0
	buffer_load_dwordx4 v207, s[4:7], s59 offen lds
	s_mov_b32 m0, s34
	s_nop 0
	buffer_load_dwordx4 v209, s[4:7], s59 offen lds
	s_waitcnt vmcnt(8)
	s_waitcnt lgkmcnt(0)
	s_barrier
	s_setprio 1
	s_waitcnt lgkmcnt(7)
	s_nop 0
	v_mfma_f32_16x16x32_bf16 v[78:81], v[130:133], v[162:165], v[78:81]
	v_mfma_f32_16x16x32_bf16 v[46:49], v[138:141], v[162:165], v[46:49]
	s_waitcnt lgkmcnt(6)
	s_nop 0
	v_mfma_f32_16x16x32_bf16 v[42:45], v[130:133], v[166:169], v[42:45]
	v_mfma_f32_16x16x32_bf16 v[38:41], v[138:141], v[166:169], v[38:41]
	s_waitcnt lgkmcnt(3)
	s_nop 0
	v_mfma_f32_16x16x32_bf16 v[34:37], v[130:133], v[178:181], v[34:37]
	v_mfma_f32_16x16x32_bf16 v[30:33], v[138:141], v[178:181], v[30:33]
	s_waitcnt lgkmcnt(2)
	s_nop 0
	v_mfma_f32_16x16x32_bf16 v[26:29], v[130:133], v[182:185], v[26:29]
	v_mfma_f32_16x16x32_bf16 v[22:25], v[138:141], v[182:185], v[22:25]
	v_mfma_f32_16x16x32_bf16 v[78:81], v[134:137], v[170:173], v[78:81]
	v_mfma_f32_16x16x32_bf16 v[46:49], v[142:145], v[170:173], v[46:49]
	v_mfma_f32_16x16x32_bf16 v[42:45], v[134:137], v[174:177], v[42:45]
	v_mfma_f32_16x16x32_bf16 v[38:41], v[142:145], v[174:177], v[38:41]
	s_waitcnt lgkmcnt(1)
	s_nop 0
	v_mfma_f32_16x16x32_bf16 v[34:37], v[134:137], v[186:189], v[34:37]
	v_mfma_f32_16x16x32_bf16 v[30:33], v[142:145], v[186:189], v[30:33]
	s_waitcnt lgkmcnt(0)
	s_nop 0
	v_mfma_f32_16x16x32_bf16 v[26:29], v[134:137], v[190:193], v[26:29]
	v_mfma_f32_16x16x32_bf16 v[22:25], v[142:145], v[190:193], v[22:25]
	s_setprio 0
	s_setprio 1
	v_mfma_f32_16x16x32_bf16 v[18:21], v[146:149], v[162:165], v[18:21]
	v_mfma_f32_16x16x32_bf16 v[14:17], v[154:157], v[162:165], v[14:17]
	v_mfma_f32_16x16x32_bf16 v[10:13], v[146:149], v[166:169], v[10:13]
	v_mfma_f32_16x16x32_bf16 v[6:9], v[154:157], v[166:169], v[6:9]
	v_mfma_f32_16x16x32_bf16 v[2:5], v[146:149], v[178:181], v[2:5]
	v_mfma_f32_16x16x32_bf16 v[126:129], v[154:157], v[178:181], v[126:129]
	v_mfma_f32_16x16x32_bf16 v[122:125], v[146:149], v[182:185], v[122:125]
	v_mfma_f32_16x16x32_bf16 v[118:121], v[154:157], v[182:185], v[118:121]
	v_mfma_f32_16x16x32_bf16 v[18:21], v[150:153], v[170:173], v[18:21]
	v_mfma_f32_16x16x32_bf16 v[14:17], v[158:161], v[170:173], v[14:17]
	v_mfma_f32_16x16x32_bf16 v[10:13], v[150:153], v[174:177], v[10:13]
	v_mfma_f32_16x16x32_bf16 v[6:9], v[158:161], v[174:177], v[6:9]
	v_mfma_f32_16x16x32_bf16 v[2:5], v[150:153], v[186:189], v[2:5]
	v_mfma_f32_16x16x32_bf16 v[126:129], v[158:161], v[186:189], v[126:129]
	v_mfma_f32_16x16x32_bf16 v[122:125], v[150:153], v[190:193], v[122:125]
	v_mfma_f32_16x16x32_bf16 v[118:121], v[158:161], v[190:193], v[118:121]
	s_setprio 0
	s_barrier
	s_add_i32 s58, s58, 2
	s_addk_i32 s33, 0x100
	s_addk_i32 s57, 0x100
	s_cmp_gt_u32 s58, 13
	s_cbranch_scc0 .LBB0_233
	s_and_b64 vcc, exec, s[16:17]
	s_cbranch_vccz .LBB0_236
	s_barrier

.LBB0_271:
	s_waitcnt lgkmcnt(13)
	s_nop 0
	v_mfma_scale_f32_16x16x128_f8f6f4 v[222:225], v[18:25], v[82:89], v[222:225], v250, v249 op_sel_hi:[0,0,0]
	s_waitcnt lgkmcnt(0)
	s_add_i32 s16, s56, 0x80
	s_add_i32 s17, s33, 0x80
	s_barrier
	v_mfma_scale_f32_16x16x128_f8f6f4 v[218:221], v[26:33], v[82:89], v[218:221], v250, v249 op_sel_hi:[0,0,0]
	s_waitcnt lgkmcnt(12)
	s_nop 0
	v_mfma_scale_f32_16x16x128_f8f6f4 v[214:217], v[18:25], v[74:81], v[214:217], v250, v249 op_sel_hi:[0,0,0]
	v_mfma_scale_f32_16x16x128_f8f6f4 v[210:213], v[26:33], v[74:81], v[210:213], v250, v249 op_sel_hi:[0,0,0]
	s_waitcnt lgkmcnt(9)
	s_nop 0
	v_mfma_scale_f32_16x16x128_f8f6f4 v[206:209], v[18:25], v[90:97], v[206:209], v250, v249 op_sel_hi:[0,0,0]
	v_mfma_scale_f32_16x16x128_f8f6f4 v[202:205], v[26:33], v[90:97], v[202:205], v250, v249 op_sel_hi:[0,0,0]
	s_waitcnt lgkmcnt(8)
	s_nop 0
	v_mfma_scale_f32_16x16x128_f8f6f4 v[198:201], v[18:25], v[34:41], v[198:201], v250, v249 op_sel_hi:[0,0,0]
	v_mfma_scale_f32_16x16x128_f8f6f4 v[194:197], v[26:33], v[34:41], v[194:197], v250, v249 op_sel_hi:[0,0,0]
	v_mfma_scale_f32_16x16x128_f8f6f4 v[166:169], v[2:9], v[82:89], v[166:169], v250, v249 op_sel_hi:[0,0,0]
	v_mfma_scale_f32_16x16x128_f8f6f4 v[130:133], v[10:17], v[34:41], v[130:133], v250, v249 op_sel_hi:[0,0,0]
	v_mfma_scale_f32_16x16x128_f8f6f4 v[82:85], v[10:17], v[82:89], v[154:157], v250, v249 op_sel_hi:[0,0,0]
	v_mfma_scale_f32_16x16x128_f8f6f4 v[86:89], v[2:9], v[74:81], v[150:153], v250, v249 op_sel_hi:[0,0,0]
	v_mfma_scale_f32_16x16x128_f8f6f4 v[74:77], v[10:17], v[74:81], v[146:149], v250, v249 op_sel_hi:[0,0,0]
	v_mfma_scale_f32_16x16x128_f8f6f4 v[78:81], v[2:9], v[90:97], v[142:145], v250, v249 op_sel_hi:[0,0,0]
	v_mfma_scale_f32_16x16x128_f8f6f4 v[90:93], v[10:17], v[90:97], v[138:141], v250, v249 op_sel_hi:[0,0,0]
	v_mfma_scale_f32_16x16x128_f8f6f4 v[94:97], v[2:9], v[34:41], v[134:137], v250, v249 op_sel_hi:[0,0,0]
	s_setprio 1
	s_waitcnt lgkmcnt(5)
	v_mfma_scale_f32_16x16x128_f8f6f4 v[190:193], v[18:25], v[50:57], v[190:193], v250, v249 op_sel_hi:[0,0,0]
	v_mfma_scale_f32_16x16x128_f8f6f4 v[186:189], v[26:33], v[50:57], v[186:189], v250, v249 op_sel_hi:[0,0,0]
	s_waitcnt lgkmcnt(4)
	s_nop 0
	v_mfma_scale_f32_16x16x128_f8f6f4 v[182:185], v[18:25], v[42:49], v[182:185], v250, v249 op_sel_hi:[0,0,0]
	v_mfma_scale_f32_16x16x128_f8f6f4 v[178:181], v[26:33], v[42:49], v[178:181], v250, v249 op_sel_hi:[0,0,0]
	s_waitcnt lgkmcnt(1)
	s_nop 0
	v_mfma_scale_f32_16x16x128_f8f6f4 v[174:177], v[18:25], v[66:73], v[174:177], v250, v249 op_sel_hi:[0,0,0]
	v_mfma_scale_f32_16x16x128_f8f6f4 v[170:173], v[26:33], v[66:73], v[170:173], v250, v249 op_sel_hi:[0,0,0]
	s_waitcnt lgkmcnt(0)
	s_nop 0
	v_mfma_scale_f32_16x16x128_f8f6f4 v[162:165], v[18:25], v[58:65], v[162:165], v250, v249 op_sel_hi:[0,0,0]
	v_mfma_scale_f32_16x16x128_f8f6f4 v[158:161], v[26:33], v[58:65], v[158:161], v250, v249 op_sel_hi:[0,0,0]
	s_setprio 0
	s_setprio 1
	v_mfma_scale_f32_16x16x128_f8f6f4 v[126:129], v[2:9], v[50:57], v[126:129], v250, v249 op_sel_hi:[0,0,0]
	v_mfma_scale_f32_16x16x128_f8f6f4 v[122:125], v[10:17], v[50:57], v[122:125], v250, v249 op_sel_hi:[0,0,0]
	v_mfma_scale_f32_16x16x128_f8f6f4 v[118:121], v[2:9], v[42:49], v[118:121], v250, v249 op_sel_hi:[0,0,0]
	v_mfma_scale_f32_16x16x128_f8f6f4 v[114:117], v[10:17], v[42:49], v[114:117], v250, v249 op_sel_hi:[0,0,0]
	v_mfma_scale_f32_16x16x128_f8f6f4 v[110:113], v[2:9], v[66:73], v[110:113], v250, v249 op_sel_hi:[0,0,0]
	v_mfma_scale_f32_16x16x128_f8f6f4 v[98:101], v[10:17], v[58:65], v[98:101], v250, v249 op_sel_hi:[0,0,0]
	v_mfma_scale_f32_16x16x128_f8f6f4 v[66:69], v[10:17], v[66:73], v[106:109], v250, v249 op_sel_hi:[0,0,0]
	v_mfma_scale_f32_16x16x128_f8f6f4 v[70:73], v[2:9], v[58:65], v[102:105], v250, v249 op_sel_hi:[0,0,0]
	s_setprio 0
	s_barrier
	s_add_i32 s4, 0, 0x18000
	v_add_u32_e32 v2, s4, v237
	v_add_u32_e32 v6, s4, v238
	s_add_i32 s4, 0, 0x1c000
	v_add_u32_e32 v10, s42, v237
	v_add_u32_e32 v14, s42, v238
	v_add_u32_e32 v18, s4, v237
	v_add_u32_e32 v22, s4, v238
	v_add_u32_e32 v26, s43, v237
	v_add_u32_e32 v30, s43, v238
	ds_read_b128 v[2:5], v2
	ds_read_b128 v[6:9], v6
	ds_read_b128 v[10:13], v10
	ds_read_b128 v[14:17], v14
	ds_read_b128 v[18:21], v18
	ds_read_b128 v[22:25], v22
	ds_read_b128 v[26:29], v26
	ds_read_b128 v[30:33], v30
	s_add_i32 s56, s56, 0x20000
	s_mov_b32 s4, s70
	s_mov_b32 m0, s27
	ds_read_b128 v[34:37], v247 offset:32768
	ds_read_b128 v[42:45], v247 offset:34816
	ds_read_b128 v[38:41], v248 offset:32768
	ds_read_b128 v[46:49], v248 offset:34816
	ds_read_b128 v[50:53], v247 offset:36864
	ds_read_b128 v[58:61], v247 offset:38912
	ds_read_b128 v[54:57], v248 offset:36864
	ds_read_b128 v[62:65], v248 offset:38912
	buffer_load_dwordx4 v233, s[4:7], s56 offen lds
	s_mov_b32 m0, s28
	s_nop 0
	buffer_load_dwordx4 v235, s[4:7], s56 offen lds
	s_waitcnt vmcnt(8)
	s_waitcnt lgkmcnt(0)
	s_barrier
	s_setprio 1
	s_waitcnt lgkmcnt(5)
	s_nop 0
	v_mfma_scale_f32_16x16x128_f8f6f4 v[222:225], v[2:9], v[34:41], v[222:225], v250, v249 op_sel_hi:[0,0,0]
	v_mfma_scale_f32_16x16x128_f8f6f4 v[218:221], v[10:17], v[34:41], v[218:221], v250, v249 op_sel_hi:[0,0,0]
	s_waitcnt lgkmcnt(4)
	s_nop 0
	v_mfma_scale_f32_16x16x128_f8f6f4 v[214:217], v[2:9], v[42:49], v[214:217], v250, v249 op_sel_hi:[0,0,0]
	v_mfma_scale_f32_16x16x128_f8f6f4 v[210:213], v[10:17], v[42:49], v[210:213], v250, v249 op_sel_hi:[0,0,0]
	s_waitcnt lgkmcnt(1)
	s_nop 0
	v_mfma_scale_f32_16x16x128_f8f6f4 v[206:209], v[2:9], v[50:57], v[206:209], v250, v249 op_sel_hi:[0,0,0]
	v_mfma_scale_f32_16x16x128_f8f6f4 v[202:205], v[10:17], v[50:57], v[202:205], v250, v249 op_sel_hi:[0,0,0]
	s_waitcnt lgkmcnt(0)
	s_nop 0
	v_mfma_scale_f32_16x16x128_f8f6f4 v[198:201], v[2:9], v[58:65], v[198:201], v250, v249 op_sel_hi:[0,0,0]
	v_mfma_scale_f32_16x16x128_f8f6f4 v[194:197], v[10:17], v[58:65], v[194:197], v250, v249 op_sel_hi:[0,0,0]
	s_setprio 0
	s_setprio 1
	v_mfma_scale_f32_16x16x128_f8f6f4 v[166:169], v[18:25], v[34:41], v[166:169], v250, v249 op_sel_hi:[0,0,0]
	v_mfma_scale_f32_16x16x128_f8f6f4 v[154:157], v[26:33], v[34:41], v[82:85], v250, v249 op_sel_hi:[0,0,0]
	v_mfma_scale_f32_16x16x128_f8f6f4 v[150:153], v[18:25], v[42:49], v[86:89], v250, v249 op_sel_hi:[0,0,0]
	v_mfma_scale_f32_16x16x128_f8f6f4 v[146:149], v[26:33], v[42:49], v[74:77], v250, v249 op_sel_hi:[0,0,0]
	v_mfma_scale_f32_16x16x128_f8f6f4 v[142:145], v[18:25], v[50:57], v[78:81], v250, v249 op_sel_hi:[0,0,0]
	v_mfma_scale_f32_16x16x128_f8f6f4 v[138:141], v[26:33], v[50:57], v[90:93], v250, v249 op_sel_hi:[0,0,0]
	v_mfma_scale_f32_16x16x128_f8f6f4 v[134:137], v[18:25], v[58:65], v[94:97], v250, v249 op_sel_hi:[0,0,0]
	v_mfma_scale_f32_16x16x128_f8f6f4 v[130:133], v[26:33], v[58:65], v[130:133], v250, v249 op_sel_hi:[0,0,0]
	s_setprio 0
	s_barrier
	s_mov_b32 m0, s29
	ds_read_b128 v[34:37], v247 offset:49152
	ds_read_b128 v[42:45], v247 offset:51200
	ds_read_b128 v[38:41], v248 offset:49152
	ds_read_b128 v[46:49], v248 offset:51200
	ds_read_b128 v[50:53], v247 offset:53248
	ds_read_b128 v[58:61], v247 offset:55296
	ds_read_b128 v[54:57], v248 offset:53248
	ds_read_b128 v[62:65], v248 offset:55296
	buffer_load_dwordx4 v234, s[4:7], s17 offen lds
	s_mov_b32 m0, s30
	s_add_i32 s33, s33, 0x20080
	buffer_load_dwordx4 v236, s[4:7], s17 offen lds
	s_mov_b32 m0, s35
	s_nop 0
	buffer_load_dwordx4 v234, s[4:7], s33 offen lds
	s_mov_b32 m0, s36
	s_nop 0
	buffer_load_dwordx4 v236, s[4:7], s33 offen lds
	s_mov_b32 m0, s31
	s_nop 0
	buffer_load_dwordx4 v233, s[4:7], s16 offen lds
	s_mov_b32 m0, s34
	s_nop 0
	buffer_load_dwordx4 v235, s[4:7], s16 offen lds
	s_waitcnt vmcnt(8)
	s_waitcnt lgkmcnt(0)
	s_barrier
	s_setprio 1
	s_waitcnt lgkmcnt(5)
	s_nop 0
	v_mfma_scale_f32_16x16x128_f8f6f4 v[190:193], v[2:9], v[34:41], v[190:193], v250, v249 op_sel_hi:[0,0,0]
	v_mfma_scale_f32_16x16x128_f8f6f4 v[186:189], v[10:17], v[34:41], v[186:189], v250, v249 op_sel_hi:[0,0,0]
	s_waitcnt lgkmcnt(4)
	s_nop 0
	v_mfma_scale_f32_16x16x128_f8f6f4 v[182:185], v[2:9], v[42:49], v[182:185], v250, v249 op_sel_hi:[0,0,0]
	v_mfma_scale_f32_16x16x128_f8f6f4 v[178:181], v[10:17], v[42:49], v[178:181], v250, v249 op_sel_hi:[0,0,0]
	s_waitcnt lgkmcnt(1)
	s_nop 0
	v_mfma_scale_f32_16x16x128_f8f6f4 v[174:177], v[2:9], v[50:57], v[174:177], v250, v249 op_sel_hi:[0,0,0]
	v_mfma_scale_f32_16x16x128_f8f6f4 v[170:173], v[10:17], v[50:57], v[170:173], v250, v249 op_sel_hi:[0,0,0]
	s_waitcnt lgkmcnt(0)
	s_nop 0
	v_mfma_scale_f32_16x16x128_f8f6f4 v[162:165], v[2:9], v[58:65], v[162:165], v250, v249 op_sel_hi:[0,0,0]
	v_mfma_scale_f32_16x16x128_f8f6f4 v[158:161], v[10:17], v[58:65], v[158:161], v250, v249 op_sel_hi:[0,0,0]
	s_setprio 0
	s_setprio 1
	v_mfma_scale_f32_16x16x128_f8f6f4 v[126:129], v[18:25], v[34:41], v[126:129], v250, v249 op_sel_hi:[0,0,0]
	v_mfma_scale_f32_16x16x128_f8f6f4 v[122:125], v[26:33], v[34:41], v[122:125], v250, v249 op_sel_hi:[0,0,0]
	v_mfma_scale_f32_16x16x128_f8f6f4 v[118:121], v[18:25], v[42:49], v[118:121], v250, v249 op_sel_hi:[0,0,0]
	v_mfma_scale_f32_16x16x128_f8f6f4 v[114:117], v[26:33], v[42:49], v[114:117], v250, v249 op_sel_hi:[0,0,0]
	v_mfma_scale_f32_16x16x128_f8f6f4 v[110:113], v[18:25], v[50:57], v[110:113], v250, v249 op_sel_hi:[0,0,0]
	v_mfma_scale_f32_16x16x128_f8f6f4 v[106:109], v[26:33], v[50:57], v[66:69], v250, v249 op_sel_hi:[0,0,0]
	v_mfma_scale_f32_16x16x128_f8f6f4 v[102:105], v[18:25], v[58:65], v[70:73], v250, v249 op_sel_hi:[0,0,0]
	v_mfma_scale_f32_16x16x128_f8f6f4 v[98:101], v[26:33], v[58:65], v[98:101], v250, v249 op_sel_hi:[0,0,0]
	s_setprio 0
	s_barrier
	s_add_i32 s55, s55, 2
	s_addk_i32 s53, 0x100
	s_addk_i32 s54, 0x100
	s_cmp_gt_u32 s55, 5
	s_cbranch_scc1 .LBB0_280

.LBB0_379:
	s_waitcnt lgkmcnt(0)
	s_add_i32 s2, s23, 0x100
	s_add_i32 s3, s4, 0x100
	s_barrier
	s_setprio 1
	s_waitcnt lgkmcnt(7)
	v_mfma_f32_16x16x32_bf16 v[126:129], v[158:161], v[186:189], 0
	v_mfma_f32_16x16x32_bf16 v[122:125], v[150:153], v[186:189], 0
	s_waitcnt lgkmcnt(6)
	s_nop 0
	v_mfma_f32_16x16x32_bf16 v[118:121], v[158:161], v[178:181], 0
	v_mfma_f32_16x16x32_bf16 v[114:117], v[150:153], v[178:181], 0
	s_waitcnt lgkmcnt(3)
	s_nop 0
	v_mfma_f32_16x16x32_bf16 v[110:113], v[158:161], v[170:173], 0
	v_mfma_f32_16x16x32_bf16 v[106:109], v[150:153], v[170:173], 0
	s_waitcnt lgkmcnt(2)
	s_nop 0
	v_mfma_f32_16x16x32_bf16 v[102:105], v[158:161], v[162:165], 0
	v_mfma_f32_16x16x32_bf16 v[98:101], v[150:153], v[162:165], 0
	v_mfma_f32_16x16x32_bf16 v[126:129], v[154:157], v[190:193], v[126:129]
	v_mfma_f32_16x16x32_bf16 v[122:125], v[146:149], v[190:193], v[122:125]
	v_mfma_f32_16x16x32_bf16 v[118:121], v[154:157], v[182:185], v[118:121]
	v_mfma_f32_16x16x32_bf16 v[114:117], v[146:149], v[182:185], v[114:117]
	s_waitcnt lgkmcnt(1)
	s_nop 0
	v_mfma_f32_16x16x32_bf16 v[110:113], v[154:157], v[174:177], v[110:113]
	v_mfma_f32_16x16x32_bf16 v[106:109], v[146:149], v[174:177], v[106:109]
	s_waitcnt lgkmcnt(0)
	s_nop 0
	v_mfma_f32_16x16x32_bf16 v[102:105], v[154:157], v[166:169], v[102:105]
	v_mfma_f32_16x16x32_bf16 v[98:101], v[146:149], v[166:169], v[98:101]
	s_setprio 0
	s_setprio 1
	s_nop 0
	s_setprio 0
	s_barrier
	s_mov_b32 m0, s28
	ds_read_b128 v[186:189], v216 offset:16384
	ds_read_b128 v[178:181], v216 offset:18432
	ds_read_b128 v[190:193], v217 offset:16384
	ds_read_b128 v[182:185], v217 offset:18432
	ds_read_b128 v[170:173], v216 offset:20480
	ds_read_b128 v[162:165], v216 offset:22528
	ds_read_b128 v[174:177], v217 offset:20480
	ds_read_b128 v[166:169], v217 offset:22528
	buffer_load_dwordx4 v203, s[8:11], s3 offen lds
	s_mov_b32 m0, s29
	v_cndmask_b32_e64 v218, 0, 1, s[24:25]
	buffer_load_dwordx4 v205, s[8:11], s3 offen lds
	s_add_i32 s3, s4, 0x10100
	s_mov_b32 m0, s30
	s_andn2_b64 vcc, exec, s[24:25]
	buffer_load_dwordx4 v203, s[8:11], s3 offen lds
	s_mov_b32 m0, s31
	s_mov_b64 s[24:25], -1
	buffer_load_dwordx4 v205, s[8:11], s3 offen lds
	s_mov_b32 m0, s27
	s_nop 0
	buffer_load_dwordx4 v198, s[8:11], s2 offen lds
	s_mov_b32 m0, s34
	s_nop 0
	buffer_load_dwordx4 v204, s[8:11], s2 offen lds
	v_cmp_ne_u32_e64 s[2:3], 1, v218
	s_cbranch_vccnz .LBB0_381
	s_waitcnt vmcnt(22)
	s_mov_b64 s[24:25], 0

.LBB0_383:
	s_waitcnt lgkmcnt(0)
	s_barrier
	s_setprio 1
	s_waitcnt lgkmcnt(7)
	s_nop 0
	v_mfma_f32_16x16x32_bf16 v[62:65], v[158:161], v[186:189], 0
	v_mfma_f32_16x16x32_bf16 v[58:61], v[150:153], v[186:189], 0
	s_waitcnt lgkmcnt(6)
	s_nop 0
	v_mfma_f32_16x16x32_bf16 v[54:57], v[158:161], v[178:181], 0
	v_mfma_f32_16x16x32_bf16 v[50:53], v[150:153], v[178:181], 0
	s_waitcnt lgkmcnt(3)
	s_nop 0
	v_mfma_f32_16x16x32_bf16 v[46:49], v[158:161], v[170:173], 0
	v_mfma_f32_16x16x32_bf16 v[42:45], v[150:153], v[170:173], 0
	s_waitcnt lgkmcnt(2)
	s_nop 0
	v_mfma_f32_16x16x32_bf16 v[38:41], v[158:161], v[162:165], 0
	v_mfma_f32_16x16x32_bf16 v[34:37], v[150:153], v[162:165], 0
	v_mfma_f32_16x16x32_bf16 v[62:65], v[154:157], v[190:193], v[62:65]
	v_mfma_f32_16x16x32_bf16 v[58:61], v[146:149], v[190:193], v[58:61]
	v_mfma_f32_16x16x32_bf16 v[54:57], v[154:157], v[182:185], v[54:57]
	v_mfma_f32_16x16x32_bf16 v[50:53], v[146:149], v[182:185], v[50:53]
	s_waitcnt lgkmcnt(1)
	s_nop 0
	v_mfma_f32_16x16x32_bf16 v[46:49], v[154:157], v[174:177], v[46:49]
	v_mfma_f32_16x16x32_bf16 v[42:45], v[146:149], v[174:177], v[42:45]
	s_waitcnt lgkmcnt(0)
	s_nop 0
	v_mfma_f32_16x16x32_bf16 v[38:41], v[154:157], v[166:169], v[38:41]
	v_mfma_f32_16x16x32_bf16 v[34:37], v[146:149], v[166:169], v[34:37]
	s_setprio 0
	s_setprio 1
	s_nop 0
	s_setprio 0
	s_barrier
	v_add_u32_e32 v218, s48, v206
	v_add_u32_e32 v220, s49, v206
	v_add_u32_e32 v222, s50, v206
	v_add_u32_e32 v224, s51, v206
	v_add_u32_e32 v219, s48, v207
	ds_read_b128 v[146:149], v218
	ds_read_b128 v[150:153], v219
	v_add_u32_e32 v221, s49, v207
	ds_read_b128 v[154:157], v220
	ds_read_b128 v[158:161], v221
	v_add_u32_e32 v223, s50, v207
	ds_read_b128 v[130:133], v222
	ds_read_b128 v[134:137], v223
	v_add_u32_e32 v225, s51, v207
	ds_read_b128 v[138:141], v224
	ds_read_b128 v[142:145], v225
	s_mov_b32 m0, s35
	s_add_i32 s24, s23, 0xd00
	ds_read_b128 v[186:189], v216 offset:32768
	ds_read_b128 v[174:177], v216 offset:34816
	ds_read_b128 v[190:193], v217 offset:32768
	ds_read_b128 v[178:181], v217 offset:34816
	ds_read_b128 v[170:173], v216 offset:36864
	ds_read_b128 v[162:165], v216 offset:38912
	ds_read_b128 v[182:185], v217 offset:36864
	ds_read_b128 v[166:169], v217 offset:38912
	buffer_load_dwordx4 v198, s[8:11], s24 offen lds
	s_mov_b32 m0, s36
	s_and_b64 vcc, exec, s[2:3]
	buffer_load_dwordx4 v204, s[8:11], s24 offen lds
	s_mov_b64 s[24:25], -1
	s_cbranch_vccnz .LBB0_385
	s_waitcnt vmcnt(24)
	s_mov_b64 s[24:25], 0

.LBB0_387:
	s_waitcnt lgkmcnt(0)
	s_add_i32 s24, s23, 0x180
	s_add_i32 s25, s4, 0x180
	s_barrier
	s_setprio 1
	s_waitcnt lgkmcnt(7)
	s_nop 0
	v_mfma_f32_16x16x32_bf16 v[126:129], v[146:149], v[186:189], v[126:129]
	v_mfma_f32_16x16x32_bf16 v[122:125], v[154:157], v[186:189], v[122:125]
	s_waitcnt lgkmcnt(6)
	s_nop 0
	v_mfma_f32_16x16x32_bf16 v[118:121], v[146:149], v[174:177], v[118:121]
	v_mfma_f32_16x16x32_bf16 v[114:117], v[154:157], v[174:177], v[114:117]
	s_waitcnt lgkmcnt(3)
	s_nop 0
	v_mfma_f32_16x16x32_bf16 v[110:113], v[146:149], v[170:173], v[110:113]
	v_mfma_f32_16x16x32_bf16 v[106:109], v[154:157], v[170:173], v[106:109]
	s_waitcnt lgkmcnt(2)
	s_nop 0
	v_mfma_f32_16x16x32_bf16 v[102:105], v[146:149], v[162:165], v[102:105]
	v_mfma_f32_16x16x32_bf16 v[98:101], v[154:157], v[162:165], v[98:101]
	v_mfma_f32_16x16x32_bf16 v[126:129], v[150:153], v[190:193], v[126:129]
	v_mfma_f32_16x16x32_bf16 v[122:125], v[158:161], v[190:193], v[122:125]
	v_mfma_f32_16x16x32_bf16 v[118:121], v[150:153], v[178:181], v[118:121]
	v_mfma_f32_16x16x32_bf16 v[114:117], v[158:161], v[178:181], v[114:117]
	s_waitcnt lgkmcnt(1)
	s_nop 0
	v_mfma_f32_16x16x32_bf16 v[110:113], v[150:153], v[182:185], v[110:113]
	v_mfma_f32_16x16x32_bf16 v[106:109], v[158:161], v[182:185], v[106:109]
	s_waitcnt lgkmcnt(0)
	s_nop 0
	v_mfma_f32_16x16x32_bf16 v[102:105], v[150:153], v[166:169], v[102:105]
	v_mfma_f32_16x16x32_bf16 v[98:101], v[158:161], v[166:169], v[98:101]
	s_setprio 0
	s_setprio 1
	s_setprio 0
	s_barrier
	s_mov_b32 m0, s37
	ds_read_b128 v[186:189], v216 offset:49152
	ds_read_b128 v[174:177], v216 offset:51200
	ds_read_b128 v[190:193], v217 offset:49152
	ds_read_b128 v[178:181], v217 offset:51200
	ds_read_b128 v[170:173], v216 offset:53248
	ds_read_b128 v[162:165], v216 offset:55296
	ds_read_b128 v[182:185], v217 offset:53248
	ds_read_b128 v[166:169], v217 offset:55296
	buffer_load_dwordx4 v203, s[8:11], s25 offen lds
	s_mov_b32 m0, s38
	s_and_b64 vcc, exec, s[2:3]
	buffer_load_dwordx4 v205, s[8:11], s25 offen lds
	s_add_i32 s25, s4, 0x10180
	s_mov_b32 m0, s42
	s_mov_b64 s[2:3], -1
	buffer_load_dwordx4 v203, s[8:11], s25 offen lds
	s_mov_b32 m0, s43
	s_nop 0
	buffer_load_dwordx4 v205, s[8:11], s25 offen lds
	s_mov_b32 m0, s40
	s_nop 0
	buffer_load_dwordx4 v198, s[8:11], s24 offen lds
	s_mov_b32 m0, s41
	s_nop 0
	buffer_load_dwordx4 v204, s[8:11], s24 offen lds
	s_cbranch_vccnz .LBB0_389
	s_waitcnt vmcnt(30)
	s_mov_b64 s[2:3], 0

.LBB0_391:
	s_waitcnt lgkmcnt(0)
	s_barrier
	s_setprio 1
	s_waitcnt lgkmcnt(7)
	s_nop 0
	v_mfma_f32_16x16x32_bf16 v[62:65], v[146:149], v[186:189], v[62:65]
	v_mfma_f32_16x16x32_bf16 v[58:61], v[154:157], v[186:189], v[58:61]
	s_waitcnt lgkmcnt(6)
	s_nop 0
	v_mfma_f32_16x16x32_bf16 v[54:57], v[146:149], v[174:177], v[54:57]
	v_mfma_f32_16x16x32_bf16 v[50:53], v[154:157], v[174:177], v[50:53]
	s_waitcnt lgkmcnt(3)
	s_nop 0
	v_mfma_f32_16x16x32_bf16 v[46:49], v[146:149], v[170:173], v[46:49]
	v_mfma_f32_16x16x32_bf16 v[42:45], v[154:157], v[170:173], v[42:45]
	s_waitcnt lgkmcnt(2)
	s_nop 0
	v_mfma_f32_16x16x32_bf16 v[38:41], v[146:149], v[162:165], v[38:41]
	v_mfma_f32_16x16x32_bf16 v[34:37], v[154:157], v[162:165], v[34:37]
	v_mfma_f32_16x16x32_bf16 v[62:65], v[150:153], v[190:193], v[62:65]
	v_mfma_f32_16x16x32_bf16 v[58:61], v[158:161], v[190:193], v[58:61]
	v_mfma_f32_16x16x32_bf16 v[54:57], v[150:153], v[178:181], v[54:57]
	v_mfma_f32_16x16x32_bf16 v[50:53], v[158:161], v[178:181], v[50:53]
	s_waitcnt lgkmcnt(1)
	s_nop 0
	v_mfma_f32_16x16x32_bf16 v[46:49], v[150:153], v[182:185], v[46:49]
	v_mfma_f32_16x16x32_bf16 v[42:45], v[158:161], v[182:185], v[42:45]
	s_waitcnt lgkmcnt(0)
	s_nop 0
	v_mfma_f32_16x16x32_bf16 v[38:41], v[150:153], v[166:169], v[38:41]
	v_mfma_f32_16x16x32_bf16 v[34:37], v[158:161], v[166:169], v[34:37]
	s_setprio 0
	s_setprio 1
	s_setprio 0
	s_barrier
	ds_read_b128 v[130:133], v208
	ds_read_b128 v[134:137], v209
	ds_read_b128 v[138:141], v210
	ds_read_b128 v[142:145], v211
	ds_read_b128 v[146:149], v212
	ds_read_b128 v[150:153], v213
	ds_read_b128 v[154:157], v214
	ds_read_b128 v[158:161], v215
	s_add_i32 s24, s55, s26
	s_and_b64 s[2:3], s[18:19], exec
	s_cselect_b32 s2, s24, s33
	s_mul_i32 s25, s2, 0x30000
	s_add_i32 s25, s25, 0xc000000
	s_and_b64 s[2:3], s[18:19], exec
	s_cselect_b32 s2, s25, s23
	s_lshl_b32 s3, s24, 12
	s_and_b32 s54, s3, 0xffff0000
	s_add_i32 s54, s54, 0x3000000
	s_and_b64 s[56:57], s[18:19], exec
	s_cselect_b32 s33, s54, s4
	s_add_i32 s3, s2, 0x80
	s_addk_i32 s23, 0xd80
	s_mov_b32 s4, s70
	s_mov_b32 m0, s44
	ds_read_b128 v[162:165], v216
	ds_read_b128 v[166:169], v216 offset:2048
	ds_read_b128 v[170:173], v217
	ds_read_b128 v[174:177], v217 offset:2048
	ds_read_b128 v[178:181], v216 offset:4096
	ds_read_b128 v[182:185], v216 offset:6144
	ds_read_b128 v[186:189], v217 offset:4096
	ds_read_b128 v[190:193], v217 offset:6144
	buffer_load_dwordx4 v198, s[4:7], s23 offen lds
	s_mov_b32 m0, s47
	s_nop 0
	buffer_load_dwordx4 v204, s[4:7], s23 offen lds
	s_waitcnt vmcnt(8)
	s_waitcnt lgkmcnt(0)
	s_barrier
	s_setprio 1
	s_waitcnt lgkmcnt(7)
	v_mfma_f32_16x16x32_bf16 v[126:129], v[130:133], v[162:165], v[126:129]
	v_mfma_f32_16x16x32_bf16 v[122:125], v[138:141], v[162:165], v[122:125]
	s_waitcnt lgkmcnt(6)
	s_nop 0
	v_mfma_f32_16x16x32_bf16 v[118:121], v[130:133], v[166:169], v[118:121]
	v_mfma_f32_16x16x32_bf16 v[114:117], v[138:141], v[166:169], v[114:117]
	s_waitcnt lgkmcnt(3)
	s_nop 0
	v_mfma_f32_16x16x32_bf16 v[110:113], v[130:133], v[178:181], v[110:113]
	v_mfma_f32_16x16x32_bf16 v[106:109], v[138:141], v[178:181], v[106:109]
	s_waitcnt lgkmcnt(2)
	s_nop 0
	v_mfma_f32_16x16x32_bf16 v[102:105], v[130:133], v[182:185], v[102:105]
	v_mfma_f32_16x16x32_bf16 v[98:101], v[138:141], v[182:185], v[98:101]
	v_mfma_f32_16x16x32_bf16 v[126:129], v[134:137], v[170:173], v[126:129]
	v_mfma_f32_16x16x32_bf16 v[122:125], v[142:145], v[170:173], v[122:125]
	v_mfma_f32_16x16x32_bf16 v[118:121], v[134:137], v[174:177], v[118:121]
	v_mfma_f32_16x16x32_bf16 v[114:117], v[142:145], v[174:177], v[114:117]
	s_waitcnt lgkmcnt(1)
	s_nop 0
	v_mfma_f32_16x16x32_bf16 v[110:113], v[134:137], v[186:189], v[110:113]
	v_mfma_f32_16x16x32_bf16 v[106:109], v[142:145], v[186:189], v[106:109]
	s_waitcnt lgkmcnt(0)
	s_nop 0
	v_mfma_f32_16x16x32_bf16 v[102:105], v[134:137], v[190:193], v[102:105]
	v_mfma_f32_16x16x32_bf16 v[98:101], v[142:145], v[190:193], v[98:101]
	s_setprio 0
	s_setprio 1
	s_setprio 0
	s_barrier
	s_mov_b32 m0, s28
	ds_read_b128 v[162:165], v216 offset:16384
	ds_read_b128 v[166:169], v216 offset:18432
	ds_read_b128 v[170:173], v217 offset:16384
	ds_read_b128 v[174:177], v217 offset:18432
	ds_read_b128 v[178:181], v216 offset:20480
	ds_read_b128 v[182:185], v216 offset:22528
	ds_read_b128 v[186:189], v217 offset:20480
	ds_read_b128 v[190:193], v217 offset:22528
	buffer_load_dwordx4 v203, s[4:7], s33 offen lds
	s_mov_b32 m0, s29
	s_add_i32 s23, s33, 0x10000
	buffer_load_dwordx4 v205, s[4:7], s33 offen lds
	s_mov_b32 m0, s30
	s_nop 0
	buffer_load_dwordx4 v203, s[4:7], s23 offen lds
	s_mov_b32 m0, s31
	s_nop 0
	buffer_load_dwordx4 v205, s[4:7], s23 offen lds
	s_mov_b32 m0, s27
	s_nop 0
	buffer_load_dwordx4 v198, s[4:7], s2 offen lds
	s_mov_b32 m0, s34
	s_nop 0
	buffer_load_dwordx4 v204, s[4:7], s2 offen lds
	s_waitcnt vmcnt(8)
	s_waitcnt lgkmcnt(0)
	s_barrier
	s_setprio 1
	s_waitcnt lgkmcnt(7)
	s_nop 0
	v_mfma_f32_16x16x32_bf16 v[62:65], v[130:133], v[162:165], v[62:65]
	v_mfma_f32_16x16x32_bf16 v[58:61], v[138:141], v[162:165], v[58:61]
	s_waitcnt lgkmcnt(6)
	s_nop 0
	v_mfma_f32_16x16x32_bf16 v[54:57], v[130:133], v[166:169], v[54:57]
	v_mfma_f32_16x16x32_bf16 v[50:53], v[138:141], v[166:169], v[50:53]
	s_waitcnt lgkmcnt(3)
	s_nop 0
	v_mfma_f32_16x16x32_bf16 v[46:49], v[130:133], v[178:181], v[46:49]
	v_mfma_f32_16x16x32_bf16 v[42:45], v[138:141], v[178:181], v[42:45]
	s_waitcnt lgkmcnt(2)
	s_nop 0
	v_mfma_f32_16x16x32_bf16 v[38:41], v[130:133], v[182:185], v[38:41]
	v_mfma_f32_16x16x32_bf16 v[34:37], v[138:141], v[182:185], v[34:37]
	v_mfma_f32_16x16x32_bf16 v[62:65], v[134:137], v[170:173], v[62:65]
	v_mfma_f32_16x16x32_bf16 v[58:61], v[142:145], v[170:173], v[58:61]
	v_mfma_f32_16x16x32_bf16 v[54:57], v[134:137], v[174:177], v[54:57]
	v_mfma_f32_16x16x32_bf16 v[50:53], v[142:145], v[174:177], v[50:53]
	s_waitcnt lgkmcnt(1)
	s_nop 0
	v_mfma_f32_16x16x32_bf16 v[46:49], v[134:137], v[186:189], v[46:49]
	v_mfma_f32_16x16x32_bf16 v[42:45], v[142:145], v[186:189], v[42:45]
	s_waitcnt lgkmcnt(0)
	s_nop 0
	v_mfma_f32_16x16x32_bf16 v[38:41], v[134:137], v[190:193], v[38:41]
	v_mfma_f32_16x16x32_bf16 v[34:37], v[142:145], v[190:193], v[34:37]
	s_setprio 0
	s_setprio 1
	s_setprio 0
	s_barrier
	ds_read_b128 v[130:133], v218
	ds_read_b128 v[134:137], v219
	ds_read_b128 v[138:141], v220
	ds_read_b128 v[142:145], v221
	ds_read_b128 v[146:149], v222
	ds_read_b128 v[150:153], v223
	ds_read_b128 v[154:157], v224
	ds_read_b128 v[158:161], v225
	s_add_i32 s23, s2, 0xc00
	s_mov_b32 m0, s35
	ds_read_b128 v[162:165], v216 offset:32768
	ds_read_b128 v[166:169], v216 offset:34816
	ds_read_b128 v[170:173], v217 offset:32768
	ds_read_b128 v[174:177], v217 offset:34816
	ds_read_b128 v[178:181], v216 offset:36864
	ds_read_b128 v[182:185], v216 offset:38912
	ds_read_b128 v[186:189], v217 offset:36864
	ds_read_b128 v[190:193], v217 offset:38912
	buffer_load_dwordx4 v198, s[4:7], s23 offen lds
	s_mov_b32 m0, s36
	s_nop 0
	buffer_load_dwordx4 v204, s[4:7], s23 offen lds
	s_waitcnt vmcnt(8)
	s_waitcnt lgkmcnt(0)
	s_barrier
	s_setprio 1
	s_waitcnt lgkmcnt(7)
	v_mfma_f32_16x16x32_bf16 v[126:129], v[130:133], v[162:165], v[126:129]
	v_mfma_f32_16x16x32_bf16 v[122:125], v[138:141], v[162:165], v[122:125]
	s_waitcnt lgkmcnt(6)
	s_nop 0
	v_mfma_f32_16x16x32_bf16 v[118:121], v[130:133], v[166:169], v[118:121]
	v_mfma_f32_16x16x32_bf16 v[114:117], v[138:141], v[166:169], v[114:117]
	s_waitcnt lgkmcnt(3)
	s_nop 0
	v_mfma_f32_16x16x32_bf16 v[110:113], v[130:133], v[178:181], v[110:113]
	v_mfma_f32_16x16x32_bf16 v[106:109], v[138:141], v[178:181], v[106:109]
	s_waitcnt lgkmcnt(2)
	s_nop 0
	v_mfma_f32_16x16x32_bf16 v[102:105], v[130:133], v[182:185], v[102:105]
	v_mfma_f32_16x16x32_bf16 v[98:101], v[138:141], v[182:185], v[98:101]
	v_mfma_f32_16x16x32_bf16 v[126:129], v[134:137], v[170:173], v[126:129]
	v_mfma_f32_16x16x32_bf16 v[122:125], v[142:145], v[170:173], v[122:125]
	v_mfma_f32_16x16x32_bf16 v[118:121], v[134:137], v[174:177], v[118:121]
	v_mfma_f32_16x16x32_bf16 v[114:117], v[142:145], v[174:177], v[114:117]
	s_waitcnt lgkmcnt(1)
	s_nop 0
	v_mfma_f32_16x16x32_bf16 v[110:113], v[134:137], v[186:189], v[110:113]
	v_mfma_f32_16x16x32_bf16 v[106:109], v[142:145], v[186:189], v[106:109]
	s_waitcnt lgkmcnt(0)
	s_nop 0
	v_mfma_f32_16x16x32_bf16 v[102:105], v[134:137], v[190:193], v[102:105]
	v_mfma_f32_16x16x32_bf16 v[98:101], v[142:145], v[190:193], v[98:101]
	s_setprio 0
	s_setprio 1
	s_setprio 0
	s_barrier
	s_mov_b32 m0, s37
	s_add_i32 s23, s33, 0x80
	ds_read_b128 v[162:165], v216 offset:49152
	ds_read_b128 v[166:169], v216 offset:51200
	ds_read_b128 v[170:173], v217 offset:49152
	ds_read_b128 v[174:177], v217 offset:51200
	ds_read_b128 v[178:181], v216 offset:53248
	ds_read_b128 v[182:185], v216 offset:55296
	ds_read_b128 v[186:189], v217 offset:53248
	ds_read_b128 v[190:193], v217 offset:55296
	buffer_load_dwordx4 v203, s[4:7], s23 offen lds
	s_mov_b32 m0, s38
	s_add_i32 s33, s33, 0x10080
	buffer_load_dwordx4 v205, s[4:7], s23 offen lds
	s_mov_b32 m0, s42
	s_nop 0
	buffer_load_dwordx4 v203, s[4:7], s33 offen lds
	s_mov_b32 m0, s43
	s_nop 0
	buffer_load_dwordx4 v205, s[4:7], s33 offen lds
	s_mov_b32 m0, s40
	s_nop 0
	buffer_load_dwordx4 v198, s[4:7], s3 offen lds
	s_mov_b32 m0, s41
	s_nop 0
	buffer_load_dwordx4 v204, s[4:7], s3 offen lds
	s_waitcnt vmcnt(8)
	s_waitcnt lgkmcnt(0)
	s_barrier
	s_setprio 1
	s_waitcnt lgkmcnt(7)
	s_nop 0
	v_mfma_f32_16x16x32_bf16 v[62:65], v[130:133], v[162:165], v[62:65]
	v_mfma_f32_16x16x32_bf16 v[58:61], v[138:141], v[162:165], v[58:61]
	s_waitcnt lgkmcnt(6)
	s_nop 0
	v_mfma_f32_16x16x32_bf16 v[54:57], v[130:133], v[166:169], v[54:57]
	v_mfma_f32_16x16x32_bf16 v[50:53], v[138:141], v[166:169], v[50:53]
	s_waitcnt lgkmcnt(3)
	s_nop 0
	v_mfma_f32_16x16x32_bf16 v[46:49], v[130:133], v[178:181], v[46:49]
	v_mfma_f32_16x16x32_bf16 v[42:45], v[138:141], v[178:181], v[42:45]
	s_waitcnt lgkmcnt(2)
	s_nop 0
	v_mfma_f32_16x16x32_bf16 v[38:41], v[130:133], v[182:185], v[38:41]
	v_mfma_f32_16x16x32_bf16 v[34:37], v[138:141], v[182:185], v[34:37]
	v_mfma_f32_16x16x32_bf16 v[62:65], v[134:137], v[170:173], v[62:65]
	v_mfma_f32_16x16x32_bf16 v[58:61], v[142:145], v[170:173], v[58:61]
	v_mfma_f32_16x16x32_bf16 v[54:57], v[134:137], v[174:177], v[54:57]
	v_mfma_f32_16x16x32_bf16 v[50:53], v[142:145], v[174:177], v[50:53]
	s_waitcnt lgkmcnt(1)
	s_nop 0
	v_mfma_f32_16x16x32_bf16 v[46:49], v[134:137], v[186:189], v[46:49]
	v_mfma_f32_16x16x32_bf16 v[42:45], v[142:145], v[186:189], v[42:45]
	s_waitcnt lgkmcnt(0)
	s_nop 0
	v_mfma_f32_16x16x32_bf16 v[38:41], v[134:137], v[190:193], v[38:41]
	v_mfma_f32_16x16x32_bf16 v[34:37], v[142:145], v[190:193], v[34:37]
	s_setprio 0
	s_setprio 1
	s_setprio 0
	s_barrier
	s_andn2_b64 vcc, exec, s[16:17]
	s_cbranch_vccnz .LBB0_393
	s_barrier

.LBB0_407:
	s_waitcnt lgkmcnt(0)
	s_add_i32 s2, s52, 0x100
	s_add_i32 s3, s51, 0x100
	s_barrier
	s_setprio 1
	s_waitcnt lgkmcnt(7)
	v_mfma_f32_16x16x32_bf16 v[126:129], v[158:161], v[186:189], 0
	v_mfma_f32_16x16x32_bf16 v[122:125], v[150:153], v[186:189], 0
	s_waitcnt lgkmcnt(6)
	s_nop 0
	v_mfma_f32_16x16x32_bf16 v[118:121], v[158:161], v[178:181], 0
	v_mfma_f32_16x16x32_bf16 v[114:117], v[150:153], v[178:181], 0
	s_waitcnt lgkmcnt(3)
	s_nop 0
	v_mfma_f32_16x16x32_bf16 v[110:113], v[158:161], v[170:173], 0
	v_mfma_f32_16x16x32_bf16 v[106:109], v[150:153], v[170:173], 0
	s_waitcnt lgkmcnt(2)
	s_nop 0
	v_mfma_f32_16x16x32_bf16 v[102:105], v[158:161], v[162:165], 0
	v_mfma_f32_16x16x32_bf16 v[98:101], v[150:153], v[162:165], 0
	v_mfma_f32_16x16x32_bf16 v[126:129], v[154:157], v[190:193], v[126:129]
	v_mfma_f32_16x16x32_bf16 v[122:125], v[146:149], v[190:193], v[122:125]
	v_mfma_f32_16x16x32_bf16 v[118:121], v[154:157], v[182:185], v[118:121]
	v_mfma_f32_16x16x32_bf16 v[114:117], v[146:149], v[182:185], v[114:117]
	s_waitcnt lgkmcnt(1)
	s_nop 0
	v_mfma_f32_16x16x32_bf16 v[110:113], v[154:157], v[174:177], v[110:113]
	v_mfma_f32_16x16x32_bf16 v[106:109], v[146:149], v[174:177], v[106:109]
	s_waitcnt lgkmcnt(0)
	s_nop 0
	v_mfma_f32_16x16x32_bf16 v[102:105], v[154:157], v[166:169], v[102:105]
	v_mfma_f32_16x16x32_bf16 v[98:101], v[146:149], v[166:169], v[98:101]
	s_setprio 0
	s_setprio 1
	v_mfma_f32_16x16x32_bf16 v[94:97], v[142:145], v[186:189], 0
	v_mfma_f32_16x16x32_bf16 v[86:89], v[134:137], v[186:189], 0
	v_mfma_f32_16x16x32_bf16 v[82:85], v[142:145], v[178:181], 0
	v_mfma_f32_16x16x32_bf16 v[78:81], v[134:137], v[178:181], 0
	v_mfma_f32_16x16x32_bf16 v[74:77], v[142:145], v[170:173], 0
	v_mfma_f32_16x16x32_bf16 v[70:73], v[134:137], v[170:173], 0
	v_mfma_f32_16x16x32_bf16 v[66:69], v[142:145], v[162:165], 0
	v_mfma_f32_16x16x32_bf16 v[62:65], v[134:137], v[162:165], 0
	s_nop 0
	s_nop 0
	v_mfma_f32_16x16x32_bf16 v[94:97], v[138:141], v[190:193], v[94:97]
	v_mfma_f32_16x16x32_bf16 v[86:89], v[130:133], v[190:193], v[86:89]
	v_mfma_f32_16x16x32_bf16 v[82:85], v[138:141], v[182:185], v[82:85]
	v_mfma_f32_16x16x32_bf16 v[78:81], v[130:133], v[182:185], v[78:81]
	v_mfma_f32_16x16x32_bf16 v[74:77], v[138:141], v[174:177], v[74:77]
	v_mfma_f32_16x16x32_bf16 v[70:73], v[130:133], v[174:177], v[70:73]
	v_mfma_f32_16x16x32_bf16 v[66:69], v[138:141], v[166:169], v[66:69]
	v_mfma_f32_16x16x32_bf16 v[62:65], v[130:133], v[166:169], v[62:65]
	s_setprio 0
	s_barrier
	s_mov_b32 m0, s25
	ds_read_b128 v[186:189], v211 offset:16384
	ds_read_b128 v[178:181], v211 offset:18432
	ds_read_b128 v[190:193], v212 offset:16384
	ds_read_b128 v[182:185], v212 offset:18432
	ds_read_b128 v[170:173], v211 offset:20480
	ds_read_b128 v[162:165], v211 offset:22528
	ds_read_b128 v[174:177], v212 offset:20480
	ds_read_b128 v[166:169], v212 offset:22528
	buffer_load_dwordx4 v198, s[8:11], s3 offen lds
	s_mov_b32 m0, s27
	v_cndmask_b32_e64 v194, 0, 1, s[22:23]
	buffer_load_dwordx4 v200, s[8:11], s3 offen lds
	s_add_i32 s3, s51, 0x18100
	s_mov_b32 m0, s28
	s_andn2_b64 vcc, exec, s[22:23]
	buffer_load_dwordx4 v198, s[8:11], s3 offen lds
	s_mov_b32 m0, s29
	s_mov_b64 s[22:23], -1
	buffer_load_dwordx4 v200, s[8:11], s3 offen lds
	s_mov_b32 m0, s24
	s_nop 0
	buffer_load_dwordx4 v197, s[8:11], s2 offen lds
	s_mov_b32 m0, s30
	s_nop 0
	buffer_load_dwordx4 v199, s[8:11], s2 offen lds
	v_cmp_ne_u32_e64 s[2:3], 1, v194
	s_cbranch_vccnz .LBB0_409
	s_waitcnt vmcnt(22)
	s_mov_b64 s[22:23], 0

.LBB0_411:
	s_waitcnt lgkmcnt(0)
	s_barrier
	s_setprio 1
	s_waitcnt lgkmcnt(7)
	v_mfma_f32_16x16x32_bf16 v[90:93], v[158:161], v[186:189], 0
	v_mfma_f32_16x16x32_bf16 v[58:61], v[150:153], v[186:189], 0
	s_waitcnt lgkmcnt(6)
	s_nop 0
	v_mfma_f32_16x16x32_bf16 v[54:57], v[158:161], v[178:181], 0
	v_mfma_f32_16x16x32_bf16 v[50:53], v[150:153], v[178:181], 0
	s_waitcnt lgkmcnt(3)
	s_nop 0
	v_mfma_f32_16x16x32_bf16 v[46:49], v[158:161], v[170:173], 0
	v_mfma_f32_16x16x32_bf16 v[42:45], v[150:153], v[170:173], 0
	s_waitcnt lgkmcnt(2)
	s_nop 0
	v_mfma_f32_16x16x32_bf16 v[38:41], v[158:161], v[162:165], 0
	v_mfma_f32_16x16x32_bf16 v[34:37], v[150:153], v[162:165], 0
	v_mfma_f32_16x16x32_bf16 v[90:93], v[154:157], v[190:193], v[90:93]
	v_mfma_f32_16x16x32_bf16 v[58:61], v[146:149], v[190:193], v[58:61]
	v_mfma_f32_16x16x32_bf16 v[54:57], v[154:157], v[182:185], v[54:57]
	v_mfma_f32_16x16x32_bf16 v[50:53], v[146:149], v[182:185], v[50:53]
	s_waitcnt lgkmcnt(1)
	s_nop 0
	v_mfma_f32_16x16x32_bf16 v[46:49], v[154:157], v[174:177], v[46:49]
	v_mfma_f32_16x16x32_bf16 v[42:45], v[146:149], v[174:177], v[42:45]
	s_waitcnt lgkmcnt(0)
	s_nop 0
	v_mfma_f32_16x16x32_bf16 v[38:41], v[154:157], v[166:169], v[38:41]
	v_mfma_f32_16x16x32_bf16 v[34:37], v[146:149], v[166:169], v[34:37]
	s_setprio 0
	s_setprio 1
	v_mfma_f32_16x16x32_bf16 v[30:33], v[142:145], v[186:189], 0
	v_mfma_f32_16x16x32_bf16 v[26:29], v[134:137], v[186:189], 0
	v_mfma_f32_16x16x32_bf16 v[22:25], v[142:145], v[178:181], 0
	v_mfma_f32_16x16x32_bf16 v[18:21], v[134:137], v[178:181], 0
	v_mfma_f32_16x16x32_bf16 v[14:17], v[142:145], v[170:173], 0
	v_mfma_f32_16x16x32_bf16 v[10:13], v[134:137], v[170:173], 0
	v_mfma_f32_16x16x32_bf16 v[6:9], v[142:145], v[162:165], 0
	v_mfma_f32_16x16x32_bf16 v[2:5], v[134:137], v[162:165], 0
	s_nop 0
	s_nop 0
	v_mfma_f32_16x16x32_bf16 v[30:33], v[138:141], v[190:193], v[30:33]
	v_mfma_f32_16x16x32_bf16 v[26:29], v[130:133], v[190:193], v[26:29]
	v_mfma_f32_16x16x32_bf16 v[22:25], v[138:141], v[182:185], v[22:25]
	v_mfma_f32_16x16x32_bf16 v[18:21], v[130:133], v[182:185], v[18:21]
	v_mfma_f32_16x16x32_bf16 v[14:17], v[138:141], v[174:177], v[14:17]
	v_mfma_f32_16x16x32_bf16 v[10:13], v[130:133], v[174:177], v[10:13]
	v_mfma_f32_16x16x32_bf16 v[6:9], v[138:141], v[166:169], v[6:9]
	v_mfma_f32_16x16x32_bf16 v[2:5], v[130:133], v[166:169], v[2:5]
	s_setprio 0
	s_barrier
	v_add_u32_e32 v194, s45, v201
	v_add_u32_e32 v214, s46, v201
	v_add_u32_e32 v216, s47, v201
	v_add_u32_e32 v218, s48, v201
	v_add_u32_e32 v213, s45, v202
	ds_read_b128 v[146:149], v194
	ds_read_b128 v[150:153], v213
	v_add_u32_e32 v215, s46, v202
	ds_read_b128 v[154:157], v214
	ds_read_b128 v[158:161], v215
	v_add_u32_e32 v217, s47, v202
	ds_read_b128 v[130:133], v216
	ds_read_b128 v[134:137], v217
	v_add_u32_e32 v219, s48, v202
	ds_read_b128 v[138:141], v218
	ds_read_b128 v[142:145], v219
	s_mov_b32 m0, s31
	s_add_i32 s4, s52, 0x18100
	ds_read_b128 v[186:189], v211 offset:32768
	ds_read_b128 v[174:177], v211 offset:34816
	ds_read_b128 v[190:193], v212 offset:32768
	ds_read_b128 v[178:181], v212 offset:34816
	ds_read_b128 v[170:173], v211 offset:36864
	ds_read_b128 v[162:165], v211 offset:38912
	ds_read_b128 v[182:185], v212 offset:36864
	ds_read_b128 v[166:169], v212 offset:38912
	buffer_load_dwordx4 v197, s[8:11], s4 offen lds
	s_mov_b32 m0, s34
	s_and_b64 vcc, exec, s[2:3]
	buffer_load_dwordx4 v199, s[8:11], s4 offen lds
	s_mov_b64 s[22:23], -1
	s_cbranch_vccnz .LBB0_413
	s_waitcnt vmcnt(24)
	s_mov_b64 s[22:23], 0

.LBB0_415:
	s_waitcnt lgkmcnt(0)
	s_add_i32 s22, s52, 0x180
	s_add_i32 s23, s51, 0x180
	s_barrier
	s_setprio 1
	s_waitcnt lgkmcnt(7)
	v_mfma_f32_16x16x32_bf16 v[126:129], v[146:149], v[186:189], v[126:129]
	v_mfma_f32_16x16x32_bf16 v[122:125], v[154:157], v[186:189], v[122:125]
	s_waitcnt lgkmcnt(6)
	s_nop 0
	v_mfma_f32_16x16x32_bf16 v[118:121], v[146:149], v[174:177], v[118:121]
	v_mfma_f32_16x16x32_bf16 v[114:117], v[154:157], v[174:177], v[114:117]
	s_waitcnt lgkmcnt(3)
	s_nop 0
	v_mfma_f32_16x16x32_bf16 v[110:113], v[146:149], v[170:173], v[110:113]
	v_mfma_f32_16x16x32_bf16 v[106:109], v[154:157], v[170:173], v[106:109]
	s_waitcnt lgkmcnt(2)
	s_nop 0
	v_mfma_f32_16x16x32_bf16 v[102:105], v[146:149], v[162:165], v[102:105]
	v_mfma_f32_16x16x32_bf16 v[98:101], v[154:157], v[162:165], v[98:101]
	v_mfma_f32_16x16x32_bf16 v[126:129], v[150:153], v[190:193], v[126:129]
	v_mfma_f32_16x16x32_bf16 v[122:125], v[158:161], v[190:193], v[122:125]
	v_mfma_f32_16x16x32_bf16 v[118:121], v[150:153], v[178:181], v[118:121]
	v_mfma_f32_16x16x32_bf16 v[114:117], v[158:161], v[178:181], v[114:117]
	s_waitcnt lgkmcnt(1)
	s_nop 0
	v_mfma_f32_16x16x32_bf16 v[110:113], v[150:153], v[182:185], v[110:113]
	v_mfma_f32_16x16x32_bf16 v[106:109], v[158:161], v[182:185], v[106:109]
	s_waitcnt lgkmcnt(0)
	s_nop 0
	v_mfma_f32_16x16x32_bf16 v[102:105], v[150:153], v[166:169], v[102:105]
	v_mfma_f32_16x16x32_bf16 v[98:101], v[158:161], v[166:169], v[98:101]
	s_setprio 0
	s_setprio 1
	v_mfma_f32_16x16x32_bf16 v[94:97], v[130:133], v[186:189], v[94:97]
	v_mfma_f32_16x16x32_bf16 v[86:89], v[138:141], v[186:189], v[86:89]
	v_mfma_f32_16x16x32_bf16 v[82:85], v[130:133], v[174:177], v[82:85]
	v_mfma_f32_16x16x32_bf16 v[78:81], v[138:141], v[174:177], v[78:81]
	v_mfma_f32_16x16x32_bf16 v[74:77], v[130:133], v[170:173], v[74:77]
	v_mfma_f32_16x16x32_bf16 v[70:73], v[138:141], v[170:173], v[70:73]
	v_mfma_f32_16x16x32_bf16 v[66:69], v[130:133], v[162:165], v[66:69]
	v_mfma_f32_16x16x32_bf16 v[62:65], v[138:141], v[162:165], v[62:65]
	v_mfma_f32_16x16x32_bf16 v[94:97], v[134:137], v[190:193], v[94:97]
	v_mfma_f32_16x16x32_bf16 v[86:89], v[142:145], v[190:193], v[86:89]
	v_mfma_f32_16x16x32_bf16 v[82:85], v[134:137], v[178:181], v[82:85]
	v_mfma_f32_16x16x32_bf16 v[78:81], v[142:145], v[178:181], v[78:81]
	v_mfma_f32_16x16x32_bf16 v[74:77], v[134:137], v[182:185], v[74:77]
	v_mfma_f32_16x16x32_bf16 v[70:73], v[142:145], v[182:185], v[70:73]
	v_mfma_f32_16x16x32_bf16 v[66:69], v[134:137], v[166:169], v[66:69]
	v_mfma_f32_16x16x32_bf16 v[62:65], v[142:145], v[166:169], v[62:65]
	s_setprio 0
	s_barrier
	s_mov_b32 m0, s36
	s_mov_b32 s4, s70
	ds_read_b128 v[186:189], v211 offset:49152
	ds_read_b128 v[174:177], v211 offset:51200
	ds_read_b128 v[190:193], v212 offset:49152
	ds_read_b128 v[178:181], v212 offset:51200
	ds_read_b128 v[170:173], v211 offset:53248
	ds_read_b128 v[162:165], v211 offset:55296
	ds_read_b128 v[182:185], v212 offset:53248
	ds_read_b128 v[166:169], v212 offset:55296
	buffer_load_dwordx4 v198, s[4:7], s23 offen lds
	s_mov_b32 m0, s37
	s_and_b64 vcc, exec, s[2:3]
	buffer_load_dwordx4 v200, s[4:7], s23 offen lds
	s_add_i32 s23, s51, 0x18180
	s_mov_b32 m0, s40
	s_mov_b64 s[2:3], -1
	buffer_load_dwordx4 v198, s[4:7], s23 offen lds
	s_mov_b32 m0, s41
	s_nop 0
	buffer_load_dwordx4 v200, s[4:7], s23 offen lds
	s_mov_b32 m0, s38
	s_nop 0
	buffer_load_dwordx4 v197, s[4:7], s22 offen lds
	s_mov_b32 m0, s39
	s_nop 0
	buffer_load_dwordx4 v199, s[4:7], s22 offen lds
	s_cbranch_vccnz .LBB0_417
	s_waitcnt vmcnt(30)
	s_mov_b64 s[2:3], 0

.LBB0_419:
	s_waitcnt lgkmcnt(0)
	s_barrier
	s_setprio 1
	s_waitcnt lgkmcnt(7)
	v_mfma_f32_16x16x32_bf16 v[90:93], v[146:149], v[186:189], v[90:93]
	v_mfma_f32_16x16x32_bf16 v[58:61], v[154:157], v[186:189], v[58:61]
	s_waitcnt lgkmcnt(6)
	s_nop 0
	v_mfma_f32_16x16x32_bf16 v[54:57], v[146:149], v[174:177], v[54:57]
	v_mfma_f32_16x16x32_bf16 v[50:53], v[154:157], v[174:177], v[50:53]
	s_waitcnt lgkmcnt(3)
	s_nop 0
	v_mfma_f32_16x16x32_bf16 v[46:49], v[146:149], v[170:173], v[46:49]
	v_mfma_f32_16x16x32_bf16 v[42:45], v[154:157], v[170:173], v[42:45]
	s_waitcnt lgkmcnt(2)
	s_nop 0
	v_mfma_f32_16x16x32_bf16 v[38:41], v[146:149], v[162:165], v[38:41]
	v_mfma_f32_16x16x32_bf16 v[34:37], v[154:157], v[162:165], v[34:37]
	v_mfma_f32_16x16x32_bf16 v[90:93], v[150:153], v[190:193], v[90:93]
	v_mfma_f32_16x16x32_bf16 v[58:61], v[158:161], v[190:193], v[58:61]
	v_mfma_f32_16x16x32_bf16 v[54:57], v[150:153], v[178:181], v[54:57]
	v_mfma_f32_16x16x32_bf16 v[50:53], v[158:161], v[178:181], v[50:53]
	s_waitcnt lgkmcnt(1)
	s_nop 0
	v_mfma_f32_16x16x32_bf16 v[46:49], v[150:153], v[182:185], v[46:49]
	v_mfma_f32_16x16x32_bf16 v[42:45], v[158:161], v[182:185], v[42:45]
	s_waitcnt lgkmcnt(0)
	s_nop 0
	v_mfma_f32_16x16x32_bf16 v[38:41], v[150:153], v[166:169], v[38:41]
	v_mfma_f32_16x16x32_bf16 v[34:37], v[158:161], v[166:169], v[34:37]
	s_setprio 0
	s_setprio 1
	v_mfma_f32_16x16x32_bf16 v[30:33], v[130:133], v[186:189], v[30:33]
	v_mfma_f32_16x16x32_bf16 v[26:29], v[138:141], v[186:189], v[26:29]
	v_mfma_f32_16x16x32_bf16 v[22:25], v[130:133], v[174:177], v[22:25]
	v_mfma_f32_16x16x32_bf16 v[18:21], v[138:141], v[174:177], v[18:21]
	v_mfma_f32_16x16x32_bf16 v[14:17], v[130:133], v[170:173], v[14:17]
	v_mfma_f32_16x16x32_bf16 v[10:13], v[138:141], v[170:173], v[10:13]
	v_mfma_f32_16x16x32_bf16 v[6:9], v[130:133], v[162:165], v[6:9]
	v_mfma_f32_16x16x32_bf16 v[2:5], v[138:141], v[162:165], v[2:5]
	v_mfma_f32_16x16x32_bf16 v[30:33], v[134:137], v[190:193], v[30:33]
	v_mfma_f32_16x16x32_bf16 v[26:29], v[142:145], v[190:193], v[26:29]
	v_mfma_f32_16x16x32_bf16 v[22:25], v[134:137], v[178:181], v[22:25]
	v_mfma_f32_16x16x32_bf16 v[18:21], v[142:145], v[178:181], v[18:21]
	v_mfma_f32_16x16x32_bf16 v[14:17], v[134:137], v[182:185], v[14:17]
	v_mfma_f32_16x16x32_bf16 v[10:13], v[142:145], v[182:185], v[10:13]
	v_mfma_f32_16x16x32_bf16 v[6:9], v[134:137], v[166:169], v[6:9]
	v_mfma_f32_16x16x32_bf16 v[2:5], v[142:145], v[166:169], v[2:5]
	s_setprio 0
	s_barrier
	v_cndmask_b32_e64 v130, 0, 1, s[20:21]
	s_add_i32 s22, s53, s26
	v_cmp_ne_u32_e64 s[2:3], 1, v130
	s_andn2_b64 vcc, exec, s[20:21]
	s_mov_b32 s23, s51
	s_cbranch_vccnz .LBB0_421
	s_lshr_b32 s4, s22, 4
	s_mul_i32 s4, s4, 0x30000
	s_add_i32 s23, s4, 0x2a00000

.LBB0_422:
	ds_read_b128 v[130:133], v203
	ds_read_b128 v[134:137], v204
	ds_read_b128 v[138:141], v205
	ds_read_b128 v[142:145], v206
	ds_read_b128 v[146:149], v207
	ds_read_b128 v[150:153], v208
	ds_read_b128 v[154:157], v209
	ds_read_b128 v[158:161], v210
	s_add_i32 s4, s21, 0xfffe8080
	s_cmp_eq_u32 s51, 2
	s_cselect_b32 s54, s20, s4
	s_cselect_b32 s53, s23, s33
	s_add_i32 s52, s54, 0x80
	s_mov_b32 s4, s70
	s_mov_b32 m0, s42
	ds_read_b128 v[162:165], v211
	ds_read_b128 v[166:169], v211 offset:2048
	ds_read_b128 v[170:173], v212
	ds_read_b128 v[174:177], v212 offset:2048
	ds_read_b128 v[178:181], v211 offset:4096
	ds_read_b128 v[182:185], v211 offset:6144
	ds_read_b128 v[186:189], v212 offset:4096
	ds_read_b128 v[190:193], v212 offset:6144
	buffer_load_dwordx4 v197, s[4:7], s21 offen lds
	s_mov_b32 m0, s44
	s_nop 0
	buffer_load_dwordx4 v199, s[4:7], s21 offen lds
	s_waitcnt vmcnt(8)
	s_waitcnt lgkmcnt(0)
	s_barrier
	s_setprio 1
	s_waitcnt lgkmcnt(7)
	v_mfma_f32_16x16x32_bf16 v[126:129], v[130:133], v[162:165], v[126:129]
	v_mfma_f32_16x16x32_bf16 v[122:125], v[138:141], v[162:165], v[122:125]
	s_waitcnt lgkmcnt(6)
	s_nop 0
	v_mfma_f32_16x16x32_bf16 v[118:121], v[130:133], v[166:169], v[118:121]
	v_mfma_f32_16x16x32_bf16 v[114:117], v[138:141], v[166:169], v[114:117]
	s_waitcnt lgkmcnt(3)
	s_nop 0
	v_mfma_f32_16x16x32_bf16 v[110:113], v[130:133], v[178:181], v[110:113]
	v_mfma_f32_16x16x32_bf16 v[106:109], v[138:141], v[178:181], v[106:109]
	s_waitcnt lgkmcnt(2)
	s_nop 0
	v_mfma_f32_16x16x32_bf16 v[102:105], v[130:133], v[182:185], v[102:105]
	v_mfma_f32_16x16x32_bf16 v[98:101], v[138:141], v[182:185], v[98:101]
	v_mfma_f32_16x16x32_bf16 v[126:129], v[134:137], v[170:173], v[126:129]
	v_mfma_f32_16x16x32_bf16 v[122:125], v[142:145], v[170:173], v[122:125]
	v_mfma_f32_16x16x32_bf16 v[118:121], v[134:137], v[174:177], v[118:121]
	v_mfma_f32_16x16x32_bf16 v[114:117], v[142:145], v[174:177], v[114:117]
	s_waitcnt lgkmcnt(1)
	s_nop 0
	v_mfma_f32_16x16x32_bf16 v[110:113], v[134:137], v[186:189], v[110:113]
	v_mfma_f32_16x16x32_bf16 v[106:109], v[142:145], v[186:189], v[106:109]
	s_waitcnt lgkmcnt(0)
	s_nop 0
	v_mfma_f32_16x16x32_bf16 v[102:105], v[134:137], v[190:193], v[102:105]
	v_mfma_f32_16x16x32_bf16 v[98:101], v[142:145], v[190:193], v[98:101]
	s_setprio 0
	s_setprio 1
	v_mfma_f32_16x16x32_bf16 v[94:97], v[146:149], v[162:165], v[94:97]
	v_mfma_f32_16x16x32_bf16 v[86:89], v[154:157], v[162:165], v[86:89]
	v_mfma_f32_16x16x32_bf16 v[82:85], v[146:149], v[166:169], v[82:85]
	v_mfma_f32_16x16x32_bf16 v[78:81], v[154:157], v[166:169], v[78:81]
	v_mfma_f32_16x16x32_bf16 v[74:77], v[146:149], v[178:181], v[74:77]
	v_mfma_f32_16x16x32_bf16 v[70:73], v[154:157], v[178:181], v[70:73]
	v_mfma_f32_16x16x32_bf16 v[66:69], v[146:149], v[182:185], v[66:69]
	v_mfma_f32_16x16x32_bf16 v[62:65], v[154:157], v[182:185], v[62:65]
	v_mfma_f32_16x16x32_bf16 v[94:97], v[150:153], v[170:173], v[94:97]
	v_mfma_f32_16x16x32_bf16 v[86:89], v[158:161], v[170:173], v[86:89]
	v_mfma_f32_16x16x32_bf16 v[82:85], v[150:153], v[174:177], v[82:85]
	v_mfma_f32_16x16x32_bf16 v[78:81], v[158:161], v[174:177], v[78:81]
	v_mfma_f32_16x16x32_bf16 v[74:77], v[150:153], v[186:189], v[74:77]
	v_mfma_f32_16x16x32_bf16 v[70:73], v[158:161], v[186:189], v[70:73]
	v_mfma_f32_16x16x32_bf16 v[66:69], v[150:153], v[190:193], v[66:69]
	v_mfma_f32_16x16x32_bf16 v[62:65], v[158:161], v[190:193], v[62:65]
	s_setprio 0
	s_barrier
	s_mov_b32 m0, s25
	ds_read_b128 v[162:165], v211 offset:16384
	ds_read_b128 v[166:169], v211 offset:18432
	ds_read_b128 v[170:173], v212 offset:16384
	ds_read_b128 v[174:177], v212 offset:18432
	ds_read_b128 v[178:181], v211 offset:20480
	ds_read_b128 v[182:185], v211 offset:22528
	ds_read_b128 v[186:189], v212 offset:20480
	ds_read_b128 v[190:193], v212 offset:22528
	buffer_load_dwordx4 v198, s[4:7], s53 offen lds
	s_mov_b32 m0, s27
	s_add_i32 s55, s53, 0x18000
	buffer_load_dwordx4 v200, s[4:7], s53 offen lds
	s_mov_b32 m0, s28
	s_nop 0
	buffer_load_dwordx4 v198, s[4:7], s55 offen lds
	s_mov_b32 m0, s29
	s_nop 0
	buffer_load_dwordx4 v200, s[4:7], s55 offen lds
	s_mov_b32 m0, s24
	s_nop 0
	buffer_load_dwordx4 v197, s[4:7], s54 offen lds
	s_mov_b32 m0, s30
	s_nop 0
	buffer_load_dwordx4 v199, s[4:7], s54 offen lds
	s_waitcnt vmcnt(8)
	s_waitcnt lgkmcnt(0)
	s_barrier
	s_setprio 1
	s_waitcnt lgkmcnt(7)
	s_nop 0
	v_mfma_f32_16x16x32_bf16 v[90:93], v[130:133], v[162:165], v[90:93]
	v_mfma_f32_16x16x32_bf16 v[58:61], v[138:141], v[162:165], v[58:61]
	s_waitcnt lgkmcnt(6)
	s_nop 0
	v_mfma_f32_16x16x32_bf16 v[54:57], v[130:133], v[166:169], v[54:57]
	v_mfma_f32_16x16x32_bf16 v[50:53], v[138:141], v[166:169], v[50:53]
	s_waitcnt lgkmcnt(3)
	s_nop 0
	v_mfma_f32_16x16x32_bf16 v[46:49], v[130:133], v[178:181], v[46:49]
	v_mfma_f32_16x16x32_bf16 v[42:45], v[138:141], v[178:181], v[42:45]
	s_waitcnt lgkmcnt(2)
	s_nop 0
	v_mfma_f32_16x16x32_bf16 v[38:41], v[130:133], v[182:185], v[38:41]
	v_mfma_f32_16x16x32_bf16 v[34:37], v[138:141], v[182:185], v[34:37]
	v_mfma_f32_16x16x32_bf16 v[90:93], v[134:137], v[170:173], v[90:93]
	v_mfma_f32_16x16x32_bf16 v[58:61], v[142:145], v[170:173], v[58:61]
	v_mfma_f32_16x16x32_bf16 v[54:57], v[134:137], v[174:177], v[54:57]
	v_mfma_f32_16x16x32_bf16 v[50:53], v[142:145], v[174:177], v[50:53]
	s_waitcnt lgkmcnt(1)
	s_nop 0
	v_mfma_f32_16x16x32_bf16 v[46:49], v[134:137], v[186:189], v[46:49]
	v_mfma_f32_16x16x32_bf16 v[42:45], v[142:145], v[186:189], v[42:45]
	s_waitcnt lgkmcnt(0)
	s_nop 0
	v_mfma_f32_16x16x32_bf16 v[38:41], v[134:137], v[190:193], v[38:41]
	v_mfma_f32_16x16x32_bf16 v[34:37], v[142:145], v[190:193], v[34:37]
	s_setprio 0
	s_setprio 1
	v_mfma_f32_16x16x32_bf16 v[30:33], v[146:149], v[162:165], v[30:33]
	v_mfma_f32_16x16x32_bf16 v[26:29], v[154:157], v[162:165], v[26:29]
	v_mfma_f32_16x16x32_bf16 v[22:25], v[146:149], v[166:169], v[22:25]
	v_mfma_f32_16x16x32_bf16 v[18:21], v[154:157], v[166:169], v[18:21]
	v_mfma_f32_16x16x32_bf16 v[14:17], v[146:149], v[178:181], v[14:17]
	v_mfma_f32_16x16x32_bf16 v[10:13], v[154:157], v[178:181], v[10:13]
	v_mfma_f32_16x16x32_bf16 v[6:9], v[146:149], v[182:185], v[6:9]
	v_mfma_f32_16x16x32_bf16 v[2:5], v[154:157], v[182:185], v[2:5]
	v_mfma_f32_16x16x32_bf16 v[30:33], v[150:153], v[170:173], v[30:33]
	v_mfma_f32_16x16x32_bf16 v[26:29], v[158:161], v[170:173], v[26:29]
	v_mfma_f32_16x16x32_bf16 v[22:25], v[150:153], v[174:177], v[22:25]
	v_mfma_f32_16x16x32_bf16 v[18:21], v[158:161], v[174:177], v[18:21]
	v_mfma_f32_16x16x32_bf16 v[14:17], v[150:153], v[186:189], v[14:17]
	v_mfma_f32_16x16x32_bf16 v[10:13], v[158:161], v[186:189], v[10:13]
	v_mfma_f32_16x16x32_bf16 v[6:9], v[150:153], v[190:193], v[6:9]
	v_mfma_f32_16x16x32_bf16 v[2:5], v[158:161], v[190:193], v[2:5]
	s_setprio 0
	s_barrier
	ds_read_b128 v[130:133], v194
	ds_read_b128 v[134:137], v213
	ds_read_b128 v[138:141], v214
	ds_read_b128 v[142:145], v215
	ds_read_b128 v[146:149], v216
	ds_read_b128 v[150:153], v217
	ds_read_b128 v[154:157], v218
	ds_read_b128 v[158:161], v219
	s_add_i32 s54, s54, 0x18000
	s_mov_b32 m0, s31
	ds_read_b128 v[162:165], v211 offset:32768
	ds_read_b128 v[166:169], v211 offset:34816
	ds_read_b128 v[170:173], v212 offset:32768
	ds_read_b128 v[174:177], v212 offset:34816
	ds_read_b128 v[178:181], v211 offset:36864
	ds_read_b128 v[182:185], v211 offset:38912
	ds_read_b128 v[186:189], v212 offset:36864
	ds_read_b128 v[190:193], v212 offset:38912
	buffer_load_dwordx4 v197, s[4:7], s54 offen lds
	s_mov_b32 m0, s34
	s_nop 0
	buffer_load_dwordx4 v199, s[4:7], s54 offen lds
	s_waitcnt vmcnt(8)
	s_waitcnt lgkmcnt(0)
	s_barrier
	s_setprio 1
	s_waitcnt lgkmcnt(7)
	v_mfma_f32_16x16x32_bf16 v[126:129], v[130:133], v[162:165], v[126:129]
	v_mfma_f32_16x16x32_bf16 v[122:125], v[138:141], v[162:165], v[122:125]
	s_waitcnt lgkmcnt(6)
	s_nop 0
	v_mfma_f32_16x16x32_bf16 v[118:121], v[130:133], v[166:169], v[118:121]
	v_mfma_f32_16x16x32_bf16 v[114:117], v[138:141], v[166:169], v[114:117]
	s_waitcnt lgkmcnt(3)
	s_nop 0
	v_mfma_f32_16x16x32_bf16 v[110:113], v[130:133], v[178:181], v[110:113]
	v_mfma_f32_16x16x32_bf16 v[106:109], v[138:141], v[178:181], v[106:109]
	s_waitcnt lgkmcnt(2)
	s_nop 0
	v_mfma_f32_16x16x32_bf16 v[102:105], v[130:133], v[182:185], v[102:105]
	v_mfma_f32_16x16x32_bf16 v[98:101], v[138:141], v[182:185], v[98:101]
	v_mfma_f32_16x16x32_bf16 v[126:129], v[134:137], v[170:173], v[126:129]
	v_mfma_f32_16x16x32_bf16 v[122:125], v[142:145], v[170:173], v[122:125]
	v_mfma_f32_16x16x32_bf16 v[118:121], v[134:137], v[174:177], v[118:121]
	v_mfma_f32_16x16x32_bf16 v[114:117], v[142:145], v[174:177], v[114:117]
	s_waitcnt lgkmcnt(1)
	s_nop 0
	v_mfma_f32_16x16x32_bf16 v[110:113], v[134:137], v[186:189], v[110:113]
	v_mfma_f32_16x16x32_bf16 v[106:109], v[142:145], v[186:189], v[106:109]
	s_waitcnt lgkmcnt(0)
	s_nop 0
	v_mfma_f32_16x16x32_bf16 v[102:105], v[134:137], v[190:193], v[102:105]
	v_mfma_f32_16x16x32_bf16 v[98:101], v[142:145], v[190:193], v[98:101]
	s_setprio 0
	s_setprio 1
	v_mfma_f32_16x16x32_bf16 v[94:97], v[146:149], v[162:165], v[94:97]
	v_mfma_f32_16x16x32_bf16 v[86:89], v[154:157], v[162:165], v[86:89]
	v_mfma_f32_16x16x32_bf16 v[82:85], v[146:149], v[166:169], v[82:85]
	v_mfma_f32_16x16x32_bf16 v[78:81], v[154:157], v[166:169], v[78:81]
	v_mfma_f32_16x16x32_bf16 v[74:77], v[146:149], v[178:181], v[74:77]
	v_mfma_f32_16x16x32_bf16 v[70:73], v[154:157], v[178:181], v[70:73]
	v_mfma_f32_16x16x32_bf16 v[66:69], v[146:149], v[182:185], v[66:69]
	v_mfma_f32_16x16x32_bf16 v[62:65], v[154:157], v[182:185], v[62:65]
	v_mfma_f32_16x16x32_bf16 v[94:97], v[150:153], v[170:173], v[94:97]
	v_mfma_f32_16x16x32_bf16 v[86:89], v[158:161], v[170:173], v[86:89]
	v_mfma_f32_16x16x32_bf16 v[82:85], v[150:153], v[174:177], v[82:85]
	v_mfma_f32_16x16x32_bf16 v[78:81], v[158:161], v[174:177], v[78:81]
	v_mfma_f32_16x16x32_bf16 v[74:77], v[150:153], v[186:189], v[74:77]
	v_mfma_f32_16x16x32_bf16 v[70:73], v[158:161], v[186:189], v[70:73]
	v_mfma_f32_16x16x32_bf16 v[66:69], v[150:153], v[190:193], v[66:69]
	v_mfma_f32_16x16x32_bf16 v[62:65], v[158:161], v[190:193], v[62:65]
	s_setprio 0
	s_barrier
	s_mov_b32 m0, s36
	s_add_i32 s54, s53, 0x80
	ds_read_b128 v[162:165], v211 offset:49152
	ds_read_b128 v[166:169], v211 offset:51200
	ds_read_b128 v[170:173], v212 offset:49152
	ds_read_b128 v[174:177], v212 offset:51200
	ds_read_b128 v[178:181], v211 offset:53248
	ds_read_b128 v[182:185], v211 offset:55296
	ds_read_b128 v[186:189], v212 offset:53248
	ds_read_b128 v[190:193], v212 offset:55296
	buffer_load_dwordx4 v198, s[4:7], s54 offen lds
	s_mov_b32 m0, s37
	s_add_i32 s53, s53, 0x18080
	buffer_load_dwordx4 v200, s[4:7], s54 offen lds
	s_mov_b32 m0, s40
	s_nop 0
	buffer_load_dwordx4 v198, s[4:7], s53 offen lds
	s_mov_b32 m0, s41
	s_nop 0
	buffer_load_dwordx4 v200, s[4:7], s53 offen lds
	s_mov_b32 m0, s38
	s_nop 0
	buffer_load_dwordx4 v197, s[4:7], s52 offen lds
	s_mov_b32 m0, s39
	s_nop 0
	buffer_load_dwordx4 v199, s[4:7], s52 offen lds
	s_waitcnt vmcnt(8)
	s_waitcnt lgkmcnt(0)
	s_barrier
	s_setprio 1
	s_waitcnt lgkmcnt(7)
	s_nop 0
	v_mfma_f32_16x16x32_bf16 v[90:93], v[130:133], v[162:165], v[90:93]
	v_mfma_f32_16x16x32_bf16 v[58:61], v[138:141], v[162:165], v[58:61]
	s_waitcnt lgkmcnt(6)
	s_nop 0
	v_mfma_f32_16x16x32_bf16 v[54:57], v[130:133], v[166:169], v[54:57]
	v_mfma_f32_16x16x32_bf16 v[50:53], v[138:141], v[166:169], v[50:53]
	s_waitcnt lgkmcnt(3)
	s_nop 0
	v_mfma_f32_16x16x32_bf16 v[46:49], v[130:133], v[178:181], v[46:49]
	v_mfma_f32_16x16x32_bf16 v[42:45], v[138:141], v[178:181], v[42:45]
	s_waitcnt lgkmcnt(2)
	s_nop 0
	v_mfma_f32_16x16x32_bf16 v[38:41], v[130:133], v[182:185], v[38:41]
	v_mfma_f32_16x16x32_bf16 v[34:37], v[138:141], v[182:185], v[34:37]
	v_mfma_f32_16x16x32_bf16 v[90:93], v[134:137], v[170:173], v[90:93]
	v_mfma_f32_16x16x32_bf16 v[58:61], v[142:145], v[170:173], v[58:61]
	v_mfma_f32_16x16x32_bf16 v[54:57], v[134:137], v[174:177], v[54:57]
	v_mfma_f32_16x16x32_bf16 v[50:53], v[142:145], v[174:177], v[50:53]
	s_waitcnt lgkmcnt(1)
	s_nop 0
	v_mfma_f32_16x16x32_bf16 v[46:49], v[134:137], v[186:189], v[46:49]
	v_mfma_f32_16x16x32_bf16 v[42:45], v[142:145], v[186:189], v[42:45]
	s_waitcnt lgkmcnt(0)
	s_nop 0
	v_mfma_f32_16x16x32_bf16 v[38:41], v[134:137], v[190:193], v[38:41]
	v_mfma_f32_16x16x32_bf16 v[34:37], v[142:145], v[190:193], v[34:37]
	s_setprio 0
	s_setprio 1
	v_mfma_f32_16x16x32_bf16 v[30:33], v[146:149], v[162:165], v[30:33]
	v_mfma_f32_16x16x32_bf16 v[26:29], v[154:157], v[162:165], v[26:29]
	v_mfma_f32_16x16x32_bf16 v[22:25], v[146:149], v[166:169], v[22:25]
	v_mfma_f32_16x16x32_bf16 v[18:21], v[154:157], v[166:169], v[18:21]
	v_mfma_f32_16x16x32_bf16 v[14:17], v[146:149], v[178:181], v[14:17]
	v_mfma_f32_16x16x32_bf16 v[10:13], v[154:157], v[178:181], v[10:13]
	v_mfma_f32_16x16x32_bf16 v[6:9], v[146:149], v[182:185], v[6:9]
	v_mfma_f32_16x16x32_bf16 v[2:5], v[154:157], v[182:185], v[2:5]
	v_mfma_f32_16x16x32_bf16 v[30:33], v[150:153], v[170:173], v[30:33]
	v_mfma_f32_16x16x32_bf16 v[26:29], v[158:161], v[170:173], v[26:29]
	v_mfma_f32_16x16x32_bf16 v[22:25], v[150:153], v[174:177], v[22:25]
	v_mfma_f32_16x16x32_bf16 v[18:21], v[158:161], v[174:177], v[18:21]
	v_mfma_f32_16x16x32_bf16 v[14:17], v[150:153], v[186:189], v[14:17]
	v_mfma_f32_16x16x32_bf16 v[10:13], v[158:161], v[186:189], v[10:13]
	v_mfma_f32_16x16x32_bf16 v[6:9], v[150:153], v[190:193], v[6:9]
	v_mfma_f32_16x16x32_bf16 v[2:5], v[158:161], v[190:193], v[2:5]
	s_setprio 0
	s_barrier
	s_add_i32 s51, s51, 2
	s_addk_i32 s21, 0x100
	s_addk_i32 s33, 0x100
	s_cmp_gt_u32 s51, 3
	s_cbranch_scc0 .LBB0_422
	s_and_b64 vcc, exec, s[16:17]
	s_cbranch_vccz .LBB0_425
	s_barrier

.LBB0_530:
	s_waitcnt lgkmcnt(0)
	s_add_i32 s33, s55, 0x100
	s_add_i32 s53, s61, 0x100
	s_barrier
	s_setprio 1
	s_waitcnt lgkmcnt(7)
	v_mfma_f32_16x16x32_bf16 v[126:129], v[158:161], v[186:189], 0
	v_mfma_f32_16x16x32_bf16 v[122:125], v[150:153], v[186:189], 0
	s_waitcnt lgkmcnt(6)
	s_nop 0
	v_mfma_f32_16x16x32_bf16 v[118:121], v[158:161], v[178:181], 0
	v_mfma_f32_16x16x32_bf16 v[114:117], v[150:153], v[178:181], 0
	s_waitcnt lgkmcnt(3)
	s_nop 0
	v_mfma_f32_16x16x32_bf16 v[110:113], v[158:161], v[170:173], 0
	v_mfma_f32_16x16x32_bf16 v[106:109], v[150:153], v[170:173], 0
	s_waitcnt lgkmcnt(2)
	s_nop 0
	v_mfma_f32_16x16x32_bf16 v[102:105], v[158:161], v[162:165], 0
	v_mfma_f32_16x16x32_bf16 v[98:101], v[150:153], v[162:165], 0
	v_mfma_f32_16x16x32_bf16 v[126:129], v[154:157], v[190:193], v[126:129]
	v_mfma_f32_16x16x32_bf16 v[122:125], v[146:149], v[190:193], v[122:125]
	v_mfma_f32_16x16x32_bf16 v[118:121], v[154:157], v[182:185], v[118:121]
	v_mfma_f32_16x16x32_bf16 v[114:117], v[146:149], v[182:185], v[114:117]
	s_waitcnt lgkmcnt(1)
	s_nop 0
	v_mfma_f32_16x16x32_bf16 v[110:113], v[154:157], v[174:177], v[110:113]
	v_mfma_f32_16x16x32_bf16 v[106:109], v[146:149], v[174:177], v[106:109]
	s_waitcnt lgkmcnt(0)
	s_nop 0
	v_mfma_f32_16x16x32_bf16 v[102:105], v[154:157], v[166:169], v[102:105]
	v_mfma_f32_16x16x32_bf16 v[98:101], v[146:149], v[166:169], v[98:101]
	s_setprio 0
	s_setprio 1
	v_mfma_f32_16x16x32_bf16 v[94:97], v[142:145], v[186:189], 0
	v_mfma_f32_16x16x32_bf16 v[90:93], v[134:137], v[186:189], 0
	v_mfma_f32_16x16x32_bf16 v[86:89], v[142:145], v[178:181], 0
	v_mfma_f32_16x16x32_bf16 v[82:85], v[134:137], v[178:181], 0
	v_mfma_f32_16x16x32_bf16 v[78:81], v[142:145], v[170:173], 0
	v_mfma_f32_16x16x32_bf16 v[74:77], v[134:137], v[170:173], 0
	v_mfma_f32_16x16x32_bf16 v[70:73], v[142:145], v[162:165], 0
	v_mfma_f32_16x16x32_bf16 v[66:69], v[134:137], v[162:165], 0
	s_nop 0
	s_nop 0
	v_mfma_f32_16x16x32_bf16 v[94:97], v[138:141], v[190:193], v[94:97]
	v_mfma_f32_16x16x32_bf16 v[90:93], v[130:133], v[190:193], v[90:93]
	v_mfma_f32_16x16x32_bf16 v[86:89], v[138:141], v[182:185], v[86:89]
	v_mfma_f32_16x16x32_bf16 v[82:85], v[130:133], v[182:185], v[82:85]
	v_mfma_f32_16x16x32_bf16 v[78:81], v[138:141], v[174:177], v[78:81]
	v_mfma_f32_16x16x32_bf16 v[74:77], v[130:133], v[174:177], v[74:77]
	v_mfma_f32_16x16x32_bf16 v[70:73], v[138:141], v[166:169], v[70:73]
	v_mfma_f32_16x16x32_bf16 v[66:69], v[130:133], v[166:169], v[66:69]
	s_setprio 0
	s_barrier
	s_cmp_lg_u32 s59, 0
	s_cselect_b64 s[20:21], -1, 0
	s_cmp_eq_u32 s59, 0
	s_cselect_b64 s[2:3], -1, 0
	v_cndmask_b32_e64 v194, v200, 0, s[2:3]
	s_mov_b32 m0, s25
	v_sub_u32_e32 v233, v201, v194
	s_mov_b32 s4, s70
	v_cndmask_b32_e64 v194, v203, 0, s[2:3]
	ds_read_b128 v[186:189], v219 offset:16384
	ds_read_b128 v[178:181], v219 offset:18432
	ds_read_b128 v[190:193], v220 offset:16384
	ds_read_b128 v[182:185], v220 offset:18432
	ds_read_b128 v[170:173], v219 offset:20480
	ds_read_b128 v[162:165], v219 offset:22528
	ds_read_b128 v[174:177], v220 offset:20480
	ds_read_b128 v[166:169], v220 offset:22528
	buffer_load_dwordx4 v233, s[4:7], s53 offen lds
	v_sub_u32_e32 v234, v204, v194
	s_mov_b32 m0, s26
	v_cndmask_b32_e64 v194, v205, 0, s[2:3]
	buffer_load_dwordx4 v234, s[4:7], s53 offen lds
	s_add_i32 s53, s53, s60
	s_mov_b32 m0, s27
	v_sub_u32_e32 v194, v1, v194
	buffer_load_dwordx4 v233, s[4:7], s53 offen lds
	s_mov_b32 m0, s28
	v_cndmask_b32_e64 v222, v206, 0, s[2:3]
	buffer_load_dwordx4 v234, s[4:7], s53 offen lds
	s_mov_b32 m0, s24
	v_sub_u32_e32 v222, v202, v222
	buffer_load_dwordx4 v194, s[4:7], s33 offen lds
	s_mov_b32 m0, s29
	v_cndmask_b32_e64 v223, 0, 1, s[22:23]
	buffer_load_dwordx4 v222, s[4:7], s33 offen lds
	v_cmp_ne_u32_e64 s[2:3], 1, v223
	s_andn2_b64 vcc, exec, s[22:23]
	s_cbranch_vccnz .LBB0_557
	s_waitcnt vmcnt(14)
	s_cbranch_execnz .LBB0_533

.LBB0_533:
	s_waitcnt lgkmcnt(0)
	s_barrier
	s_setprio 1
	s_waitcnt lgkmcnt(7)
	s_nop 0
	v_mfma_f32_16x16x32_bf16 v[62:65], v[158:161], v[186:189], 0
	v_mfma_f32_16x16x32_bf16 v[58:61], v[150:153], v[186:189], 0
	s_waitcnt lgkmcnt(6)
	s_nop 0
	v_mfma_f32_16x16x32_bf16 v[54:57], v[158:161], v[178:181], 0
	v_mfma_f32_16x16x32_bf16 v[50:53], v[150:153], v[178:181], 0
	s_waitcnt lgkmcnt(3)
	s_nop 0
	v_mfma_f32_16x16x32_bf16 v[46:49], v[158:161], v[170:173], 0
	v_mfma_f32_16x16x32_bf16 v[42:45], v[150:153], v[170:173], 0
	s_waitcnt lgkmcnt(2)
	s_nop 0
	v_mfma_f32_16x16x32_bf16 v[38:41], v[158:161], v[162:165], 0
	v_mfma_f32_16x16x32_bf16 v[34:37], v[150:153], v[162:165], 0
	v_mfma_f32_16x16x32_bf16 v[62:65], v[154:157], v[190:193], v[62:65]
	v_mfma_f32_16x16x32_bf16 v[58:61], v[146:149], v[190:193], v[58:61]
	v_mfma_f32_16x16x32_bf16 v[54:57], v[154:157], v[182:185], v[54:57]
	v_mfma_f32_16x16x32_bf16 v[50:53], v[146:149], v[182:185], v[50:53]
	s_waitcnt lgkmcnt(1)
	s_nop 0
	v_mfma_f32_16x16x32_bf16 v[46:49], v[154:157], v[174:177], v[46:49]
	v_mfma_f32_16x16x32_bf16 v[42:45], v[146:149], v[174:177], v[42:45]
	s_waitcnt lgkmcnt(0)
	s_nop 0
	v_mfma_f32_16x16x32_bf16 v[38:41], v[154:157], v[166:169], v[38:41]
	v_mfma_f32_16x16x32_bf16 v[34:37], v[146:149], v[166:169], v[34:37]
	s_setprio 0
	s_setprio 1
	v_mfma_f32_16x16x32_bf16 v[30:33], v[142:145], v[186:189], 0
	v_mfma_f32_16x16x32_bf16 v[26:29], v[134:137], v[186:189], 0
	v_mfma_f32_16x16x32_bf16 v[22:25], v[142:145], v[178:181], 0
	v_mfma_f32_16x16x32_bf16 v[18:21], v[134:137], v[178:181], 0
	v_mfma_f32_16x16x32_bf16 v[14:17], v[142:145], v[170:173], 0
	v_mfma_f32_16x16x32_bf16 v[10:13], v[134:137], v[170:173], 0
	v_mfma_f32_16x16x32_bf16 v[6:9], v[142:145], v[162:165], 0
	v_mfma_f32_16x16x32_bf16 v[2:5], v[134:137], v[162:165], 0
	s_nop 0
	s_nop 0
	v_mfma_f32_16x16x32_bf16 v[30:33], v[138:141], v[190:193], v[30:33]
	v_mfma_f32_16x16x32_bf16 v[26:29], v[130:133], v[190:193], v[26:29]
	v_mfma_f32_16x16x32_bf16 v[22:25], v[138:141], v[182:185], v[22:25]
	v_mfma_f32_16x16x32_bf16 v[18:21], v[130:133], v[182:185], v[18:21]
	v_mfma_f32_16x16x32_bf16 v[14:17], v[138:141], v[174:177], v[14:17]
	v_mfma_f32_16x16x32_bf16 v[10:13], v[130:133], v[174:177], v[10:13]
	v_mfma_f32_16x16x32_bf16 v[6:9], v[138:141], v[166:169], v[6:9]
	v_mfma_f32_16x16x32_bf16 v[2:5], v[130:133], v[166:169], v[2:5]
	s_setprio 0
	s_barrier
	s_add_i32 s4, 0, 0x18000
	v_add_u32_e32 v223, s4, v209
	v_add_u32_e32 v224, s4, v210
	s_add_i32 s4, 0, 0x1c000
	v_add_u32_e32 v225, s46, v209
	v_add_u32_e32 v228, s4, v209
	v_add_u32_e32 v230, s47, v209
	ds_read_b128 v[146:149], v223
	ds_read_b128 v[150:153], v224
	v_add_u32_e32 v227, s46, v210
	ds_read_b128 v[154:157], v225
	ds_read_b128 v[158:161], v227
	v_add_u32_e32 v229, s4, v210
	ds_read_b128 v[130:133], v228
	ds_read_b128 v[134:137], v229
	v_add_u32_e32 v231, s47, v210
	ds_read_b128 v[138:141], v230
	ds_read_b128 v[142:145], v231
	s_mov_b32 m0, s30
	s_add_i32 s33, s33, s60
	s_mov_b32 s4, s70
	ds_read_b128 v[186:189], v219 offset:32768
	ds_read_b128 v[174:177], v219 offset:34816
	ds_read_b128 v[190:193], v220 offset:32768
	ds_read_b128 v[178:181], v220 offset:34816
	ds_read_b128 v[170:173], v219 offset:36864
	ds_read_b128 v[162:165], v219 offset:38912
	ds_read_b128 v[182:185], v220 offset:36864
	ds_read_b128 v[166:169], v220 offset:38912
	buffer_load_dwordx4 v194, s[4:7], s33 offen lds
	s_mov_b32 m0, s31
	s_and_b64 vcc, exec, s[2:3]
	buffer_load_dwordx4 v222, s[4:7], s33 offen lds
	s_cbranch_vccnz .LBB0_558
	s_waitcnt vmcnt(16)
	s_cbranch_execnz .LBB0_536

.LBB0_536:
	s_waitcnt lgkmcnt(0)
	s_add_i32 s62, s55, 0x180
	s_add_i32 s22, s61, 0x180
	s_barrier
	s_setprio 1
	s_waitcnt lgkmcnt(7)
	s_nop 0
	v_mfma_f32_16x16x32_bf16 v[126:129], v[146:149], v[186:189], v[126:129]
	v_mfma_f32_16x16x32_bf16 v[122:125], v[154:157], v[186:189], v[122:125]
	s_waitcnt lgkmcnt(6)
	s_nop 0
	v_mfma_f32_16x16x32_bf16 v[118:121], v[146:149], v[174:177], v[118:121]
	v_mfma_f32_16x16x32_bf16 v[114:117], v[154:157], v[174:177], v[114:117]
	s_waitcnt lgkmcnt(3)
	s_nop 0
	v_mfma_f32_16x16x32_bf16 v[110:113], v[146:149], v[170:173], v[110:113]
	v_mfma_f32_16x16x32_bf16 v[106:109], v[154:157], v[170:173], v[106:109]
	s_waitcnt lgkmcnt(2)
	s_nop 0
	v_mfma_f32_16x16x32_bf16 v[102:105], v[146:149], v[162:165], v[102:105]
	v_mfma_f32_16x16x32_bf16 v[98:101], v[154:157], v[162:165], v[98:101]
	v_mfma_f32_16x16x32_bf16 v[126:129], v[150:153], v[190:193], v[126:129]
	v_mfma_f32_16x16x32_bf16 v[122:125], v[158:161], v[190:193], v[122:125]
	v_mfma_f32_16x16x32_bf16 v[118:121], v[150:153], v[178:181], v[118:121]
	v_mfma_f32_16x16x32_bf16 v[114:117], v[158:161], v[178:181], v[114:117]
	s_waitcnt lgkmcnt(1)
	s_nop 0
	v_mfma_f32_16x16x32_bf16 v[110:113], v[150:153], v[182:185], v[110:113]
	v_mfma_f32_16x16x32_bf16 v[106:109], v[158:161], v[182:185], v[106:109]
	s_waitcnt lgkmcnt(0)
	s_nop 0
	v_mfma_f32_16x16x32_bf16 v[102:105], v[150:153], v[166:169], v[102:105]
	v_mfma_f32_16x16x32_bf16 v[98:101], v[158:161], v[166:169], v[98:101]
	s_setprio 0
	s_setprio 1
	v_mfma_f32_16x16x32_bf16 v[94:97], v[130:133], v[186:189], v[94:97]
	v_mfma_f32_16x16x32_bf16 v[90:93], v[138:141], v[186:189], v[90:93]
	v_mfma_f32_16x16x32_bf16 v[86:89], v[130:133], v[174:177], v[86:89]
	v_mfma_f32_16x16x32_bf16 v[82:85], v[138:141], v[174:177], v[82:85]
	v_mfma_f32_16x16x32_bf16 v[78:81], v[130:133], v[170:173], v[78:81]
	v_mfma_f32_16x16x32_bf16 v[74:77], v[138:141], v[170:173], v[74:77]
	v_mfma_f32_16x16x32_bf16 v[70:73], v[130:133], v[162:165], v[70:73]
	v_mfma_f32_16x16x32_bf16 v[66:69], v[138:141], v[162:165], v[66:69]
	v_mfma_f32_16x16x32_bf16 v[94:97], v[134:137], v[190:193], v[94:97]
	v_mfma_f32_16x16x32_bf16 v[90:93], v[142:145], v[190:193], v[90:93]
	v_mfma_f32_16x16x32_bf16 v[86:89], v[134:137], v[178:181], v[86:89]
	v_mfma_f32_16x16x32_bf16 v[82:85], v[142:145], v[178:181], v[82:85]
	v_mfma_f32_16x16x32_bf16 v[78:81], v[134:137], v[182:185], v[78:81]
	v_mfma_f32_16x16x32_bf16 v[74:77], v[142:145], v[182:185], v[74:77]
	v_mfma_f32_16x16x32_bf16 v[70:73], v[134:137], v[166:169], v[70:73]
	v_mfma_f32_16x16x32_bf16 v[66:69], v[142:145], v[166:169], v[66:69]
	s_setprio 0
	s_barrier
	s_mov_b32 m0, s36
	s_mov_b32 s4, s70
	ds_read_b128 v[186:189], v219 offset:49152
	ds_read_b128 v[174:177], v219 offset:51200
	ds_read_b128 v[190:193], v220 offset:49152
	ds_read_b128 v[178:181], v220 offset:51200
	ds_read_b128 v[170:173], v219 offset:53248
	ds_read_b128 v[162:165], v219 offset:55296
	ds_read_b128 v[182:185], v220 offset:53248
	ds_read_b128 v[166:169], v220 offset:55296
	buffer_load_dwordx4 v233, s[4:7], s22 offen lds
	s_mov_b32 m0, s37
	s_and_b64 vcc, exec, s[2:3]
	buffer_load_dwordx4 v234, s[4:7], s22 offen lds
	s_add_i32 s22, s22, s60
	s_mov_b32 m0, s40
	s_nop 0
	buffer_load_dwordx4 v233, s[4:7], s22 offen lds
	s_mov_b32 m0, s41
	s_nop 0
	buffer_load_dwordx4 v234, s[4:7], s22 offen lds
	s_mov_b32 m0, s38
	s_nop 0
	buffer_load_dwordx4 v194, s[4:7], s62 offen lds
	s_mov_b32 m0, s39
	s_nop 0
	buffer_load_dwordx4 v222, s[4:7], s62 offen lds
	s_cbranch_vccnz .LBB0_559
	s_waitcnt vmcnt(22)
	s_cbranch_execnz .LBB0_539

.LBB0_539:
	s_waitcnt lgkmcnt(0)
	s_barrier
	s_setprio 1
	s_waitcnt lgkmcnt(7)
	s_nop 0
	v_mfma_f32_16x16x32_bf16 v[62:65], v[146:149], v[186:189], v[62:65]
	v_mfma_f32_16x16x32_bf16 v[58:61], v[154:157], v[186:189], v[58:61]
	s_waitcnt lgkmcnt(6)
	s_nop 0
	v_mfma_f32_16x16x32_bf16 v[54:57], v[146:149], v[174:177], v[54:57]
	v_mfma_f32_16x16x32_bf16 v[50:53], v[154:157], v[174:177], v[50:53]
	s_waitcnt lgkmcnt(3)
	s_nop 0
	v_mfma_f32_16x16x32_bf16 v[46:49], v[146:149], v[170:173], v[46:49]
	v_mfma_f32_16x16x32_bf16 v[42:45], v[154:157], v[170:173], v[42:45]
	s_waitcnt lgkmcnt(2)
	s_nop 0
	v_mfma_f32_16x16x32_bf16 v[38:41], v[146:149], v[162:165], v[38:41]
	v_mfma_f32_16x16x32_bf16 v[34:37], v[154:157], v[162:165], v[34:37]
	v_mfma_f32_16x16x32_bf16 v[62:65], v[150:153], v[190:193], v[62:65]
	v_mfma_f32_16x16x32_bf16 v[58:61], v[158:161], v[190:193], v[58:61]
	v_mfma_f32_16x16x32_bf16 v[54:57], v[150:153], v[178:181], v[54:57]
	v_mfma_f32_16x16x32_bf16 v[50:53], v[158:161], v[178:181], v[50:53]
	s_waitcnt lgkmcnt(1)
	s_nop 0
	v_mfma_f32_16x16x32_bf16 v[46:49], v[150:153], v[182:185], v[46:49]
	v_mfma_f32_16x16x32_bf16 v[42:45], v[158:161], v[182:185], v[42:45]
	s_waitcnt lgkmcnt(0)
	s_nop 0
	v_mfma_f32_16x16x32_bf16 v[38:41], v[150:153], v[166:169], v[38:41]
	v_mfma_f32_16x16x32_bf16 v[34:37], v[158:161], v[166:169], v[34:37]
	s_setprio 0
	s_setprio 1
	v_mfma_f32_16x16x32_bf16 v[30:33], v[130:133], v[186:189], v[30:33]
	v_mfma_f32_16x16x32_bf16 v[26:29], v[138:141], v[186:189], v[26:29]
	v_mfma_f32_16x16x32_bf16 v[22:25], v[130:133], v[174:177], v[22:25]
	v_mfma_f32_16x16x32_bf16 v[18:21], v[138:141], v[174:177], v[18:21]
	v_mfma_f32_16x16x32_bf16 v[14:17], v[130:133], v[170:173], v[14:17]
	v_mfma_f32_16x16x32_bf16 v[10:13], v[138:141], v[170:173], v[10:13]
	v_mfma_f32_16x16x32_bf16 v[6:9], v[130:133], v[162:165], v[6:9]
	v_mfma_f32_16x16x32_bf16 v[2:5], v[138:141], v[162:165], v[2:5]
	v_mfma_f32_16x16x32_bf16 v[30:33], v[134:137], v[190:193], v[30:33]
	v_mfma_f32_16x16x32_bf16 v[26:29], v[142:145], v[190:193], v[26:29]
	v_mfma_f32_16x16x32_bf16 v[22:25], v[134:137], v[178:181], v[22:25]
	v_mfma_f32_16x16x32_bf16 v[18:21], v[142:145], v[178:181], v[18:21]
	v_mfma_f32_16x16x32_bf16 v[14:17], v[134:137], v[182:185], v[14:17]
	v_mfma_f32_16x16x32_bf16 v[10:13], v[142:145], v[182:185], v[10:13]
	v_mfma_f32_16x16x32_bf16 v[6:9], v[134:137], v[166:169], v[6:9]
	v_mfma_f32_16x16x32_bf16 v[2:5], v[142:145], v[166:169], v[2:5]
	s_setprio 0
	s_barrier
	s_add_i32 s53, s54, 1
	s_mul_hi_u32 s2, s53, 0xaaaaaaab
	s_lshr_b32 s4, s2, 1
	s_mul_i32 s3, s4, s94
	s_mul_hi_i32 s2, s4, s94
	s_add_u32 s22, s3, s95
	s_addc_u32 s23, s2, s45
	v_cmp_gt_i64_e32 vcc, s[22:23], v[198:199]
	v_cmp_lt_i64_e64 s[2:3], s[22:23], v[196:197]
	s_mov_b32 s33, s59
	s_cbranch_vccnz .LBB0_545
	s_ashr_i32 s23, s22, 31
	s_lshr_b32 s23, s23, 29
	s_add_i32 s33, s22, s23
	s_and_b32 s23, s33, -8
	s_sub_i32 s51, s22, s23
	s_cmp_gt_i32 s51, -1
	s_mov_b64 s[22:23], -1
	s_cbranch_scc0 .LBB0_542
	s_lshl_b32 s50, s51, 7
	s_mov_b64 s[22:23], 0

.LBB0_546:
	ds_read_b128 v[130:133], v211
	ds_read_b128 v[134:137], v212
	ds_read_b128 v[138:141], v213
	ds_read_b128 v[142:145], v214
	ds_read_b128 v[146:149], v215
	ds_read_b128 v[150:153], v216
	ds_read_b128 v[154:157], v217
	ds_read_b128 v[158:161], v218
	s_add_i32 s4, s62, 0x80
	s_cmp_eq_u32 s63, s78
	s_cselect_b32 s84, s64, s4
	s_cselect_b32 s82, s33, s59
	s_cselect_b32 s81, s65, s61
	s_cselect_b32 s80, s56, s60
	s_add_i32 s79, s84, 0x80
	s_add_i32 s83, s60, s62
	s_mov_b32 s4, s70
	s_mov_b32 m0, s43
	ds_read_b128 v[162:165], v219
	ds_read_b128 v[166:169], v219 offset:2048
	ds_read_b128 v[170:173], v220
	ds_read_b128 v[174:177], v220 offset:2048
	ds_read_b128 v[178:181], v219 offset:4096
	ds_read_b128 v[182:185], v219 offset:6144
	ds_read_b128 v[186:189], v220 offset:4096
	ds_read_b128 v[190:193], v220 offset:6144
	buffer_load_dwordx4 v194, s[4:7], s83 offen lds
	s_mov_b32 m0, s44
	s_nop 0
	buffer_load_dwordx4 v222, s[4:7], s83 offen lds
	s_waitcnt vmcnt(8)
	s_waitcnt lgkmcnt(0)
	s_barrier
	s_setprio 1
	s_waitcnt lgkmcnt(7)
	s_nop 0
	v_mfma_f32_16x16x32_bf16 v[126:129], v[130:133], v[162:165], v[126:129]
	v_mfma_f32_16x16x32_bf16 v[122:125], v[138:141], v[162:165], v[122:125]
	s_waitcnt lgkmcnt(6)
	s_nop 0
	v_mfma_f32_16x16x32_bf16 v[118:121], v[130:133], v[166:169], v[118:121]
	v_mfma_f32_16x16x32_bf16 v[114:117], v[138:141], v[166:169], v[114:117]
	s_waitcnt lgkmcnt(3)
	s_nop 0
	v_mfma_f32_16x16x32_bf16 v[110:113], v[130:133], v[178:181], v[110:113]
	v_mfma_f32_16x16x32_bf16 v[106:109], v[138:141], v[178:181], v[106:109]
	s_waitcnt lgkmcnt(2)
	s_nop 0
	v_mfma_f32_16x16x32_bf16 v[102:105], v[130:133], v[182:185], v[102:105]
	v_mfma_f32_16x16x32_bf16 v[98:101], v[138:141], v[182:185], v[98:101]
	v_mfma_f32_16x16x32_bf16 v[126:129], v[134:137], v[170:173], v[126:129]
	v_mfma_f32_16x16x32_bf16 v[122:125], v[142:145], v[170:173], v[122:125]
	v_mfma_f32_16x16x32_bf16 v[118:121], v[134:137], v[174:177], v[118:121]
	v_mfma_f32_16x16x32_bf16 v[114:117], v[142:145], v[174:177], v[114:117]
	s_waitcnt lgkmcnt(1)
	s_nop 0
	v_mfma_f32_16x16x32_bf16 v[110:113], v[134:137], v[186:189], v[110:113]
	v_mfma_f32_16x16x32_bf16 v[106:109], v[142:145], v[186:189], v[106:109]
	s_waitcnt lgkmcnt(0)
	s_nop 0
	v_mfma_f32_16x16x32_bf16 v[102:105], v[134:137], v[190:193], v[102:105]
	v_mfma_f32_16x16x32_bf16 v[98:101], v[142:145], v[190:193], v[98:101]
	s_setprio 0
	s_setprio 1
	v_mfma_f32_16x16x32_bf16 v[94:97], v[146:149], v[162:165], v[94:97]
	v_mfma_f32_16x16x32_bf16 v[90:93], v[154:157], v[162:165], v[90:93]
	v_mfma_f32_16x16x32_bf16 v[86:89], v[146:149], v[166:169], v[86:89]
	v_mfma_f32_16x16x32_bf16 v[82:85], v[154:157], v[166:169], v[82:85]
	v_mfma_f32_16x16x32_bf16 v[78:81], v[146:149], v[178:181], v[78:81]
	v_mfma_f32_16x16x32_bf16 v[74:77], v[154:157], v[178:181], v[74:77]
	v_mfma_f32_16x16x32_bf16 v[70:73], v[146:149], v[182:185], v[70:73]
	v_mfma_f32_16x16x32_bf16 v[66:69], v[154:157], v[182:185], v[66:69]
	v_mfma_f32_16x16x32_bf16 v[94:97], v[150:153], v[170:173], v[94:97]
	v_mfma_f32_16x16x32_bf16 v[90:93], v[158:161], v[170:173], v[90:93]
	v_mfma_f32_16x16x32_bf16 v[86:89], v[150:153], v[174:177], v[86:89]
	v_mfma_f32_16x16x32_bf16 v[82:85], v[158:161], v[174:177], v[82:85]
	v_mfma_f32_16x16x32_bf16 v[78:81], v[150:153], v[186:189], v[78:81]
	v_mfma_f32_16x16x32_bf16 v[74:77], v[158:161], v[186:189], v[74:77]
	v_mfma_f32_16x16x32_bf16 v[70:73], v[150:153], v[190:193], v[70:73]
	v_mfma_f32_16x16x32_bf16 v[66:69], v[158:161], v[190:193], v[66:69]
	s_setprio 0
	s_barrier
	s_cmp_eq_u32 s82, 0
	s_cselect_b64 s[82:83], -1, 0
	v_cndmask_b32_e64 v233, v200, 0, s[82:83]
	s_mov_b32 m0, s25
	v_sub_u32_e32 v233, v201, v233
	v_cndmask_b32_e64 v234, v203, 0, s[82:83]
	ds_read_b128 v[162:165], v219 offset:16384
	ds_read_b128 v[166:169], v219 offset:18432
	ds_read_b128 v[170:173], v220 offset:16384
	ds_read_b128 v[174:177], v220 offset:18432
	ds_read_b128 v[178:181], v219 offset:20480
	ds_read_b128 v[182:185], v219 offset:22528
	ds_read_b128 v[186:189], v220 offset:20480
	ds_read_b128 v[190:193], v220 offset:22528
	buffer_load_dwordx4 v233, s[4:7], s81 offen lds
	v_sub_u32_e32 v234, v204, v234
	s_mov_b32 m0, s26
	s_add_i32 s85, s81, s80
	buffer_load_dwordx4 v234, s[4:7], s81 offen lds
	s_mov_b32 m0, s27
	v_cndmask_b32_e64 v235, v205, 0, s[82:83]
	buffer_load_dwordx4 v233, s[4:7], s85 offen lds
	s_mov_b32 m0, s28
	v_sub_u32_e32 v235, v1, v235
	buffer_load_dwordx4 v234, s[4:7], s85 offen lds
	s_mov_b32 m0, s24
	v_cndmask_b32_e64 v236, v206, 0, s[82:83]
	buffer_load_dwordx4 v235, s[4:7], s84 offen lds
	v_sub_u32_e32 v236, v202, v236
	s_mov_b32 m0, s29
	s_nop 0
	buffer_load_dwordx4 v236, s[4:7], s84 offen lds
	s_waitcnt vmcnt(8)
	s_waitcnt lgkmcnt(0)
	s_barrier
	s_setprio 1
	s_waitcnt lgkmcnt(7)
	s_nop 0
	v_mfma_f32_16x16x32_bf16 v[62:65], v[130:133], v[162:165], v[62:65]
	v_mfma_f32_16x16x32_bf16 v[58:61], v[138:141], v[162:165], v[58:61]
	s_waitcnt lgkmcnt(6)
	s_nop 0
	v_mfma_f32_16x16x32_bf16 v[54:57], v[130:133], v[166:169], v[54:57]
	v_mfma_f32_16x16x32_bf16 v[50:53], v[138:141], v[166:169], v[50:53]
	s_waitcnt lgkmcnt(3)
	s_nop 0
	v_mfma_f32_16x16x32_bf16 v[46:49], v[130:133], v[178:181], v[46:49]
	v_mfma_f32_16x16x32_bf16 v[42:45], v[138:141], v[178:181], v[42:45]
	s_waitcnt lgkmcnt(2)
	s_nop 0
	v_mfma_f32_16x16x32_bf16 v[38:41], v[130:133], v[182:185], v[38:41]
	v_mfma_f32_16x16x32_bf16 v[34:37], v[138:141], v[182:185], v[34:37]
	v_mfma_f32_16x16x32_bf16 v[62:65], v[134:137], v[170:173], v[62:65]
	v_mfma_f32_16x16x32_bf16 v[58:61], v[142:145], v[170:173], v[58:61]
	v_mfma_f32_16x16x32_bf16 v[54:57], v[134:137], v[174:177], v[54:57]
	v_mfma_f32_16x16x32_bf16 v[50:53], v[142:145], v[174:177], v[50:53]
	s_waitcnt lgkmcnt(1)
	s_nop 0
	v_mfma_f32_16x16x32_bf16 v[46:49], v[134:137], v[186:189], v[46:49]
	v_mfma_f32_16x16x32_bf16 v[42:45], v[142:145], v[186:189], v[42:45]
	s_waitcnt lgkmcnt(0)
	s_nop 0
	v_mfma_f32_16x16x32_bf16 v[38:41], v[134:137], v[190:193], v[38:41]
	v_mfma_f32_16x16x32_bf16 v[34:37], v[142:145], v[190:193], v[34:37]
	s_setprio 0
	s_setprio 1
	v_mfma_f32_16x16x32_bf16 v[30:33], v[146:149], v[162:165], v[30:33]
	v_mfma_f32_16x16x32_bf16 v[26:29], v[154:157], v[162:165], v[26:29]
	v_mfma_f32_16x16x32_bf16 v[22:25], v[146:149], v[166:169], v[22:25]
	v_mfma_f32_16x16x32_bf16 v[18:21], v[154:157], v[166:169], v[18:21]
	v_mfma_f32_16x16x32_bf16 v[14:17], v[146:149], v[178:181], v[14:17]
	v_mfma_f32_16x16x32_bf16 v[10:13], v[154:157], v[178:181], v[10:13]
	v_mfma_f32_16x16x32_bf16 v[6:9], v[146:149], v[182:185], v[6:9]
	v_mfma_f32_16x16x32_bf16 v[2:5], v[154:157], v[182:185], v[2:5]
	v_mfma_f32_16x16x32_bf16 v[30:33], v[150:153], v[170:173], v[30:33]
	v_mfma_f32_16x16x32_bf16 v[26:29], v[158:161], v[170:173], v[26:29]
	v_mfma_f32_16x16x32_bf16 v[22:25], v[150:153], v[174:177], v[22:25]
	v_mfma_f32_16x16x32_bf16 v[18:21], v[158:161], v[174:177], v[18:21]
	v_mfma_f32_16x16x32_bf16 v[14:17], v[150:153], v[186:189], v[14:17]
	v_mfma_f32_16x16x32_bf16 v[10:13], v[158:161], v[186:189], v[10:13]
	v_mfma_f32_16x16x32_bf16 v[6:9], v[150:153], v[190:193], v[6:9]
	v_mfma_f32_16x16x32_bf16 v[2:5], v[158:161], v[190:193], v[2:5]
	s_setprio 0
	s_barrier
	ds_read_b128 v[130:133], v223
	ds_read_b128 v[134:137], v224
	ds_read_b128 v[138:141], v225
	ds_read_b128 v[142:145], v227
	ds_read_b128 v[146:149], v228
	ds_read_b128 v[150:153], v229
	ds_read_b128 v[154:157], v230
	ds_read_b128 v[158:161], v231
	s_add_i32 s84, s84, s80
	s_mov_b32 m0, s30
	ds_read_b128 v[162:165], v219 offset:32768
	ds_read_b128 v[166:169], v219 offset:34816
	ds_read_b128 v[170:173], v220 offset:32768
	ds_read_b128 v[174:177], v220 offset:34816
	ds_read_b128 v[178:181], v219 offset:36864
	ds_read_b128 v[182:185], v219 offset:38912
	ds_read_b128 v[186:189], v220 offset:36864
	ds_read_b128 v[190:193], v220 offset:38912
	buffer_load_dwordx4 v235, s[4:7], s84 offen lds
	s_mov_b32 m0, s31
	s_nop 0
	buffer_load_dwordx4 v236, s[4:7], s84 offen lds
	s_waitcnt vmcnt(8)
	s_waitcnt lgkmcnt(0)
	s_barrier
	s_setprio 1
	s_waitcnt lgkmcnt(7)
	s_nop 0
	v_mfma_f32_16x16x32_bf16 v[126:129], v[130:133], v[162:165], v[126:129]
	v_mfma_f32_16x16x32_bf16 v[122:125], v[138:141], v[162:165], v[122:125]
	s_waitcnt lgkmcnt(6)
	s_nop 0
	v_mfma_f32_16x16x32_bf16 v[118:121], v[130:133], v[166:169], v[118:121]
	v_mfma_f32_16x16x32_bf16 v[114:117], v[138:141], v[166:169], v[114:117]
	s_waitcnt lgkmcnt(3)
	s_nop 0
	v_mfma_f32_16x16x32_bf16 v[110:113], v[130:133], v[178:181], v[110:113]
	v_mfma_f32_16x16x32_bf16 v[106:109], v[138:141], v[178:181], v[106:109]
	s_waitcnt lgkmcnt(2)
	s_nop 0
	v_mfma_f32_16x16x32_bf16 v[102:105], v[130:133], v[182:185], v[102:105]
	v_mfma_f32_16x16x32_bf16 v[98:101], v[138:141], v[182:185], v[98:101]
	v_mfma_f32_16x16x32_bf16 v[126:129], v[134:137], v[170:173], v[126:129]
	v_mfma_f32_16x16x32_bf16 v[122:125], v[142:145], v[170:173], v[122:125]
	v_mfma_f32_16x16x32_bf16 v[118:121], v[134:137], v[174:177], v[118:121]
	v_mfma_f32_16x16x32_bf16 v[114:117], v[142:145], v[174:177], v[114:117]
	s_waitcnt lgkmcnt(1)
	s_nop 0
	v_mfma_f32_16x16x32_bf16 v[110:113], v[134:137], v[186:189], v[110:113]
	v_mfma_f32_16x16x32_bf16 v[106:109], v[142:145], v[186:189], v[106:109]
	s_waitcnt lgkmcnt(0)
	s_nop 0
	v_mfma_f32_16x16x32_bf16 v[102:105], v[134:137], v[190:193], v[102:105]
	v_mfma_f32_16x16x32_bf16 v[98:101], v[142:145], v[190:193], v[98:101]
	s_setprio 0
	s_setprio 1
	v_mfma_f32_16x16x32_bf16 v[94:97], v[146:149], v[162:165], v[94:97]
	v_mfma_f32_16x16x32_bf16 v[90:93], v[154:157], v[162:165], v[90:93]
	v_mfma_f32_16x16x32_bf16 v[86:89], v[146:149], v[166:169], v[86:89]
	v_mfma_f32_16x16x32_bf16 v[82:85], v[154:157], v[166:169], v[82:85]
	v_mfma_f32_16x16x32_bf16 v[78:81], v[146:149], v[178:181], v[78:81]
	v_mfma_f32_16x16x32_bf16 v[74:77], v[154:157], v[178:181], v[74:77]
	v_mfma_f32_16x16x32_bf16 v[70:73], v[146:149], v[182:185], v[70:73]
	v_mfma_f32_16x16x32_bf16 v[66:69], v[154:157], v[182:185], v[66:69]
	v_mfma_f32_16x16x32_bf16 v[94:97], v[150:153], v[170:173], v[94:97]
	v_mfma_f32_16x16x32_bf16 v[90:93], v[158:161], v[170:173], v[90:93]
	v_mfma_f32_16x16x32_bf16 v[86:89], v[150:153], v[174:177], v[86:89]
	v_mfma_f32_16x16x32_bf16 v[82:85], v[158:161], v[174:177], v[82:85]
	v_mfma_f32_16x16x32_bf16 v[78:81], v[150:153], v[186:189], v[78:81]
	v_mfma_f32_16x16x32_bf16 v[74:77], v[158:161], v[186:189], v[74:77]
	v_mfma_f32_16x16x32_bf16 v[70:73], v[150:153], v[190:193], v[70:73]
	v_mfma_f32_16x16x32_bf16 v[66:69], v[158:161], v[190:193], v[66:69]
	s_setprio 0
	s_barrier
	s_mov_b32 m0, s36
	s_addk_i32 s81, 0x80
	ds_read_b128 v[162:165], v219 offset:49152
	ds_read_b128 v[166:169], v219 offset:51200
	ds_read_b128 v[170:173], v220 offset:49152
	ds_read_b128 v[174:177], v220 offset:51200
	ds_read_b128 v[178:181], v219 offset:53248
	ds_read_b128 v[182:185], v219 offset:55296
	ds_read_b128 v[186:189], v220 offset:53248
	ds_read_b128 v[190:193], v220 offset:55296
	buffer_load_dwordx4 v233, s[4:7], s81 offen lds
	s_mov_b32 m0, s37
	s_nop 0
	buffer_load_dwordx4 v234, s[4:7], s81 offen lds
	s_add_i32 s81, s81, s80
	s_mov_b32 m0, s40
	s_nop 0
	buffer_load_dwordx4 v233, s[4:7], s81 offen lds
	s_mov_b32 m0, s41
	s_nop 0
	buffer_load_dwordx4 v234, s[4:7], s81 offen lds
	s_mov_b32 m0, s38
	s_nop 0
	buffer_load_dwordx4 v235, s[4:7], s79 offen lds
	s_mov_b32 m0, s39
	s_nop 0
	buffer_load_dwordx4 v236, s[4:7], s79 offen lds
	s_waitcnt vmcnt(8)
	s_waitcnt lgkmcnt(0)
	s_barrier
	s_setprio 1
	s_waitcnt lgkmcnt(7)
	v_mfma_f32_16x16x32_bf16 v[62:65], v[130:133], v[162:165], v[62:65]
	v_mfma_f32_16x16x32_bf16 v[58:61], v[138:141], v[162:165], v[58:61]
	s_waitcnt lgkmcnt(6)
	s_nop 0
	v_mfma_f32_16x16x32_bf16 v[54:57], v[130:133], v[166:169], v[54:57]
	v_mfma_f32_16x16x32_bf16 v[50:53], v[138:141], v[166:169], v[50:53]
	s_waitcnt lgkmcnt(3)
	s_nop 0
	v_mfma_f32_16x16x32_bf16 v[46:49], v[130:133], v[178:181], v[46:49]
	v_mfma_f32_16x16x32_bf16 v[42:45], v[138:141], v[178:181], v[42:45]
	s_waitcnt lgkmcnt(2)
	s_nop 0
	v_mfma_f32_16x16x32_bf16 v[38:41], v[130:133], v[182:185], v[38:41]
	v_mfma_f32_16x16x32_bf16 v[34:37], v[138:141], v[182:185], v[34:37]
	v_mfma_f32_16x16x32_bf16 v[62:65], v[134:137], v[170:173], v[62:65]
	v_mfma_f32_16x16x32_bf16 v[58:61], v[142:145], v[170:173], v[58:61]
	v_mfma_f32_16x16x32_bf16 v[54:57], v[134:137], v[174:177], v[54:57]
	v_mfma_f32_16x16x32_bf16 v[50:53], v[142:145], v[174:177], v[50:53]
	s_waitcnt lgkmcnt(1)
	s_nop 0
	v_mfma_f32_16x16x32_bf16 v[46:49], v[134:137], v[186:189], v[46:49]
	v_mfma_f32_16x16x32_bf16 v[42:45], v[142:145], v[186:189], v[42:45]
	s_waitcnt lgkmcnt(0)
	s_nop 0
	v_mfma_f32_16x16x32_bf16 v[38:41], v[134:137], v[190:193], v[38:41]
	v_mfma_f32_16x16x32_bf16 v[34:37], v[142:145], v[190:193], v[34:37]
	s_setprio 0
	s_setprio 1
	v_mfma_f32_16x16x32_bf16 v[30:33], v[146:149], v[162:165], v[30:33]
	v_mfma_f32_16x16x32_bf16 v[26:29], v[154:157], v[162:165], v[26:29]
	v_mfma_f32_16x16x32_bf16 v[22:25], v[146:149], v[166:169], v[22:25]
	v_mfma_f32_16x16x32_bf16 v[18:21], v[154:157], v[166:169], v[18:21]
	v_mfma_f32_16x16x32_bf16 v[14:17], v[146:149], v[178:181], v[14:17]
	v_mfma_f32_16x16x32_bf16 v[10:13], v[154:157], v[178:181], v[10:13]
	v_mfma_f32_16x16x32_bf16 v[6:9], v[146:149], v[182:185], v[6:9]
	v_mfma_f32_16x16x32_bf16 v[2:5], v[154:157], v[182:185], v[2:5]
	v_mfma_f32_16x16x32_bf16 v[30:33], v[150:153], v[170:173], v[30:33]
	v_mfma_f32_16x16x32_bf16 v[26:29], v[158:161], v[170:173], v[26:29]
	v_mfma_f32_16x16x32_bf16 v[22:25], v[150:153], v[174:177], v[22:25]
	v_mfma_f32_16x16x32_bf16 v[18:21], v[158:161], v[174:177], v[18:21]
	v_mfma_f32_16x16x32_bf16 v[14:17], v[150:153], v[186:189], v[14:17]
	v_mfma_f32_16x16x32_bf16 v[10:13], v[158:161], v[186:189], v[10:13]
	v_mfma_f32_16x16x32_bf16 v[6:9], v[150:153], v[190:193], v[6:9]
	v_mfma_f32_16x16x32_bf16 v[2:5], v[158:161], v[190:193], v[2:5]
	s_setprio 0
	s_barrier
	s_add_i32 s4, s78, 2
	s_addk_i32 s62, 0x100
	s_addk_i32 s61, 0x100
	s_cmp_ge_u32 s78, s63
	s_mov_b32 s78, s4
	s_cbranch_scc0 .LBB0_546
	s_and_b64 vcc, exec, s[12:13]
	s_cbranch_vccz .LBB0_549
	s_barrier

.LBB0_822:
	s_waitcnt lgkmcnt(0)
	s_add_i32 s2, s42, 0x100
	s_add_i32 s3, s34, 0x100
	s_barrier
	s_setprio 1
	s_waitcnt lgkmcnt(7)
	v_mfma_f32_16x16x32_bf16 v[74:77], v[190:193], v[218:221], 0
	v_mfma_f32_16x16x32_bf16 v[70:73], v[182:185], v[218:221], 0
	s_waitcnt lgkmcnt(6)
	s_nop 0
	v_mfma_f32_16x16x32_bf16 v[66:69], v[190:193], v[210:213], 0
	v_mfma_f32_16x16x32_bf16 v[82:85], v[182:185], v[210:213], 0
	s_waitcnt lgkmcnt(3)
	s_nop 0
	v_mfma_f32_16x16x32_bf16 v[78:81], v[190:193], v[202:205], 0
	v_mfma_f32_16x16x32_bf16 v[90:93], v[182:185], v[202:205], 0
	s_waitcnt lgkmcnt(2)
	s_nop 0
	v_mfma_f32_16x16x32_bf16 v[86:89], v[190:193], v[194:197], 0
	v_mfma_f32_16x16x32_bf16 v[102:105], v[182:185], v[194:197], 0
	v_mfma_f32_16x16x32_bf16 v[74:77], v[186:189], v[222:225], v[74:77]
	v_mfma_f32_16x16x32_bf16 v[70:73], v[178:181], v[222:225], v[70:73]
	v_mfma_f32_16x16x32_bf16 v[66:69], v[186:189], v[214:217], v[66:69]
	v_mfma_f32_16x16x32_bf16 v[82:85], v[178:181], v[214:217], v[82:85]
	s_waitcnt lgkmcnt(1)
	s_nop 0
	v_mfma_f32_16x16x32_bf16 v[78:81], v[186:189], v[206:209], v[78:81]
	v_mfma_f32_16x16x32_bf16 v[90:93], v[178:181], v[206:209], v[90:93]
	s_waitcnt lgkmcnt(0)
	s_nop 0
	v_mfma_f32_16x16x32_bf16 v[86:89], v[186:189], v[198:201], v[86:89]
	v_mfma_f32_16x16x32_bf16 v[102:105], v[178:181], v[198:201], v[102:105]
	s_setprio 0
	s_setprio 1
	v_mfma_f32_16x16x32_bf16 v[98:101], v[174:177], v[218:221], 0
	v_mfma_f32_16x16x32_bf16 v[94:97], v[142:145], v[218:221], 0
	v_mfma_f32_16x16x32_bf16 v[106:109], v[174:177], v[210:213], 0
	v_mfma_f32_16x16x32_bf16 v[110:113], v[142:145], v[210:213], 0
	v_mfma_f32_16x16x32_bf16 v[114:117], v[174:177], v[202:205], 0
	v_mfma_f32_16x16x32_bf16 v[118:121], v[142:145], v[202:205], 0
	v_mfma_f32_16x16x32_bf16 v[122:125], v[174:177], v[194:197], 0
	v_mfma_f32_16x16x32_bf16 v[126:129], v[142:145], v[194:197], 0
	s_nop 0
	s_nop 0
	v_mfma_f32_16x16x32_bf16 v[98:101], v[170:173], v[222:225], v[98:101]
	v_mfma_f32_16x16x32_bf16 v[94:97], v[134:137], v[222:225], v[94:97]
	v_mfma_f32_16x16x32_bf16 v[106:109], v[170:173], v[214:217], v[106:109]
	v_mfma_f32_16x16x32_bf16 v[110:113], v[134:137], v[214:217], v[110:113]
	v_mfma_f32_16x16x32_bf16 v[114:117], v[170:173], v[206:209], v[114:117]
	v_mfma_f32_16x16x32_bf16 v[118:121], v[134:137], v[206:209], v[118:121]
	v_mfma_f32_16x16x32_bf16 v[122:125], v[170:173], v[198:201], v[122:125]
	v_mfma_f32_16x16x32_bf16 v[126:129], v[134:137], v[198:201], v[126:129]
	s_setprio 0
	s_barrier
	s_mov_b32 m0, s29
	ds_read_b128 v[202:205], v248 offset:16384
	ds_read_b128 v[194:197], v248 offset:18432
	ds_read_b128 v[206:209], v249 offset:16384
	ds_read_b128 v[198:201], v249 offset:18432
	ds_read_b128 v[154:157], v248 offset:20480
	ds_read_b128 v[146:149], v248 offset:22528
	ds_read_b128 v[158:161], v249 offset:20480
	ds_read_b128 v[150:153], v249 offset:22528
	buffer_load_dwordx4 v233, s[12:15], s3 offen lds
	s_mov_b32 m0, s30
	s_and_b64 vcc, exec, s[0:1]
	buffer_load_dwordx4 v235, s[12:15], s3 offen lds
	s_add_i32 s3, s34, 0x40100
	s_mov_b32 m0, s31
	s_nop 0
	buffer_load_dwordx4 v233, s[12:15], s3 offen lds
	s_mov_b32 m0, s35
	s_nop 0
	buffer_load_dwordx4 v235, s[12:15], s3 offen lds
	s_mov_b32 m0, s28
	s_nop 0
	buffer_load_dwordx4 v1, s[12:15], s2 offen lds
	s_mov_b32 m0, s38
	s_nop 0
	buffer_load_dwordx4 v234, s[12:15], s2 offen lds
	s_mov_b64 s[2:3], -1
	s_cbranch_vccz .LBB0_824
	s_waitcnt vmcnt(8)
	s_mov_b64 s[2:3], 0

.LBB0_826:
	s_waitcnt lgkmcnt(0)
	s_barrier
	s_setprio 1
	s_waitcnt lgkmcnt(7)
	s_nop 0
	v_mfma_f32_16x16x32_bf16 v[10:13], v[190:193], v[202:205], 0
	v_mfma_f32_16x16x32_bf16 v[6:9], v[182:185], v[202:205], 0
	s_waitcnt lgkmcnt(6)
	s_nop 0
	v_mfma_f32_16x16x32_bf16 v[2:5], v[190:193], v[194:197], 0
	v_mfma_f32_16x16x32_bf16 v[18:21], v[182:185], v[194:197], 0
	s_waitcnt lgkmcnt(3)
	s_nop 0
	v_mfma_f32_16x16x32_bf16 v[14:17], v[190:193], v[154:157], 0
	v_mfma_f32_16x16x32_bf16 v[26:29], v[182:185], v[154:157], 0
	s_waitcnt lgkmcnt(2)
	s_nop 0
	v_mfma_f32_16x16x32_bf16 v[22:25], v[190:193], v[146:149], 0
	v_mfma_f32_16x16x32_bf16 v[38:41], v[182:185], v[146:149], 0
	v_mfma_f32_16x16x32_bf16 v[10:13], v[186:189], v[206:209], v[10:13]
	v_mfma_f32_16x16x32_bf16 v[6:9], v[178:181], v[206:209], v[6:9]
	v_mfma_f32_16x16x32_bf16 v[2:5], v[186:189], v[198:201], v[2:5]
	v_mfma_f32_16x16x32_bf16 v[18:21], v[178:181], v[198:201], v[18:21]
	s_waitcnt lgkmcnt(1)
	s_nop 0
	v_mfma_f32_16x16x32_bf16 v[14:17], v[186:189], v[158:161], v[14:17]
	v_mfma_f32_16x16x32_bf16 v[26:29], v[178:181], v[158:161], v[26:29]
	s_waitcnt lgkmcnt(0)
	s_nop 0
	v_mfma_f32_16x16x32_bf16 v[22:25], v[186:189], v[150:153], v[22:25]
	v_mfma_f32_16x16x32_bf16 v[38:41], v[178:181], v[150:153], v[38:41]
	s_setprio 0
	s_setprio 1
	v_mfma_f32_16x16x32_bf16 v[34:37], v[174:177], v[202:205], 0
	v_mfma_f32_16x16x32_bf16 v[30:33], v[142:145], v[202:205], 0
	v_mfma_f32_16x16x32_bf16 v[42:45], v[174:177], v[194:197], 0
	v_mfma_f32_16x16x32_bf16 v[46:49], v[142:145], v[194:197], 0
	v_mfma_f32_16x16x32_bf16 v[50:53], v[174:177], v[154:157], 0
	v_mfma_f32_16x16x32_bf16 v[54:57], v[142:145], v[154:157], 0
	v_mfma_f32_16x16x32_bf16 v[58:61], v[174:177], v[146:149], 0
	v_mfma_f32_16x16x32_bf16 v[62:65], v[142:145], v[146:149], 0
	s_nop 0
	s_nop 0
	v_mfma_f32_16x16x32_bf16 v[34:37], v[170:173], v[206:209], v[34:37]
	v_mfma_f32_16x16x32_bf16 v[30:33], v[134:137], v[206:209], v[30:33]
	v_mfma_f32_16x16x32_bf16 v[42:45], v[170:173], v[198:201], v[42:45]
	v_mfma_f32_16x16x32_bf16 v[46:49], v[134:137], v[198:201], v[46:49]
	v_mfma_f32_16x16x32_bf16 v[50:53], v[170:173], v[158:161], v[50:53]
	v_mfma_f32_16x16x32_bf16 v[54:57], v[134:137], v[158:161], v[54:57]
	v_mfma_f32_16x16x32_bf16 v[58:61], v[170:173], v[150:153], v[58:61]
	v_mfma_f32_16x16x32_bf16 v[62:65], v[134:137], v[150:153], v[62:65]
	s_setprio 0
	s_barrier
	v_add_u32_e32 v194, s58, v238
	v_add_u32_e32 v196, s56, v238
	v_add_u32_e32 v198, s59, v238
	v_add_u32_e32 v200, s57, v238
	v_add_u32_e32 v195, s58, v239
	ds_read_b128 v[146:149], v194
	ds_read_b128 v[150:153], v195
	v_add_u32_e32 v197, s56, v239
	ds_read_b128 v[154:157], v196
	ds_read_b128 v[158:161], v197
	v_add_u32_e32 v199, s59, v239
	ds_read_b128 v[130:133], v198
	ds_read_b128 v[134:137], v199
	v_add_u32_e32 v201, s57, v239
	ds_read_b128 v[138:141], v200
	ds_read_b128 v[142:145], v201
	s_mov_b32 m0, s39
	s_add_i32 s2, s42, 0x40100
	s_mov_b32 s8, s70
	ds_read_b128 v[186:189], v248 offset:32768
	ds_read_b128 v[174:177], v248 offset:34816
	ds_read_b128 v[190:193], v249 offset:32768
	ds_read_b128 v[178:181], v249 offset:34816
	ds_read_b128 v[170:173], v248 offset:36864
	ds_read_b128 v[162:165], v248 offset:38912
	ds_read_b128 v[182:185], v249 offset:36864
	ds_read_b128 v[166:169], v249 offset:38912
	buffer_load_dwordx4 v1, s[8:11], s2 offen lds
	s_mov_b32 m0, s41
	s_and_b64 vcc, exec, s[0:1]
	buffer_load_dwordx4 v234, s[8:11], s2 offen lds
	s_mov_b64 s[2:3], -1
	s_cbranch_vccz .LBB0_828
	s_waitcnt vmcnt(8)
	s_mov_b64 s[2:3], 0

.LBB0_830:
	s_waitcnt lgkmcnt(0)
	s_add_i32 s2, s42, 0x180
	s_add_i32 s3, s34, 0x180
	s_barrier
	s_setprio 1
	s_waitcnt lgkmcnt(7)
	s_nop 0
	v_mfma_f32_16x16x32_bf16 v[74:77], v[146:149], v[186:189], v[74:77]
	v_mfma_f32_16x16x32_bf16 v[70:73], v[154:157], v[186:189], v[70:73]
	s_waitcnt lgkmcnt(6)
	s_nop 0
	v_mfma_f32_16x16x32_bf16 v[66:69], v[146:149], v[174:177], v[66:69]
	v_mfma_f32_16x16x32_bf16 v[82:85], v[154:157], v[174:177], v[82:85]
	s_waitcnt lgkmcnt(3)
	s_nop 0
	v_mfma_f32_16x16x32_bf16 v[78:81], v[146:149], v[170:173], v[78:81]
	v_mfma_f32_16x16x32_bf16 v[90:93], v[154:157], v[170:173], v[90:93]
	s_waitcnt lgkmcnt(2)
	s_nop 0
	v_mfma_f32_16x16x32_bf16 v[86:89], v[146:149], v[162:165], v[86:89]
	v_mfma_f32_16x16x32_bf16 v[102:105], v[154:157], v[162:165], v[102:105]
	v_mfma_f32_16x16x32_bf16 v[74:77], v[150:153], v[190:193], v[74:77]
	v_mfma_f32_16x16x32_bf16 v[70:73], v[158:161], v[190:193], v[70:73]
	v_mfma_f32_16x16x32_bf16 v[66:69], v[150:153], v[178:181], v[66:69]
	v_mfma_f32_16x16x32_bf16 v[82:85], v[158:161], v[178:181], v[82:85]
	s_waitcnt lgkmcnt(1)
	s_nop 0
	v_mfma_f32_16x16x32_bf16 v[78:81], v[150:153], v[182:185], v[78:81]
	v_mfma_f32_16x16x32_bf16 v[90:93], v[158:161], v[182:185], v[90:93]
	s_waitcnt lgkmcnt(0)
	s_nop 0
	v_mfma_f32_16x16x32_bf16 v[86:89], v[150:153], v[166:169], v[86:89]
	v_mfma_f32_16x16x32_bf16 v[102:105], v[158:161], v[166:169], v[102:105]
	s_setprio 0
	s_setprio 1
	v_mfma_f32_16x16x32_bf16 v[98:101], v[130:133], v[186:189], v[98:101]
	v_mfma_f32_16x16x32_bf16 v[94:97], v[138:141], v[186:189], v[94:97]
	v_mfma_f32_16x16x32_bf16 v[106:109], v[130:133], v[174:177], v[106:109]
	v_mfma_f32_16x16x32_bf16 v[110:113], v[138:141], v[174:177], v[110:113]
	v_mfma_f32_16x16x32_bf16 v[114:117], v[130:133], v[170:173], v[114:117]
	v_mfma_f32_16x16x32_bf16 v[118:121], v[138:141], v[170:173], v[118:121]
	v_mfma_f32_16x16x32_bf16 v[122:125], v[130:133], v[162:165], v[122:125]
	v_mfma_f32_16x16x32_bf16 v[126:129], v[138:141], v[162:165], v[126:129]
	v_mfma_f32_16x16x32_bf16 v[98:101], v[134:137], v[190:193], v[98:101]
	v_mfma_f32_16x16x32_bf16 v[94:97], v[142:145], v[190:193], v[94:97]
	v_mfma_f32_16x16x32_bf16 v[106:109], v[134:137], v[178:181], v[106:109]
	v_mfma_f32_16x16x32_bf16 v[110:113], v[142:145], v[178:181], v[110:113]
	v_mfma_f32_16x16x32_bf16 v[114:117], v[134:137], v[182:185], v[114:117]
	v_mfma_f32_16x16x32_bf16 v[118:121], v[142:145], v[182:185], v[118:121]
	v_mfma_f32_16x16x32_bf16 v[122:125], v[134:137], v[166:169], v[122:125]
	v_mfma_f32_16x16x32_bf16 v[126:129], v[142:145], v[166:169], v[126:129]
	s_setprio 0
	s_barrier
	s_mov_b32 m0, s44
	s_mov_b32 s8, s70
	ds_read_b128 v[186:189], v248 offset:49152
	ds_read_b128 v[174:177], v248 offset:51200
	ds_read_b128 v[190:193], v249 offset:49152
	ds_read_b128 v[178:181], v249 offset:51200
	ds_read_b128 v[170:173], v248 offset:53248
	ds_read_b128 v[162:165], v248 offset:55296
	ds_read_b128 v[182:185], v249 offset:53248
	ds_read_b128 v[166:169], v249 offset:55296
	buffer_load_dwordx4 v233, s[8:11], s3 offen lds
	s_mov_b32 m0, s45
	s_and_b64 vcc, exec, s[0:1]
	buffer_load_dwordx4 v235, s[8:11], s3 offen lds
	s_add_i32 s3, s34, 0x40180
	s_mov_b32 m0, s48
	s_nop 0
	buffer_load_dwordx4 v233, s[8:11], s3 offen lds
	s_mov_b32 m0, s49
	s_nop 0
	buffer_load_dwordx4 v235, s[8:11], s3 offen lds
	s_mov_b32 m0, s46
	s_nop 0
	buffer_load_dwordx4 v1, s[8:11], s2 offen lds
	s_mov_b32 m0, s47
	s_nop 0
	buffer_load_dwordx4 v234, s[8:11], s2 offen lds
	s_mov_b64 s[2:3], -1
	s_cbranch_vccz .LBB0_832
	s_waitcnt vmcnt(8)
	s_mov_b64 s[2:3], 0

.LBB0_834:
	s_waitcnt lgkmcnt(0)
	s_barrier
	s_setprio 1
	s_waitcnt lgkmcnt(7)
	s_nop 0
	v_mfma_f32_16x16x32_bf16 v[10:13], v[146:149], v[186:189], v[10:13]
	v_mfma_f32_16x16x32_bf16 v[6:9], v[154:157], v[186:189], v[6:9]
	s_waitcnt lgkmcnt(6)
	s_nop 0
	v_mfma_f32_16x16x32_bf16 v[2:5], v[146:149], v[174:177], v[2:5]
	v_mfma_f32_16x16x32_bf16 v[18:21], v[154:157], v[174:177], v[18:21]
	s_waitcnt lgkmcnt(3)
	s_nop 0
	v_mfma_f32_16x16x32_bf16 v[14:17], v[146:149], v[170:173], v[14:17]
	v_mfma_f32_16x16x32_bf16 v[26:29], v[154:157], v[170:173], v[26:29]
	s_waitcnt lgkmcnt(2)
	s_nop 0
	v_mfma_f32_16x16x32_bf16 v[22:25], v[146:149], v[162:165], v[22:25]
	v_mfma_f32_16x16x32_bf16 v[38:41], v[154:157], v[162:165], v[38:41]
	v_mfma_f32_16x16x32_bf16 v[10:13], v[150:153], v[190:193], v[10:13]
	v_mfma_f32_16x16x32_bf16 v[6:9], v[158:161], v[190:193], v[6:9]
	v_mfma_f32_16x16x32_bf16 v[2:5], v[150:153], v[178:181], v[2:5]
	v_mfma_f32_16x16x32_bf16 v[18:21], v[158:161], v[178:181], v[18:21]
	s_waitcnt lgkmcnt(1)
	s_nop 0
	v_mfma_f32_16x16x32_bf16 v[14:17], v[150:153], v[182:185], v[14:17]
	v_mfma_f32_16x16x32_bf16 v[26:29], v[158:161], v[182:185], v[26:29]
	s_waitcnt lgkmcnt(0)
	s_nop 0
	v_mfma_f32_16x16x32_bf16 v[22:25], v[150:153], v[166:169], v[22:25]
	v_mfma_f32_16x16x32_bf16 v[38:41], v[158:161], v[166:169], v[38:41]
	s_setprio 0
	s_setprio 1
	v_mfma_f32_16x16x32_bf16 v[34:37], v[130:133], v[186:189], v[34:37]
	v_mfma_f32_16x16x32_bf16 v[30:33], v[138:141], v[186:189], v[30:33]
	v_mfma_f32_16x16x32_bf16 v[42:45], v[130:133], v[174:177], v[42:45]
	v_mfma_f32_16x16x32_bf16 v[46:49], v[138:141], v[174:177], v[46:49]
	v_mfma_f32_16x16x32_bf16 v[50:53], v[130:133], v[170:173], v[50:53]
	v_mfma_f32_16x16x32_bf16 v[54:57], v[138:141], v[170:173], v[54:57]
	v_mfma_f32_16x16x32_bf16 v[58:61], v[130:133], v[162:165], v[58:61]
	v_mfma_f32_16x16x32_bf16 v[62:65], v[138:141], v[162:165], v[62:65]
	v_mfma_f32_16x16x32_bf16 v[34:37], v[134:137], v[190:193], v[34:37]
	v_mfma_f32_16x16x32_bf16 v[30:33], v[142:145], v[190:193], v[30:33]
	v_mfma_f32_16x16x32_bf16 v[42:45], v[134:137], v[178:181], v[42:45]
	v_mfma_f32_16x16x32_bf16 v[46:49], v[142:145], v[178:181], v[46:49]
	v_mfma_f32_16x16x32_bf16 v[50:53], v[134:137], v[182:185], v[50:53]
	v_mfma_f32_16x16x32_bf16 v[54:57], v[142:145], v[182:185], v[54:57]
	v_mfma_f32_16x16x32_bf16 v[58:61], v[134:137], v[166:169], v[58:61]
	v_mfma_f32_16x16x32_bf16 v[62:65], v[142:145], v[166:169], v[62:65]
	s_setprio 0
	s_barrier
	s_add_i32 s62, s43, 1
	s_mul_i32 s0, s62, s94
	s_mul_hi_i32 s1, s62, s94
	s_add_u32 s0, s0, s95
	s_addc_u32 s1, s1, s40
	v_cmp_gt_i64_e64 s[2:3], s[0:1], v[226:227]
	s_and_b64 vcc, exec, s[2:3]
	s_cbranch_vccnz .LBB0_840
	s_ashr_i32 s4, s0, 31
	s_lshr_b32 s4, s4, 29
	s_add_i32 s8, s0, s4
	s_and_b32 s4, s8, -8
	s_sub_i32 s18, s0, s4
	s_cmp_gt_i32 s18, -1
	s_mov_b64 s[4:5], -1
	s_cbranch_scc0 .LBB0_837
	s_lshl_b32 s19, s18, 7
	s_mov_b64 s[4:5], 0

.LBB0_841:
	ds_read_b128 v[130:133], v240
	ds_read_b128 v[134:137], v241
	ds_read_b128 v[138:141], v242
	ds_read_b128 v[142:145], v243
	ds_read_b128 v[146:149], v244
	ds_read_b128 v[150:153], v245
	ds_read_b128 v[154:157], v246
	ds_read_b128 v[158:161], v247
	s_add_i32 s8, s42, s5
	s_add_i32 s19, s34, s5
	s_add_i32 s18, s8, 0x800
	s_addk_i32 s19, 0x800
	s_cmp_eq_u32 s5, 0
	s_cselect_b32 s20, s0, s18
	s_cselect_b32 s19, s1, s19
	s_add_i32 s18, s20, 0x80
	s_add_i32 s21, s8, 0x40780
	s_mov_b32 s8, s70
	s_mov_b32 m0, s52
	ds_read_b128 v[162:165], v248
	ds_read_b128 v[166:169], v248 offset:2048
	ds_read_b128 v[170:173], v249
	ds_read_b128 v[174:177], v249 offset:2048
	ds_read_b128 v[178:181], v248 offset:4096
	ds_read_b128 v[182:185], v248 offset:6144
	ds_read_b128 v[186:189], v249 offset:4096
	ds_read_b128 v[190:193], v249 offset:6144
	buffer_load_dwordx4 v1, s[8:11], s21 offen lds
	s_mov_b32 m0, s53
	s_nop 0
	buffer_load_dwordx4 v234, s[8:11], s21 offen lds
	s_waitcnt vmcnt(8)
	s_waitcnt lgkmcnt(0)
	s_barrier
	s_setprio 1
	s_waitcnt lgkmcnt(7)
	v_mfma_f32_16x16x32_bf16 v[74:77], v[130:133], v[162:165], v[74:77]
	v_mfma_f32_16x16x32_bf16 v[70:73], v[138:141], v[162:165], v[70:73]
	s_waitcnt lgkmcnt(6)
	s_nop 0
	v_mfma_f32_16x16x32_bf16 v[66:69], v[130:133], v[166:169], v[66:69]
	v_mfma_f32_16x16x32_bf16 v[82:85], v[138:141], v[166:169], v[82:85]
	s_waitcnt lgkmcnt(3)
	s_nop 0
	v_mfma_f32_16x16x32_bf16 v[78:81], v[130:133], v[178:181], v[78:81]
	v_mfma_f32_16x16x32_bf16 v[90:93], v[138:141], v[178:181], v[90:93]
	s_waitcnt lgkmcnt(2)
	s_nop 0
	v_mfma_f32_16x16x32_bf16 v[86:89], v[130:133], v[182:185], v[86:89]
	v_mfma_f32_16x16x32_bf16 v[102:105], v[138:141], v[182:185], v[102:105]
	v_mfma_f32_16x16x32_bf16 v[74:77], v[134:137], v[170:173], v[74:77]
	v_mfma_f32_16x16x32_bf16 v[70:73], v[142:145], v[170:173], v[70:73]
	v_mfma_f32_16x16x32_bf16 v[66:69], v[134:137], v[174:177], v[66:69]
	v_mfma_f32_16x16x32_bf16 v[82:85], v[142:145], v[174:177], v[82:85]
	s_waitcnt lgkmcnt(1)
	s_nop 0
	v_mfma_f32_16x16x32_bf16 v[78:81], v[134:137], v[186:189], v[78:81]
	v_mfma_f32_16x16x32_bf16 v[90:93], v[142:145], v[186:189], v[90:93]
	s_waitcnt lgkmcnt(0)
	s_nop 0
	v_mfma_f32_16x16x32_bf16 v[86:89], v[134:137], v[190:193], v[86:89]
	v_mfma_f32_16x16x32_bf16 v[102:105], v[142:145], v[190:193], v[102:105]
	s_setprio 0
	s_setprio 1
	v_mfma_f32_16x16x32_bf16 v[98:101], v[146:149], v[162:165], v[98:101]
	v_mfma_f32_16x16x32_bf16 v[94:97], v[154:157], v[162:165], v[94:97]
	v_mfma_f32_16x16x32_bf16 v[106:109], v[146:149], v[166:169], v[106:109]
	v_mfma_f32_16x16x32_bf16 v[110:113], v[154:157], v[166:169], v[110:113]
	v_mfma_f32_16x16x32_bf16 v[114:117], v[146:149], v[178:181], v[114:117]
	v_mfma_f32_16x16x32_bf16 v[118:121], v[154:157], v[178:181], v[118:121]
	v_mfma_f32_16x16x32_bf16 v[122:125], v[146:149], v[182:185], v[122:125]
	v_mfma_f32_16x16x32_bf16 v[126:129], v[154:157], v[182:185], v[126:129]
	v_mfma_f32_16x16x32_bf16 v[98:101], v[150:153], v[170:173], v[98:101]
	v_mfma_f32_16x16x32_bf16 v[94:97], v[158:161], v[170:173], v[94:97]
	v_mfma_f32_16x16x32_bf16 v[106:109], v[150:153], v[174:177], v[106:109]
	v_mfma_f32_16x16x32_bf16 v[110:113], v[158:161], v[174:177], v[110:113]
	v_mfma_f32_16x16x32_bf16 v[114:117], v[150:153], v[186:189], v[114:117]
	v_mfma_f32_16x16x32_bf16 v[118:121], v[158:161], v[186:189], v[118:121]
	v_mfma_f32_16x16x32_bf16 v[122:125], v[150:153], v[190:193], v[122:125]
	v_mfma_f32_16x16x32_bf16 v[126:129], v[158:161], v[190:193], v[126:129]
	s_setprio 0
	s_barrier
	s_mov_b32 m0, s29
	ds_read_b128 v[162:165], v248 offset:16384
	ds_read_b128 v[166:169], v248 offset:18432
	ds_read_b128 v[170:173], v249 offset:16384
	ds_read_b128 v[174:177], v249 offset:18432
	ds_read_b128 v[178:181], v248 offset:20480
	ds_read_b128 v[182:185], v248 offset:22528
	ds_read_b128 v[186:189], v249 offset:20480
	ds_read_b128 v[190:193], v249 offset:22528
	buffer_load_dwordx4 v233, s[8:11], s19 offen lds
	s_mov_b32 m0, s30
	s_add_i32 s21, s19, 0x40000
	buffer_load_dwordx4 v235, s[8:11], s19 offen lds
	s_mov_b32 m0, s31
	s_nop 0
	buffer_load_dwordx4 v233, s[8:11], s21 offen lds
	s_mov_b32 m0, s35
	s_nop 0
	buffer_load_dwordx4 v235, s[8:11], s21 offen lds
	s_mov_b32 m0, s28
	s_nop 0
	buffer_load_dwordx4 v1, s[8:11], s20 offen lds
	s_mov_b32 m0, s38
	s_nop 0
	buffer_load_dwordx4 v234, s[8:11], s20 offen lds
	s_waitcnt vmcnt(8)
	s_waitcnt lgkmcnt(0)
	s_barrier
	s_setprio 1
	s_waitcnt lgkmcnt(7)
	s_nop 0
	v_mfma_f32_16x16x32_bf16 v[10:13], v[130:133], v[162:165], v[10:13]
	v_mfma_f32_16x16x32_bf16 v[6:9], v[138:141], v[162:165], v[6:9]
	s_waitcnt lgkmcnt(6)
	s_nop 0
	v_mfma_f32_16x16x32_bf16 v[2:5], v[130:133], v[166:169], v[2:5]
	v_mfma_f32_16x16x32_bf16 v[18:21], v[138:141], v[166:169], v[18:21]
	s_waitcnt lgkmcnt(3)
	s_nop 0
	v_mfma_f32_16x16x32_bf16 v[14:17], v[130:133], v[178:181], v[14:17]
	v_mfma_f32_16x16x32_bf16 v[26:29], v[138:141], v[178:181], v[26:29]
	s_waitcnt lgkmcnt(2)
	s_nop 0
	v_mfma_f32_16x16x32_bf16 v[22:25], v[130:133], v[182:185], v[22:25]
	v_mfma_f32_16x16x32_bf16 v[38:41], v[138:141], v[182:185], v[38:41]
	v_mfma_f32_16x16x32_bf16 v[10:13], v[134:137], v[170:173], v[10:13]
	v_mfma_f32_16x16x32_bf16 v[6:9], v[142:145], v[170:173], v[6:9]
	v_mfma_f32_16x16x32_bf16 v[2:5], v[134:137], v[174:177], v[2:5]
	v_mfma_f32_16x16x32_bf16 v[18:21], v[142:145], v[174:177], v[18:21]
	s_waitcnt lgkmcnt(1)
	s_nop 0
	v_mfma_f32_16x16x32_bf16 v[14:17], v[134:137], v[186:189], v[14:17]
	v_mfma_f32_16x16x32_bf16 v[26:29], v[142:145], v[186:189], v[26:29]
	s_waitcnt lgkmcnt(0)
	s_nop 0
	v_mfma_f32_16x16x32_bf16 v[22:25], v[134:137], v[190:193], v[22:25]
	v_mfma_f32_16x16x32_bf16 v[38:41], v[142:145], v[190:193], v[38:41]
	s_setprio 0
	s_setprio 1
	v_mfma_f32_16x16x32_bf16 v[34:37], v[146:149], v[162:165], v[34:37]
	v_mfma_f32_16x16x32_bf16 v[30:33], v[154:157], v[162:165], v[30:33]
	v_mfma_f32_16x16x32_bf16 v[42:45], v[146:149], v[166:169], v[42:45]
	v_mfma_f32_16x16x32_bf16 v[46:49], v[154:157], v[166:169], v[46:49]
	v_mfma_f32_16x16x32_bf16 v[50:53], v[146:149], v[178:181], v[50:53]
	v_mfma_f32_16x16x32_bf16 v[54:57], v[154:157], v[178:181], v[54:57]
	v_mfma_f32_16x16x32_bf16 v[58:61], v[146:149], v[182:185], v[58:61]
	v_mfma_f32_16x16x32_bf16 v[62:65], v[154:157], v[182:185], v[62:65]
	v_mfma_f32_16x16x32_bf16 v[34:37], v[150:153], v[170:173], v[34:37]
	v_mfma_f32_16x16x32_bf16 v[30:33], v[158:161], v[170:173], v[30:33]
	v_mfma_f32_16x16x32_bf16 v[42:45], v[150:153], v[174:177], v[42:45]
	v_mfma_f32_16x16x32_bf16 v[46:49], v[158:161], v[174:177], v[46:49]
	v_mfma_f32_16x16x32_bf16 v[50:53], v[150:153], v[186:189], v[50:53]
	v_mfma_f32_16x16x32_bf16 v[54:57], v[158:161], v[186:189], v[54:57]
	v_mfma_f32_16x16x32_bf16 v[58:61], v[150:153], v[190:193], v[58:61]
	v_mfma_f32_16x16x32_bf16 v[62:65], v[158:161], v[190:193], v[62:65]
	s_setprio 0
	s_barrier
	ds_read_b128 v[130:133], v194
	ds_read_b128 v[134:137], v195
	ds_read_b128 v[138:141], v196
	ds_read_b128 v[142:145], v197
	ds_read_b128 v[146:149], v198
	ds_read_b128 v[150:153], v199
	ds_read_b128 v[154:157], v200
	ds_read_b128 v[158:161], v201
	s_add_i32 s20, s20, 0x40000
	s_mov_b32 m0, s39
	ds_read_b128 v[162:165], v248 offset:32768
	ds_read_b128 v[166:169], v248 offset:34816
	ds_read_b128 v[170:173], v249 offset:32768
	ds_read_b128 v[174:177], v249 offset:34816
	ds_read_b128 v[178:181], v248 offset:36864
	ds_read_b128 v[182:185], v248 offset:38912
	ds_read_b128 v[186:189], v249 offset:36864
	ds_read_b128 v[190:193], v249 offset:38912
	buffer_load_dwordx4 v1, s[8:11], s20 offen lds
	s_mov_b32 m0, s41
	s_nop 0
	buffer_load_dwordx4 v234, s[8:11], s20 offen lds
	s_waitcnt vmcnt(8)
	s_waitcnt lgkmcnt(0)
	s_barrier
	s_setprio 1
	s_waitcnt lgkmcnt(7)
	v_mfma_f32_16x16x32_bf16 v[74:77], v[130:133], v[162:165], v[74:77]
	v_mfma_f32_16x16x32_bf16 v[70:73], v[138:141], v[162:165], v[70:73]
	s_waitcnt lgkmcnt(6)
	s_nop 0
	v_mfma_f32_16x16x32_bf16 v[66:69], v[130:133], v[166:169], v[66:69]
	v_mfma_f32_16x16x32_bf16 v[82:85], v[138:141], v[166:169], v[82:85]
	s_waitcnt lgkmcnt(3)
	s_nop 0
	v_mfma_f32_16x16x32_bf16 v[78:81], v[130:133], v[178:181], v[78:81]
	v_mfma_f32_16x16x32_bf16 v[90:93], v[138:141], v[178:181], v[90:93]
	s_waitcnt lgkmcnt(2)
	s_nop 0
	v_mfma_f32_16x16x32_bf16 v[86:89], v[130:133], v[182:185], v[86:89]
	v_mfma_f32_16x16x32_bf16 v[102:105], v[138:141], v[182:185], v[102:105]
	v_mfma_f32_16x16x32_bf16 v[74:77], v[134:137], v[170:173], v[74:77]
	v_mfma_f32_16x16x32_bf16 v[70:73], v[142:145], v[170:173], v[70:73]
	v_mfma_f32_16x16x32_bf16 v[66:69], v[134:137], v[174:177], v[66:69]
	v_mfma_f32_16x16x32_bf16 v[82:85], v[142:145], v[174:177], v[82:85]
	s_waitcnt lgkmcnt(1)
	s_nop 0
	v_mfma_f32_16x16x32_bf16 v[78:81], v[134:137], v[186:189], v[78:81]
	v_mfma_f32_16x16x32_bf16 v[90:93], v[142:145], v[186:189], v[90:93]
	s_waitcnt lgkmcnt(0)
	s_nop 0
	v_mfma_f32_16x16x32_bf16 v[86:89], v[134:137], v[190:193], v[86:89]
	v_mfma_f32_16x16x32_bf16 v[102:105], v[142:145], v[190:193], v[102:105]
	s_setprio 0
	s_setprio 1
	v_mfma_f32_16x16x32_bf16 v[98:101], v[146:149], v[162:165], v[98:101]
	v_mfma_f32_16x16x32_bf16 v[94:97], v[154:157], v[162:165], v[94:97]
	v_mfma_f32_16x16x32_bf16 v[106:109], v[146:149], v[166:169], v[106:109]
	v_mfma_f32_16x16x32_bf16 v[110:113], v[154:157], v[166:169], v[110:113]
	v_mfma_f32_16x16x32_bf16 v[114:117], v[146:149], v[178:181], v[114:117]
	v_mfma_f32_16x16x32_bf16 v[118:121], v[154:157], v[178:181], v[118:121]
	v_mfma_f32_16x16x32_bf16 v[122:125], v[146:149], v[182:185], v[122:125]
	v_mfma_f32_16x16x32_bf16 v[126:129], v[154:157], v[182:185], v[126:129]
	v_mfma_f32_16x16x32_bf16 v[98:101], v[150:153], v[170:173], v[98:101]
	v_mfma_f32_16x16x32_bf16 v[94:97], v[158:161], v[170:173], v[94:97]
	v_mfma_f32_16x16x32_bf16 v[106:109], v[150:153], v[174:177], v[106:109]
	v_mfma_f32_16x16x32_bf16 v[110:113], v[158:161], v[174:177], v[110:113]
	v_mfma_f32_16x16x32_bf16 v[114:117], v[150:153], v[186:189], v[114:117]
	v_mfma_f32_16x16x32_bf16 v[118:121], v[158:161], v[186:189], v[118:121]
	v_mfma_f32_16x16x32_bf16 v[122:125], v[150:153], v[190:193], v[122:125]
	v_mfma_f32_16x16x32_bf16 v[126:129], v[158:161], v[190:193], v[126:129]
	s_setprio 0
	s_barrier
	s_mov_b32 m0, s44
	s_add_i32 s20, s19, 0x80
	ds_read_b128 v[162:165], v248 offset:49152
	ds_read_b128 v[166:169], v248 offset:51200
	ds_read_b128 v[170:173], v249 offset:49152
	ds_read_b128 v[174:177], v249 offset:51200
	ds_read_b128 v[178:181], v248 offset:53248
	ds_read_b128 v[182:185], v248 offset:55296
	ds_read_b128 v[186:189], v249 offset:53248
	ds_read_b128 v[190:193], v249 offset:55296
	buffer_load_dwordx4 v233, s[8:11], s20 offen lds
	s_mov_b32 m0, s45
	s_add_i32 s19, s19, 0x40080
	buffer_load_dwordx4 v235, s[8:11], s20 offen lds
	s_mov_b32 m0, s48
	s_nop 0
	buffer_load_dwordx4 v233, s[8:11], s19 offen lds
	s_mov_b32 m0, s49
	s_nop 0
	buffer_load_dwordx4 v235, s[8:11], s19 offen lds
	s_mov_b32 m0, s46
	s_nop 0
	buffer_load_dwordx4 v1, s[8:11], s18 offen lds
	s_mov_b32 m0, s47
	s_nop 0
	buffer_load_dwordx4 v234, s[8:11], s18 offen lds
	s_waitcnt vmcnt(8)
	s_waitcnt lgkmcnt(0)
	s_barrier
	s_setprio 1
	s_waitcnt lgkmcnt(7)
	s_nop 0
	v_mfma_f32_16x16x32_bf16 v[10:13], v[130:133], v[162:165], v[10:13]
	v_mfma_f32_16x16x32_bf16 v[6:9], v[138:141], v[162:165], v[6:9]
	s_waitcnt lgkmcnt(6)
	s_nop 0
	v_mfma_f32_16x16x32_bf16 v[2:5], v[130:133], v[166:169], v[2:5]
	v_mfma_f32_16x16x32_bf16 v[18:21], v[138:141], v[166:169], v[18:21]
	s_waitcnt lgkmcnt(3)
	s_nop 0
	v_mfma_f32_16x16x32_bf16 v[14:17], v[130:133], v[178:181], v[14:17]
	v_mfma_f32_16x16x32_bf16 v[26:29], v[138:141], v[178:181], v[26:29]
	s_waitcnt lgkmcnt(2)
	s_nop 0
	v_mfma_f32_16x16x32_bf16 v[22:25], v[130:133], v[182:185], v[22:25]
	v_mfma_f32_16x16x32_bf16 v[38:41], v[138:141], v[182:185], v[38:41]
	v_mfma_f32_16x16x32_bf16 v[10:13], v[134:137], v[170:173], v[10:13]
	v_mfma_f32_16x16x32_bf16 v[6:9], v[142:145], v[170:173], v[6:9]
	v_mfma_f32_16x16x32_bf16 v[2:5], v[134:137], v[174:177], v[2:5]
	v_mfma_f32_16x16x32_bf16 v[18:21], v[142:145], v[174:177], v[18:21]
	s_waitcnt lgkmcnt(1)
	s_nop 0
	v_mfma_f32_16x16x32_bf16 v[14:17], v[134:137], v[186:189], v[14:17]
	v_mfma_f32_16x16x32_bf16 v[26:29], v[142:145], v[186:189], v[26:29]
	s_waitcnt lgkmcnt(0)
	s_nop 0
	v_mfma_f32_16x16x32_bf16 v[22:25], v[134:137], v[190:193], v[22:25]
	v_mfma_f32_16x16x32_bf16 v[38:41], v[142:145], v[190:193], v[38:41]
	s_setprio 0
	s_setprio 1
	v_mfma_f32_16x16x32_bf16 v[34:37], v[146:149], v[162:165], v[34:37]
	v_mfma_f32_16x16x32_bf16 v[30:33], v[154:157], v[162:165], v[30:33]
	v_mfma_f32_16x16x32_bf16 v[42:45], v[146:149], v[166:169], v[42:45]
	v_mfma_f32_16x16x32_bf16 v[46:49], v[154:157], v[166:169], v[46:49]
	v_mfma_f32_16x16x32_bf16 v[50:53], v[146:149], v[178:181], v[50:53]
	v_mfma_f32_16x16x32_bf16 v[54:57], v[154:157], v[178:181], v[54:57]
	v_mfma_f32_16x16x32_bf16 v[58:61], v[146:149], v[182:185], v[58:61]
	v_mfma_f32_16x16x32_bf16 v[62:65], v[154:157], v[182:185], v[62:65]
	v_mfma_f32_16x16x32_bf16 v[34:37], v[150:153], v[170:173], v[34:37]
	v_mfma_f32_16x16x32_bf16 v[30:33], v[158:161], v[170:173], v[30:33]
	v_mfma_f32_16x16x32_bf16 v[42:45], v[150:153], v[174:177], v[42:45]
	v_mfma_f32_16x16x32_bf16 v[46:49], v[158:161], v[174:177], v[46:49]
	v_mfma_f32_16x16x32_bf16 v[50:53], v[150:153], v[186:189], v[50:53]
	v_mfma_f32_16x16x32_bf16 v[54:57], v[158:161], v[186:189], v[54:57]
	v_mfma_f32_16x16x32_bf16 v[58:61], v[150:153], v[190:193], v[58:61]
	v_mfma_f32_16x16x32_bf16 v[62:65], v[158:161], v[190:193], v[62:65]
	s_setprio 0
	s_barrier
	s_add_i32 s4, s4, 2
	s_addk_i32 s5, 0x100
	s_cmp_gt_u32 s4, 13
	s_cbranch_scc0 .LBB0_841
	s_and_b64 vcc, exec, s[16:17]
	s_cbranch_vccz .LBB0_844
	s_barrier

.LBB0_1103:
	s_waitcnt lgkmcnt(0)
	s_add_i32 s4, s31, 0x100
	s_add_i32 s5, s26, 0x100
	s_barrier
	s_setprio 1
	s_waitcnt lgkmcnt(7)
	s_nop 0
	v_mfma_f32_16x16x32_bf16 v[126:129], v[190:193], v[218:221], 0
	v_mfma_f32_16x16x32_bf16 v[122:125], v[182:185], v[218:221], 0
	s_waitcnt lgkmcnt(6)
	s_nop 0
	v_mfma_f32_16x16x32_bf16 v[118:121], v[190:193], v[210:213], 0
	v_mfma_f32_16x16x32_bf16 v[114:117], v[182:185], v[210:213], 0
	s_waitcnt lgkmcnt(3)
	s_nop 0
	v_mfma_f32_16x16x32_bf16 v[110:113], v[190:193], v[202:205], 0
	v_mfma_f32_16x16x32_bf16 v[106:109], v[182:185], v[202:205], 0
	s_waitcnt lgkmcnt(2)
	s_nop 0
	v_mfma_f32_16x16x32_bf16 v[102:105], v[190:193], v[194:197], 0
	v_mfma_f32_16x16x32_bf16 v[98:101], v[182:185], v[194:197], 0
	v_mfma_f32_16x16x32_bf16 v[126:129], v[186:189], v[222:225], v[126:129]
	v_mfma_f32_16x16x32_bf16 v[122:125], v[178:181], v[222:225], v[122:125]
	v_mfma_f32_16x16x32_bf16 v[118:121], v[186:189], v[214:217], v[118:121]
	v_mfma_f32_16x16x32_bf16 v[114:117], v[178:181], v[214:217], v[114:117]
	s_waitcnt lgkmcnt(1)
	s_nop 0
	v_mfma_f32_16x16x32_bf16 v[110:113], v[186:189], v[206:209], v[110:113]
	v_mfma_f32_16x16x32_bf16 v[106:109], v[178:181], v[206:209], v[106:109]
	s_waitcnt lgkmcnt(0)
	s_nop 0
	v_mfma_f32_16x16x32_bf16 v[102:105], v[186:189], v[198:201], v[102:105]
	v_mfma_f32_16x16x32_bf16 v[98:101], v[178:181], v[198:201], v[98:101]
	s_setprio 0
	s_setprio 1
	v_mfma_f32_16x16x32_bf16 v[94:97], v[174:177], v[218:221], 0
	v_mfma_f32_16x16x32_bf16 v[90:93], v[166:169], v[218:221], 0
	v_mfma_f32_16x16x32_bf16 v[86:89], v[174:177], v[210:213], 0
	v_mfma_f32_16x16x32_bf16 v[82:85], v[166:169], v[210:213], 0
	v_mfma_f32_16x16x32_bf16 v[78:81], v[174:177], v[202:205], 0
	v_mfma_f32_16x16x32_bf16 v[74:77], v[166:169], v[202:205], 0
	v_mfma_f32_16x16x32_bf16 v[70:73], v[174:177], v[194:197], 0
	v_mfma_f32_16x16x32_bf16 v[66:69], v[166:169], v[194:197], 0
	s_nop 0
	s_nop 0
	v_mfma_f32_16x16x32_bf16 v[94:97], v[170:173], v[222:225], v[94:97]
	v_mfma_f32_16x16x32_bf16 v[90:93], v[162:165], v[222:225], v[90:93]
	v_mfma_f32_16x16x32_bf16 v[86:89], v[170:173], v[214:217], v[86:89]
	v_mfma_f32_16x16x32_bf16 v[82:85], v[162:165], v[214:217], v[82:85]
	v_mfma_f32_16x16x32_bf16 v[78:81], v[170:173], v[206:209], v[78:81]
	v_mfma_f32_16x16x32_bf16 v[74:77], v[162:165], v[206:209], v[74:77]
	v_mfma_f32_16x16x32_bf16 v[70:73], v[170:173], v[198:201], v[70:73]
	v_mfma_f32_16x16x32_bf16 v[66:69], v[162:165], v[198:201], v[66:69]
	s_setprio 0
	s_barrier
	s_mov_b32 m0, s23
	ds_read_b128 v[202:205], v248 offset:16384
	ds_read_b128 v[194:197], v248 offset:18432
	ds_read_b128 v[206:209], v249 offset:16384
	ds_read_b128 v[198:201], v249 offset:18432
	ds_read_b128 v[146:149], v248 offset:20480
	ds_read_b128 v[130:133], v248 offset:22528
	ds_read_b128 v[154:157], v249 offset:20480
	ds_read_b128 v[138:141], v249 offset:22528
	buffer_load_dwordx4 v233, s[12:15], s5 offen lds
	s_mov_b32 m0, s24
	s_and_b64 vcc, exec, s[2:3]
	buffer_load_dwordx4 v235, s[12:15], s5 offen lds
	s_add_i32 s5, s26, 0x40100
	s_mov_b32 m0, s25
	s_nop 0
	buffer_load_dwordx4 v233, s[12:15], s5 offen lds
	s_mov_b32 m0, s27
	s_nop 0
	buffer_load_dwordx4 v235, s[12:15], s5 offen lds
	s_mov_b32 m0, s22
	s_nop 0
	buffer_load_dwordx4 v1, s[12:15], s4 offen lds
	s_mov_b32 m0, s28
	s_nop 0
	buffer_load_dwordx4 v234, s[12:15], s4 offen lds
	s_mov_b64 s[4:5], -1
	s_cbranch_vccz .LBB0_1105
	s_waitcnt vmcnt(8)
	s_mov_b64 s[4:5], 0

.LBB0_1107:
	s_waitcnt lgkmcnt(0)
	s_barrier
	s_setprio 1
	s_waitcnt lgkmcnt(7)
	s_nop 0
	v_mfma_f32_16x16x32_bf16 v[62:65], v[190:193], v[202:205], 0
	v_mfma_f32_16x16x32_bf16 v[58:61], v[182:185], v[202:205], 0
	s_waitcnt lgkmcnt(6)
	s_nop 0
	v_mfma_f32_16x16x32_bf16 v[54:57], v[190:193], v[194:197], 0
	v_mfma_f32_16x16x32_bf16 v[50:53], v[182:185], v[194:197], 0
	s_waitcnt lgkmcnt(3)
	s_nop 0
	v_mfma_f32_16x16x32_bf16 v[46:49], v[190:193], v[146:149], 0
	v_mfma_f32_16x16x32_bf16 v[42:45], v[182:185], v[146:149], 0
	s_waitcnt lgkmcnt(2)
	s_nop 0
	v_mfma_f32_16x16x32_bf16 v[38:41], v[190:193], v[130:133], 0
	v_mfma_f32_16x16x32_bf16 v[34:37], v[182:185], v[130:133], 0
	v_mfma_f32_16x16x32_bf16 v[62:65], v[186:189], v[206:209], v[62:65]
	v_mfma_f32_16x16x32_bf16 v[58:61], v[178:181], v[206:209], v[58:61]
	v_mfma_f32_16x16x32_bf16 v[54:57], v[186:189], v[198:201], v[54:57]
	v_mfma_f32_16x16x32_bf16 v[50:53], v[178:181], v[198:201], v[50:53]
	s_waitcnt lgkmcnt(1)
	s_nop 0
	v_mfma_f32_16x16x32_bf16 v[46:49], v[186:189], v[154:157], v[46:49]
	v_mfma_f32_16x16x32_bf16 v[42:45], v[178:181], v[154:157], v[42:45]
	s_waitcnt lgkmcnt(0)
	s_nop 0
	v_mfma_f32_16x16x32_bf16 v[38:41], v[186:189], v[138:141], v[38:41]
	v_mfma_f32_16x16x32_bf16 v[34:37], v[178:181], v[138:141], v[34:37]
	s_setprio 0
	s_setprio 1
	v_mfma_f32_16x16x32_bf16 v[30:33], v[174:177], v[202:205], 0
	v_mfma_f32_16x16x32_bf16 v[26:29], v[166:169], v[202:205], 0
	v_mfma_f32_16x16x32_bf16 v[22:25], v[174:177], v[194:197], 0
	v_mfma_f32_16x16x32_bf16 v[18:21], v[166:169], v[194:197], 0
	v_mfma_f32_16x16x32_bf16 v[14:17], v[174:177], v[146:149], 0
	v_mfma_f32_16x16x32_bf16 v[10:13], v[166:169], v[146:149], 0
	v_mfma_f32_16x16x32_bf16 v[6:9], v[174:177], v[130:133], 0
	v_mfma_f32_16x16x32_bf16 v[2:5], v[166:169], v[130:133], 0
	s_nop 0
	s_nop 0
	v_mfma_f32_16x16x32_bf16 v[30:33], v[170:173], v[206:209], v[30:33]
	v_mfma_f32_16x16x32_bf16 v[26:29], v[162:165], v[206:209], v[26:29]
	v_mfma_f32_16x16x32_bf16 v[22:25], v[170:173], v[198:201], v[22:25]
	v_mfma_f32_16x16x32_bf16 v[18:21], v[162:165], v[198:201], v[18:21]
	v_mfma_f32_16x16x32_bf16 v[14:17], v[170:173], v[154:157], v[14:17]
	v_mfma_f32_16x16x32_bf16 v[10:13], v[162:165], v[154:157], v[10:13]
	v_mfma_f32_16x16x32_bf16 v[6:9], v[170:173], v[138:141], v[6:9]
	v_mfma_f32_16x16x32_bf16 v[2:5], v[162:165], v[138:141], v[2:5]
	s_setprio 0
	s_barrier
	v_add_u32_e32 v194, s46, v238
	v_add_u32_e32 v196, s47, v238
	v_add_u32_e32 v198, s48, v238
	v_add_u32_e32 v200, s49, v238
	v_add_u32_e32 v195, s46, v239
	ds_read_b128 v[146:149], v194
	ds_read_b128 v[150:153], v195
	v_add_u32_e32 v197, s47, v239
	ds_read_b128 v[154:157], v196
	ds_read_b128 v[158:161], v197
	v_add_u32_e32 v199, s48, v239
	ds_read_b128 v[130:133], v198
	ds_read_b128 v[134:137], v199
	v_add_u32_e32 v201, s49, v239
	ds_read_b128 v[138:141], v200
	ds_read_b128 v[142:145], v201
	s_mov_b32 m0, s29
	s_add_i32 s4, s31, 0x40100
	ds_read_b128 v[186:189], v248 offset:32768
	ds_read_b128 v[174:177], v248 offset:34816
	ds_read_b128 v[190:193], v249 offset:32768
	ds_read_b128 v[178:181], v249 offset:34816
	ds_read_b128 v[170:173], v248 offset:36864
	ds_read_b128 v[162:165], v248 offset:38912
	ds_read_b128 v[182:185], v249 offset:36864
	ds_read_b128 v[166:169], v249 offset:38912
	buffer_load_dwordx4 v1, s[12:15], s4 offen lds
	s_mov_b32 m0, s30
	s_and_b64 vcc, exec, s[2:3]
	buffer_load_dwordx4 v234, s[12:15], s4 offen lds
	s_mov_b64 s[4:5], -1
	s_cbranch_vccz .LBB0_1109
	s_waitcnt vmcnt(8)
	s_mov_b64 s[4:5], 0

.LBB0_1111:
	s_waitcnt lgkmcnt(0)
	s_add_i32 s4, s31, 0x180
	s_add_i32 s5, s26, 0x180
	s_barrier
	s_setprio 1
	s_waitcnt lgkmcnt(7)
	v_mfma_f32_16x16x32_bf16 v[126:129], v[146:149], v[186:189], v[126:129]
	v_mfma_f32_16x16x32_bf16 v[122:125], v[154:157], v[186:189], v[122:125]
	s_waitcnt lgkmcnt(6)
	s_nop 0
	v_mfma_f32_16x16x32_bf16 v[118:121], v[146:149], v[174:177], v[118:121]
	v_mfma_f32_16x16x32_bf16 v[114:117], v[154:157], v[174:177], v[114:117]
	s_waitcnt lgkmcnt(3)
	s_nop 0
	v_mfma_f32_16x16x32_bf16 v[110:113], v[146:149], v[170:173], v[110:113]
	v_mfma_f32_16x16x32_bf16 v[106:109], v[154:157], v[170:173], v[106:109]
	s_waitcnt lgkmcnt(2)
	s_nop 0
	v_mfma_f32_16x16x32_bf16 v[102:105], v[146:149], v[162:165], v[102:105]
	v_mfma_f32_16x16x32_bf16 v[98:101], v[154:157], v[162:165], v[98:101]
	v_mfma_f32_16x16x32_bf16 v[126:129], v[150:153], v[190:193], v[126:129]
	v_mfma_f32_16x16x32_bf16 v[122:125], v[158:161], v[190:193], v[122:125]
	v_mfma_f32_16x16x32_bf16 v[118:121], v[150:153], v[178:181], v[118:121]
	v_mfma_f32_16x16x32_bf16 v[114:117], v[158:161], v[178:181], v[114:117]
	s_waitcnt lgkmcnt(1)
	s_nop 0
	v_mfma_f32_16x16x32_bf16 v[110:113], v[150:153], v[182:185], v[110:113]
	v_mfma_f32_16x16x32_bf16 v[106:109], v[158:161], v[182:185], v[106:109]
	s_waitcnt lgkmcnt(0)
	s_nop 0
	v_mfma_f32_16x16x32_bf16 v[102:105], v[150:153], v[166:169], v[102:105]
	v_mfma_f32_16x16x32_bf16 v[98:101], v[158:161], v[166:169], v[98:101]
	s_setprio 0
	s_setprio 1
	v_mfma_f32_16x16x32_bf16 v[94:97], v[130:133], v[186:189], v[94:97]
	v_mfma_f32_16x16x32_bf16 v[90:93], v[138:141], v[186:189], v[90:93]
	v_mfma_f32_16x16x32_bf16 v[86:89], v[130:133], v[174:177], v[86:89]
	v_mfma_f32_16x16x32_bf16 v[82:85], v[138:141], v[174:177], v[82:85]
	v_mfma_f32_16x16x32_bf16 v[78:81], v[130:133], v[170:173], v[78:81]
	v_mfma_f32_16x16x32_bf16 v[74:77], v[138:141], v[170:173], v[74:77]
	v_mfma_f32_16x16x32_bf16 v[70:73], v[130:133], v[162:165], v[70:73]
	v_mfma_f32_16x16x32_bf16 v[66:69], v[138:141], v[162:165], v[66:69]
	v_mfma_f32_16x16x32_bf16 v[94:97], v[134:137], v[190:193], v[94:97]
	v_mfma_f32_16x16x32_bf16 v[90:93], v[142:145], v[190:193], v[90:93]
	v_mfma_f32_16x16x32_bf16 v[86:89], v[134:137], v[178:181], v[86:89]
	v_mfma_f32_16x16x32_bf16 v[82:85], v[142:145], v[178:181], v[82:85]
	v_mfma_f32_16x16x32_bf16 v[78:81], v[134:137], v[182:185], v[78:81]
	v_mfma_f32_16x16x32_bf16 v[74:77], v[142:145], v[182:185], v[74:77]
	v_mfma_f32_16x16x32_bf16 v[70:73], v[134:137], v[166:169], v[70:73]
	v_mfma_f32_16x16x32_bf16 v[66:69], v[142:145], v[166:169], v[66:69]
	s_setprio 0
	s_barrier
	s_mov_b32 m0, s35
	ds_read_b128 v[186:189], v248 offset:49152
	ds_read_b128 v[174:177], v248 offset:51200
	ds_read_b128 v[190:193], v249 offset:49152
	ds_read_b128 v[178:181], v249 offset:51200
	ds_read_b128 v[170:173], v248 offset:53248
	ds_read_b128 v[162:165], v248 offset:55296
	ds_read_b128 v[182:185], v249 offset:53248
	ds_read_b128 v[166:169], v249 offset:55296
	buffer_load_dwordx4 v233, s[12:15], s5 offen lds
	s_mov_b32 m0, s36
	s_and_b64 vcc, exec, s[2:3]
	buffer_load_dwordx4 v235, s[12:15], s5 offen lds
	s_add_i32 s5, s26, 0x40180
	s_mov_b32 m0, s39
	s_nop 0
	buffer_load_dwordx4 v233, s[12:15], s5 offen lds
	s_mov_b32 m0, s41
	s_nop 0
	buffer_load_dwordx4 v235, s[12:15], s5 offen lds
	s_mov_b32 m0, s37
	s_nop 0
	buffer_load_dwordx4 v1, s[12:15], s4 offen lds
	s_mov_b32 m0, s38
	s_nop 0
	buffer_load_dwordx4 v234, s[12:15], s4 offen lds
	s_mov_b64 s[4:5], -1
	s_cbranch_vccz .LBB0_1113
	s_waitcnt vmcnt(8)
	s_mov_b64 s[4:5], 0

.LBB0_1115:
	s_waitcnt lgkmcnt(0)
	s_barrier
	s_setprio 1
	s_waitcnt lgkmcnt(7)
	v_mfma_f32_16x16x32_bf16 v[62:65], v[146:149], v[186:189], v[62:65]
	v_mfma_f32_16x16x32_bf16 v[58:61], v[154:157], v[186:189], v[58:61]
	s_waitcnt lgkmcnt(6)
	s_nop 0
	v_mfma_f32_16x16x32_bf16 v[54:57], v[146:149], v[174:177], v[54:57]
	v_mfma_f32_16x16x32_bf16 v[50:53], v[154:157], v[174:177], v[50:53]
	s_waitcnt lgkmcnt(3)
	s_nop 0
	v_mfma_f32_16x16x32_bf16 v[46:49], v[146:149], v[170:173], v[46:49]
	v_mfma_f32_16x16x32_bf16 v[42:45], v[154:157], v[170:173], v[42:45]
	s_waitcnt lgkmcnt(2)
	s_nop 0
	v_mfma_f32_16x16x32_bf16 v[38:41], v[146:149], v[162:165], v[38:41]
	v_mfma_f32_16x16x32_bf16 v[34:37], v[154:157], v[162:165], v[34:37]
	v_mfma_f32_16x16x32_bf16 v[62:65], v[150:153], v[190:193], v[62:65]
	v_mfma_f32_16x16x32_bf16 v[58:61], v[158:161], v[190:193], v[58:61]
	v_mfma_f32_16x16x32_bf16 v[54:57], v[150:153], v[178:181], v[54:57]
	v_mfma_f32_16x16x32_bf16 v[50:53], v[158:161], v[178:181], v[50:53]
	s_waitcnt lgkmcnt(1)
	s_nop 0
	v_mfma_f32_16x16x32_bf16 v[46:49], v[150:153], v[182:185], v[46:49]
	v_mfma_f32_16x16x32_bf16 v[42:45], v[158:161], v[182:185], v[42:45]
	s_waitcnt lgkmcnt(0)
	s_nop 0
	v_mfma_f32_16x16x32_bf16 v[38:41], v[150:153], v[166:169], v[38:41]
	v_mfma_f32_16x16x32_bf16 v[34:37], v[158:161], v[166:169], v[34:37]
	s_setprio 0
	s_setprio 1
	v_mfma_f32_16x16x32_bf16 v[30:33], v[130:133], v[186:189], v[30:33]
	v_mfma_f32_16x16x32_bf16 v[26:29], v[138:141], v[186:189], v[26:29]
	v_mfma_f32_16x16x32_bf16 v[22:25], v[130:133], v[174:177], v[22:25]
	v_mfma_f32_16x16x32_bf16 v[18:21], v[138:141], v[174:177], v[18:21]
	v_mfma_f32_16x16x32_bf16 v[14:17], v[130:133], v[170:173], v[14:17]
	v_mfma_f32_16x16x32_bf16 v[10:13], v[138:141], v[170:173], v[10:13]
	v_mfma_f32_16x16x32_bf16 v[6:9], v[130:133], v[162:165], v[6:9]
	v_mfma_f32_16x16x32_bf16 v[2:5], v[138:141], v[162:165], v[2:5]
	v_mfma_f32_16x16x32_bf16 v[30:33], v[134:137], v[190:193], v[30:33]
	v_mfma_f32_16x16x32_bf16 v[26:29], v[142:145], v[190:193], v[26:29]
	v_mfma_f32_16x16x32_bf16 v[22:25], v[134:137], v[178:181], v[22:25]
	v_mfma_f32_16x16x32_bf16 v[18:21], v[142:145], v[178:181], v[18:21]
	v_mfma_f32_16x16x32_bf16 v[14:17], v[134:137], v[182:185], v[14:17]
	v_mfma_f32_16x16x32_bf16 v[10:13], v[142:145], v[182:185], v[10:13]
	v_mfma_f32_16x16x32_bf16 v[6:9], v[134:137], v[166:169], v[6:9]
	v_mfma_f32_16x16x32_bf16 v[2:5], v[142:145], v[166:169], v[2:5]
	s_setprio 0
	s_barrier
	s_add_i32 s50, s34, 1
	s_mul_i32 s3, s50, s94
	s_mul_hi_i32 s2, s50, s94
	s_add_u32 s4, s3, s95
	s_addc_u32 s5, s2, s40
	v_cmp_gt_i64_e64 s[2:3], s[4:5], v[226:227]
	s_and_b64 vcc, exec, s[2:3]
	s_cbranch_vccnz .LBB0_1121
	s_ashr_i32 s8, s4, 31
	s_lshr_b32 s8, s8, 29
	s_add_i32 s8, s4, s8
	s_and_b32 s18, s8, -8
	s_sub_i32 s33, s4, s18
	s_cmp_gt_i32 s33, -1
	s_mov_b64 s[18:19], -1
	s_cbranch_scc0 .LBB0_1118
	s_lshl_b32 s51, s33, 9
	s_mov_b64 s[18:19], 0

.LBB0_1122:
	ds_read_b128 v[130:133], v240
	ds_read_b128 v[134:137], v241
	ds_read_b128 v[138:141], v242
	ds_read_b128 v[142:145], v243
	ds_read_b128 v[146:149], v244
	ds_read_b128 v[150:153], v245
	ds_read_b128 v[154:157], v246
	ds_read_b128 v[158:161], v247
	s_add_i32 s8, s31, s53
	s_add_i32 s55, s26, s53
	s_add_i32 s54, s8, 0x800
	s_addk_i32 s55, 0x800
	s_cmp_eq_u32 s53, 0
	s_cselect_b32 s56, s4, s54
	s_cselect_b32 s55, s5, s55
	s_add_i32 s54, s56, 0x80
	s_add_i32 s57, s8, 0x40780
	s_mov_b32 s8, s70
	s_mov_b32 m0, s44
	ds_read_b128 v[162:165], v248
	ds_read_b128 v[166:169], v248 offset:2048
	ds_read_b128 v[170:173], v249
	ds_read_b128 v[174:177], v249 offset:2048
	ds_read_b128 v[178:181], v248 offset:4096
	ds_read_b128 v[182:185], v248 offset:6144
	ds_read_b128 v[186:189], v249 offset:4096
	ds_read_b128 v[190:193], v249 offset:6144
	buffer_load_dwordx4 v1, s[8:11], s57 offen lds
	s_mov_b32 m0, s45
	s_nop 0
	buffer_load_dwordx4 v234, s[8:11], s57 offen lds
	s_waitcnt vmcnt(8)
	s_waitcnt lgkmcnt(0)
	s_barrier
	s_setprio 1
	s_waitcnt lgkmcnt(7)
	s_nop 0
	v_mfma_f32_16x16x32_bf16 v[126:129], v[130:133], v[162:165], v[126:129]
	v_mfma_f32_16x16x32_bf16 v[122:125], v[138:141], v[162:165], v[122:125]
	s_waitcnt lgkmcnt(6)
	s_nop 0
	v_mfma_f32_16x16x32_bf16 v[118:121], v[130:133], v[166:169], v[118:121]
	v_mfma_f32_16x16x32_bf16 v[114:117], v[138:141], v[166:169], v[114:117]
	s_waitcnt lgkmcnt(3)
	s_nop 0
	v_mfma_f32_16x16x32_bf16 v[110:113], v[130:133], v[178:181], v[110:113]
	v_mfma_f32_16x16x32_bf16 v[106:109], v[138:141], v[178:181], v[106:109]
	s_waitcnt lgkmcnt(2)
	s_nop 0
	v_mfma_f32_16x16x32_bf16 v[102:105], v[130:133], v[182:185], v[102:105]
	v_mfma_f32_16x16x32_bf16 v[98:101], v[138:141], v[182:185], v[98:101]
	v_mfma_f32_16x16x32_bf16 v[126:129], v[134:137], v[170:173], v[126:129]
	v_mfma_f32_16x16x32_bf16 v[122:125], v[142:145], v[170:173], v[122:125]
	v_mfma_f32_16x16x32_bf16 v[118:121], v[134:137], v[174:177], v[118:121]
	v_mfma_f32_16x16x32_bf16 v[114:117], v[142:145], v[174:177], v[114:117]
	s_waitcnt lgkmcnt(1)
	s_nop 0
	v_mfma_f32_16x16x32_bf16 v[110:113], v[134:137], v[186:189], v[110:113]
	v_mfma_f32_16x16x32_bf16 v[106:109], v[142:145], v[186:189], v[106:109]
	s_waitcnt lgkmcnt(0)
	s_nop 0
	v_mfma_f32_16x16x32_bf16 v[102:105], v[134:137], v[190:193], v[102:105]
	v_mfma_f32_16x16x32_bf16 v[98:101], v[142:145], v[190:193], v[98:101]
	s_setprio 0
	s_setprio 1
	v_mfma_f32_16x16x32_bf16 v[94:97], v[146:149], v[162:165], v[94:97]
	v_mfma_f32_16x16x32_bf16 v[90:93], v[154:157], v[162:165], v[90:93]
	v_mfma_f32_16x16x32_bf16 v[86:89], v[146:149], v[166:169], v[86:89]
	v_mfma_f32_16x16x32_bf16 v[82:85], v[154:157], v[166:169], v[82:85]
	v_mfma_f32_16x16x32_bf16 v[78:81], v[146:149], v[178:181], v[78:81]
	v_mfma_f32_16x16x32_bf16 v[74:77], v[154:157], v[178:181], v[74:77]
	v_mfma_f32_16x16x32_bf16 v[70:73], v[146:149], v[182:185], v[70:73]
	v_mfma_f32_16x16x32_bf16 v[66:69], v[154:157], v[182:185], v[66:69]
	v_mfma_f32_16x16x32_bf16 v[94:97], v[150:153], v[170:173], v[94:97]
	v_mfma_f32_16x16x32_bf16 v[90:93], v[158:161], v[170:173], v[90:93]
	v_mfma_f32_16x16x32_bf16 v[86:89], v[150:153], v[174:177], v[86:89]
	v_mfma_f32_16x16x32_bf16 v[82:85], v[158:161], v[174:177], v[82:85]
	v_mfma_f32_16x16x32_bf16 v[78:81], v[150:153], v[186:189], v[78:81]
	v_mfma_f32_16x16x32_bf16 v[74:77], v[158:161], v[186:189], v[74:77]
	v_mfma_f32_16x16x32_bf16 v[70:73], v[150:153], v[190:193], v[70:73]
	v_mfma_f32_16x16x32_bf16 v[66:69], v[158:161], v[190:193], v[66:69]
	s_setprio 0
	s_barrier
	s_mov_b32 m0, s23
	ds_read_b128 v[162:165], v248 offset:16384
	ds_read_b128 v[166:169], v248 offset:18432
	ds_read_b128 v[170:173], v249 offset:16384
	ds_read_b128 v[174:177], v249 offset:18432
	ds_read_b128 v[178:181], v248 offset:20480
	ds_read_b128 v[182:185], v248 offset:22528
	ds_read_b128 v[186:189], v249 offset:20480
	ds_read_b128 v[190:193], v249 offset:22528
	buffer_load_dwordx4 v233, s[8:11], s55 offen lds
	s_mov_b32 m0, s24
	s_add_i32 s57, s55, 0x40000
	buffer_load_dwordx4 v235, s[8:11], s55 offen lds
	s_mov_b32 m0, s25
	s_nop 0
	buffer_load_dwordx4 v233, s[8:11], s57 offen lds
	s_mov_b32 m0, s27
	s_nop 0
	buffer_load_dwordx4 v235, s[8:11], s57 offen lds
	s_mov_b32 m0, s22
	s_nop 0
	buffer_load_dwordx4 v1, s[8:11], s56 offen lds
	s_mov_b32 m0, s28
	s_nop 0
	buffer_load_dwordx4 v234, s[8:11], s56 offen lds
	s_waitcnt vmcnt(8)
	s_waitcnt lgkmcnt(0)
	s_barrier
	s_setprio 1
	s_waitcnt lgkmcnt(7)
	s_nop 0
	v_mfma_f32_16x16x32_bf16 v[62:65], v[130:133], v[162:165], v[62:65]
	v_mfma_f32_16x16x32_bf16 v[58:61], v[138:141], v[162:165], v[58:61]
	s_waitcnt lgkmcnt(6)
	s_nop 0
	v_mfma_f32_16x16x32_bf16 v[54:57], v[130:133], v[166:169], v[54:57]
	v_mfma_f32_16x16x32_bf16 v[50:53], v[138:141], v[166:169], v[50:53]
	s_waitcnt lgkmcnt(3)
	s_nop 0
	v_mfma_f32_16x16x32_bf16 v[46:49], v[130:133], v[178:181], v[46:49]
	v_mfma_f32_16x16x32_bf16 v[42:45], v[138:141], v[178:181], v[42:45]
	s_waitcnt lgkmcnt(2)
	s_nop 0
	v_mfma_f32_16x16x32_bf16 v[38:41], v[130:133], v[182:185], v[38:41]
	v_mfma_f32_16x16x32_bf16 v[34:37], v[138:141], v[182:185], v[34:37]
	v_mfma_f32_16x16x32_bf16 v[62:65], v[134:137], v[170:173], v[62:65]
	v_mfma_f32_16x16x32_bf16 v[58:61], v[142:145], v[170:173], v[58:61]
	v_mfma_f32_16x16x32_bf16 v[54:57], v[134:137], v[174:177], v[54:57]
	v_mfma_f32_16x16x32_bf16 v[50:53], v[142:145], v[174:177], v[50:53]
	s_waitcnt lgkmcnt(1)
	s_nop 0
	v_mfma_f32_16x16x32_bf16 v[46:49], v[134:137], v[186:189], v[46:49]
	v_mfma_f32_16x16x32_bf16 v[42:45], v[142:145], v[186:189], v[42:45]
	s_waitcnt lgkmcnt(0)
	s_nop 0
	v_mfma_f32_16x16x32_bf16 v[38:41], v[134:137], v[190:193], v[38:41]
	v_mfma_f32_16x16x32_bf16 v[34:37], v[142:145], v[190:193], v[34:37]
	s_setprio 0
	s_setprio 1
	v_mfma_f32_16x16x32_bf16 v[30:33], v[146:149], v[162:165], v[30:33]
	v_mfma_f32_16x16x32_bf16 v[26:29], v[154:157], v[162:165], v[26:29]
	v_mfma_f32_16x16x32_bf16 v[22:25], v[146:149], v[166:169], v[22:25]
	v_mfma_f32_16x16x32_bf16 v[18:21], v[154:157], v[166:169], v[18:21]
	v_mfma_f32_16x16x32_bf16 v[14:17], v[146:149], v[178:181], v[14:17]
	v_mfma_f32_16x16x32_bf16 v[10:13], v[154:157], v[178:181], v[10:13]
	v_mfma_f32_16x16x32_bf16 v[6:9], v[146:149], v[182:185], v[6:9]
	v_mfma_f32_16x16x32_bf16 v[2:5], v[154:157], v[182:185], v[2:5]
	v_mfma_f32_16x16x32_bf16 v[30:33], v[150:153], v[170:173], v[30:33]
	v_mfma_f32_16x16x32_bf16 v[26:29], v[158:161], v[170:173], v[26:29]
	v_mfma_f32_16x16x32_bf16 v[22:25], v[150:153], v[174:177], v[22:25]
	v_mfma_f32_16x16x32_bf16 v[18:21], v[158:161], v[174:177], v[18:21]
	v_mfma_f32_16x16x32_bf16 v[14:17], v[150:153], v[186:189], v[14:17]
	v_mfma_f32_16x16x32_bf16 v[10:13], v[158:161], v[186:189], v[10:13]
	v_mfma_f32_16x16x32_bf16 v[6:9], v[150:153], v[190:193], v[6:9]
	v_mfma_f32_16x16x32_bf16 v[2:5], v[158:161], v[190:193], v[2:5]
	s_setprio 0
	s_barrier
	ds_read_b128 v[130:133], v194
	ds_read_b128 v[134:137], v195
	ds_read_b128 v[138:141], v196
	ds_read_b128 v[142:145], v197
	ds_read_b128 v[146:149], v198
	ds_read_b128 v[150:153], v199
	ds_read_b128 v[154:157], v200
	ds_read_b128 v[158:161], v201
	s_add_i32 s56, s56, 0x40000
	s_mov_b32 m0, s29
	ds_read_b128 v[162:165], v248 offset:32768
	ds_read_b128 v[166:169], v248 offset:34816
	ds_read_b128 v[170:173], v249 offset:32768
	ds_read_b128 v[174:177], v249 offset:34816
	ds_read_b128 v[178:181], v248 offset:36864
	ds_read_b128 v[182:185], v248 offset:38912
	ds_read_b128 v[186:189], v249 offset:36864
	ds_read_b128 v[190:193], v249 offset:38912
	buffer_load_dwordx4 v1, s[8:11], s56 offen lds
	s_mov_b32 m0, s30
	s_nop 0
	buffer_load_dwordx4 v234, s[8:11], s56 offen lds
	s_waitcnt vmcnt(8)
	s_waitcnt lgkmcnt(0)
	s_barrier
	s_setprio 1
	s_waitcnt lgkmcnt(7)
	v_mfma_f32_16x16x32_bf16 v[126:129], v[130:133], v[162:165], v[126:129]
	v_mfma_f32_16x16x32_bf16 v[122:125], v[138:141], v[162:165], v[122:125]
	s_waitcnt lgkmcnt(6)
	s_nop 0
	v_mfma_f32_16x16x32_bf16 v[118:121], v[130:133], v[166:169], v[118:121]
	v_mfma_f32_16x16x32_bf16 v[114:117], v[138:141], v[166:169], v[114:117]
	s_waitcnt lgkmcnt(3)
	s_nop 0
	v_mfma_f32_16x16x32_bf16 v[110:113], v[130:133], v[178:181], v[110:113]
	v_mfma_f32_16x16x32_bf16 v[106:109], v[138:141], v[178:181], v[106:109]
	s_waitcnt lgkmcnt(2)
	s_nop 0
	v_mfma_f32_16x16x32_bf16 v[102:105], v[130:133], v[182:185], v[102:105]
	v_mfma_f32_16x16x32_bf16 v[98:101], v[138:141], v[182:185], v[98:101]
	v_mfma_f32_16x16x32_bf16 v[126:129], v[134:137], v[170:173], v[126:129]
	v_mfma_f32_16x16x32_bf16 v[122:125], v[142:145], v[170:173], v[122:125]
	v_mfma_f32_16x16x32_bf16 v[118:121], v[134:137], v[174:177], v[118:121]
	v_mfma_f32_16x16x32_bf16 v[114:117], v[142:145], v[174:177], v[114:117]
	s_waitcnt lgkmcnt(1)
	s_nop 0
	v_mfma_f32_16x16x32_bf16 v[110:113], v[134:137], v[186:189], v[110:113]
	v_mfma_f32_16x16x32_bf16 v[106:109], v[142:145], v[186:189], v[106:109]
	s_waitcnt lgkmcnt(0)
	s_nop 0
	v_mfma_f32_16x16x32_bf16 v[102:105], v[134:137], v[190:193], v[102:105]
	v_mfma_f32_16x16x32_bf16 v[98:101], v[142:145], v[190:193], v[98:101]
	s_setprio 0
	s_setprio 1
	v_mfma_f32_16x16x32_bf16 v[94:97], v[146:149], v[162:165], v[94:97]
	v_mfma_f32_16x16x32_bf16 v[90:93], v[154:157], v[162:165], v[90:93]
	v_mfma_f32_16x16x32_bf16 v[86:89], v[146:149], v[166:169], v[86:89]
	v_mfma_f32_16x16x32_bf16 v[82:85], v[154:157], v[166:169], v[82:85]
	v_mfma_f32_16x16x32_bf16 v[78:81], v[146:149], v[178:181], v[78:81]
	v_mfma_f32_16x16x32_bf16 v[74:77], v[154:157], v[178:181], v[74:77]
	v_mfma_f32_16x16x32_bf16 v[70:73], v[146:149], v[182:185], v[70:73]
	v_mfma_f32_16x16x32_bf16 v[66:69], v[154:157], v[182:185], v[66:69]
	v_mfma_f32_16x16x32_bf16 v[94:97], v[150:153], v[170:173], v[94:97]
	v_mfma_f32_16x16x32_bf16 v[90:93], v[158:161], v[170:173], v[90:93]
	v_mfma_f32_16x16x32_bf16 v[86:89], v[150:153], v[174:177], v[86:89]
	v_mfma_f32_16x16x32_bf16 v[82:85], v[158:161], v[174:177], v[82:85]
	v_mfma_f32_16x16x32_bf16 v[78:81], v[150:153], v[186:189], v[78:81]
	v_mfma_f32_16x16x32_bf16 v[74:77], v[158:161], v[186:189], v[74:77]
	v_mfma_f32_16x16x32_bf16 v[70:73], v[150:153], v[190:193], v[70:73]
	v_mfma_f32_16x16x32_bf16 v[66:69], v[158:161], v[190:193], v[66:69]
	s_setprio 0
	s_barrier
	s_mov_b32 m0, s35
	s_add_i32 s56, s55, 0x80
	ds_read_b128 v[162:165], v248 offset:49152
	ds_read_b128 v[166:169], v248 offset:51200
	ds_read_b128 v[170:173], v249 offset:49152
	ds_read_b128 v[174:177], v249 offset:51200
	ds_read_b128 v[178:181], v248 offset:53248
	ds_read_b128 v[182:185], v248 offset:55296
	ds_read_b128 v[186:189], v249 offset:53248
	ds_read_b128 v[190:193], v249 offset:55296
	buffer_load_dwordx4 v233, s[8:11], s56 offen lds
	s_mov_b32 m0, s36
	s_add_i32 s55, s55, 0x40080
	buffer_load_dwordx4 v235, s[8:11], s56 offen lds
	s_mov_b32 m0, s39
	s_nop 0
	buffer_load_dwordx4 v233, s[8:11], s55 offen lds
	s_mov_b32 m0, s41
	s_nop 0
	buffer_load_dwordx4 v235, s[8:11], s55 offen lds
	s_mov_b32 m0, s37
	s_nop 0
	buffer_load_dwordx4 v1, s[8:11], s54 offen lds
	s_mov_b32 m0, s38
	s_nop 0
	buffer_load_dwordx4 v234, s[8:11], s54 offen lds
	s_waitcnt vmcnt(8)
	s_waitcnt lgkmcnt(0)
	s_barrier
	s_setprio 1
	s_waitcnt lgkmcnt(7)
	s_nop 0
	v_mfma_f32_16x16x32_bf16 v[62:65], v[130:133], v[162:165], v[62:65]
	v_mfma_f32_16x16x32_bf16 v[58:61], v[138:141], v[162:165], v[58:61]
	s_waitcnt lgkmcnt(6)
	s_nop 0
	v_mfma_f32_16x16x32_bf16 v[54:57], v[130:133], v[166:169], v[54:57]
	v_mfma_f32_16x16x32_bf16 v[50:53], v[138:141], v[166:169], v[50:53]
	s_waitcnt lgkmcnt(3)
	s_nop 0
	v_mfma_f32_16x16x32_bf16 v[46:49], v[130:133], v[178:181], v[46:49]
	v_mfma_f32_16x16x32_bf16 v[42:45], v[138:141], v[178:181], v[42:45]
	s_waitcnt lgkmcnt(2)
	s_nop 0
	v_mfma_f32_16x16x32_bf16 v[38:41], v[130:133], v[182:185], v[38:41]
	v_mfma_f32_16x16x32_bf16 v[34:37], v[138:141], v[182:185], v[34:37]
	v_mfma_f32_16x16x32_bf16 v[62:65], v[134:137], v[170:173], v[62:65]
	v_mfma_f32_16x16x32_bf16 v[58:61], v[142:145], v[170:173], v[58:61]
	v_mfma_f32_16x16x32_bf16 v[54:57], v[134:137], v[174:177], v[54:57]
	v_mfma_f32_16x16x32_bf16 v[50:53], v[142:145], v[174:177], v[50:53]
	s_waitcnt lgkmcnt(1)
	s_nop 0
	v_mfma_f32_16x16x32_bf16 v[46:49], v[134:137], v[186:189], v[46:49]
	v_mfma_f32_16x16x32_bf16 v[42:45], v[142:145], v[186:189], v[42:45]
	s_waitcnt lgkmcnt(0)
	s_nop 0
	v_mfma_f32_16x16x32_bf16 v[38:41], v[134:137], v[190:193], v[38:41]
	v_mfma_f32_16x16x32_bf16 v[34:37], v[142:145], v[190:193], v[34:37]
	s_setprio 0
	s_setprio 1
	v_mfma_f32_16x16x32_bf16 v[30:33], v[146:149], v[162:165], v[30:33]
	v_mfma_f32_16x16x32_bf16 v[26:29], v[154:157], v[162:165], v[26:29]
	v_mfma_f32_16x16x32_bf16 v[22:25], v[146:149], v[166:169], v[22:25]
	v_mfma_f32_16x16x32_bf16 v[18:21], v[154:157], v[166:169], v[18:21]
	v_mfma_f32_16x16x32_bf16 v[14:17], v[146:149], v[178:181], v[14:17]
	v_mfma_f32_16x16x32_bf16 v[10:13], v[154:157], v[178:181], v[10:13]
	v_mfma_f32_16x16x32_bf16 v[6:9], v[146:149], v[182:185], v[6:9]
	v_mfma_f32_16x16x32_bf16 v[2:5], v[154:157], v[182:185], v[2:5]
	v_mfma_f32_16x16x32_bf16 v[30:33], v[150:153], v[170:173], v[30:33]
	v_mfma_f32_16x16x32_bf16 v[26:29], v[158:161], v[170:173], v[26:29]
	v_mfma_f32_16x16x32_bf16 v[22:25], v[150:153], v[174:177], v[22:25]
	v_mfma_f32_16x16x32_bf16 v[18:21], v[158:161], v[174:177], v[18:21]
	v_mfma_f32_16x16x32_bf16 v[14:17], v[150:153], v[186:189], v[14:17]
	v_mfma_f32_16x16x32_bf16 v[10:13], v[158:161], v[186:189], v[10:13]
	v_mfma_f32_16x16x32_bf16 v[6:9], v[150:153], v[190:193], v[6:9]
	v_mfma_f32_16x16x32_bf16 v[2:5], v[158:161], v[190:193], v[2:5]
	s_setprio 0
	s_barrier
	s_add_i32 s33, s33, 2
	s_addk_i32 s53, 0x100
	s_cmp_gt_u32 s33, 13
	s_cbranch_scc0 .LBB0_1122
	s_and_b64 vcc, exec, s[16:17]
	s_cbranch_vccz .LBB0_1125
	s_barrier

.LBB0_1232:
	s_waitcnt lgkmcnt(0)
	s_add_i32 s2, s51, 0x100
	s_add_i32 s3, s46, 0x100
	s_barrier
	s_setprio 1
	s_waitcnt lgkmcnt(7)
	s_nop 0
	v_mfma_f32_16x16x32_bf16 v[74:77], v[190:193], v[218:221], 0
	v_mfma_f32_16x16x32_bf16 v[70:73], v[182:185], v[218:221], 0
	s_waitcnt lgkmcnt(6)
	s_nop 0
	v_mfma_f32_16x16x32_bf16 v[66:69], v[190:193], v[210:213], 0
	v_mfma_f32_16x16x32_bf16 v[82:85], v[182:185], v[210:213], 0
	s_waitcnt lgkmcnt(3)
	s_nop 0
	v_mfma_f32_16x16x32_bf16 v[78:81], v[190:193], v[202:205], 0
	v_mfma_f32_16x16x32_bf16 v[90:93], v[182:185], v[202:205], 0
	s_waitcnt lgkmcnt(2)
	s_nop 0
	v_mfma_f32_16x16x32_bf16 v[86:89], v[190:193], v[194:197], 0
	v_mfma_f32_16x16x32_bf16 v[102:105], v[182:185], v[194:197], 0
	v_mfma_f32_16x16x32_bf16 v[74:77], v[186:189], v[222:225], v[74:77]
	v_mfma_f32_16x16x32_bf16 v[70:73], v[178:181], v[222:225], v[70:73]
	v_mfma_f32_16x16x32_bf16 v[66:69], v[186:189], v[214:217], v[66:69]
	v_mfma_f32_16x16x32_bf16 v[82:85], v[178:181], v[214:217], v[82:85]
	s_waitcnt lgkmcnt(1)
	s_nop 0
	v_mfma_f32_16x16x32_bf16 v[78:81], v[186:189], v[206:209], v[78:81]
	v_mfma_f32_16x16x32_bf16 v[90:93], v[178:181], v[206:209], v[90:93]
	s_waitcnt lgkmcnt(0)
	s_nop 0
	v_mfma_f32_16x16x32_bf16 v[86:89], v[186:189], v[198:201], v[86:89]
	v_mfma_f32_16x16x32_bf16 v[102:105], v[178:181], v[198:201], v[102:105]
	s_setprio 0
	s_setprio 1
	v_mfma_f32_16x16x32_bf16 v[98:101], v[174:177], v[218:221], 0
	v_mfma_f32_16x16x32_bf16 v[94:97], v[166:169], v[218:221], 0
	v_mfma_f32_16x16x32_bf16 v[106:109], v[174:177], v[210:213], 0
	v_mfma_f32_16x16x32_bf16 v[110:113], v[166:169], v[210:213], 0
	v_mfma_f32_16x16x32_bf16 v[114:117], v[174:177], v[202:205], 0
	v_mfma_f32_16x16x32_bf16 v[118:121], v[166:169], v[202:205], 0
	v_mfma_f32_16x16x32_bf16 v[122:125], v[174:177], v[194:197], 0
	v_mfma_f32_16x16x32_bf16 v[126:129], v[166:169], v[194:197], 0
	s_nop 0
	s_nop 0
	v_mfma_f32_16x16x32_bf16 v[98:101], v[170:173], v[222:225], v[98:101]
	v_mfma_f32_16x16x32_bf16 v[94:97], v[162:165], v[222:225], v[94:97]
	v_mfma_f32_16x16x32_bf16 v[106:109], v[170:173], v[214:217], v[106:109]
	v_mfma_f32_16x16x32_bf16 v[110:113], v[162:165], v[214:217], v[110:113]
	v_mfma_f32_16x16x32_bf16 v[114:117], v[170:173], v[206:209], v[114:117]
	v_mfma_f32_16x16x32_bf16 v[118:121], v[162:165], v[206:209], v[118:121]
	v_mfma_f32_16x16x32_bf16 v[122:125], v[170:173], v[198:201], v[122:125]
	v_mfma_f32_16x16x32_bf16 v[126:129], v[162:165], v[198:201], v[126:129]
	s_setprio 0
	s_barrier
	s_mov_b32 m0, s43
	s_mov_b32 s8, s70
	ds_read_b128 v[202:205], v247 offset:16384
	ds_read_b128 v[194:197], v247 offset:18432
	ds_read_b128 v[206:209], v248 offset:16384
	ds_read_b128 v[198:201], v248 offset:18432
	ds_read_b128 v[138:141], v247 offset:20480
	ds_read_b128 v[130:133], v247 offset:22528
	ds_read_b128 v[142:145], v248 offset:20480
	ds_read_b128 v[134:137], v248 offset:22528
	buffer_load_dwordx4 v231, s[8:11], s3 offen lds
	s_mov_b32 m0, s44
	s_and_b64 vcc, exec, s[0:1]
	buffer_load_dwordx4 v234, s[8:11], s3 offen lds
	s_add_i32 s3, s46, 0x100100
	s_mov_b32 m0, s45
	s_nop 0
	buffer_load_dwordx4 v231, s[8:11], s3 offen lds
	s_mov_b32 m0, s47
	s_nop 0
	buffer_load_dwordx4 v234, s[8:11], s3 offen lds
	s_mov_b32 m0, s42
	s_nop 0
	buffer_load_dwordx4 v230, s[8:11], s2 offen lds
	s_mov_b32 m0, s48
	s_nop 0
	buffer_load_dwordx4 v233, s[8:11], s2 offen lds
	s_mov_b64 s[2:3], -1
	s_cbranch_vccz .LBB0_1234
	s_waitcnt vmcnt(8)
	s_mov_b64 s[2:3], 0

.LBB0_1236:
	s_waitcnt lgkmcnt(0)
	s_barrier
	s_setprio 1
	s_waitcnt lgkmcnt(7)
	v_mfma_f32_16x16x32_bf16 v[10:13], v[190:193], v[202:205], 0
	v_mfma_f32_16x16x32_bf16 v[6:9], v[182:185], v[202:205], 0
	s_waitcnt lgkmcnt(6)
	s_nop 0
	v_mfma_f32_16x16x32_bf16 v[2:5], v[190:193], v[194:197], 0
	v_mfma_f32_16x16x32_bf16 v[18:21], v[182:185], v[194:197], 0
	s_waitcnt lgkmcnt(3)
	s_nop 0
	v_mfma_f32_16x16x32_bf16 v[14:17], v[190:193], v[138:141], 0
	v_mfma_f32_16x16x32_bf16 v[26:29], v[182:185], v[138:141], 0
	s_waitcnt lgkmcnt(2)
	s_nop 0
	v_mfma_f32_16x16x32_bf16 v[22:25], v[190:193], v[130:133], 0
	v_mfma_f32_16x16x32_bf16 v[38:41], v[182:185], v[130:133], 0
	v_mfma_f32_16x16x32_bf16 v[10:13], v[186:189], v[206:209], v[10:13]
	v_mfma_f32_16x16x32_bf16 v[6:9], v[178:181], v[206:209], v[6:9]
	v_mfma_f32_16x16x32_bf16 v[0:3], v[186:189], v[198:201], v[2:5]
	v_mfma_f32_16x16x32_bf16 v[18:21], v[178:181], v[198:201], v[18:21]
	s_waitcnt lgkmcnt(1)
	s_nop 0
	v_mfma_f32_16x16x32_bf16 v[14:17], v[186:189], v[142:145], v[14:17]
	v_mfma_f32_16x16x32_bf16 v[26:29], v[178:181], v[142:145], v[26:29]
	s_waitcnt lgkmcnt(0)
	s_nop 0
	v_mfma_f32_16x16x32_bf16 v[22:25], v[186:189], v[134:137], v[22:25]
	v_mfma_f32_16x16x32_bf16 v[38:41], v[178:181], v[134:137], v[38:41]
	s_setprio 0
	s_setprio 1
	v_mfma_f32_16x16x32_bf16 v[34:37], v[174:177], v[202:205], 0
	v_mfma_f32_16x16x32_bf16 v[30:33], v[166:169], v[202:205], 0
	v_mfma_f32_16x16x32_bf16 v[42:45], v[174:177], v[194:197], 0
	v_mfma_f32_16x16x32_bf16 v[46:49], v[166:169], v[194:197], 0
	v_mfma_f32_16x16x32_bf16 v[50:53], v[174:177], v[138:141], 0
	v_mfma_f32_16x16x32_bf16 v[54:57], v[166:169], v[138:141], 0
	v_mfma_f32_16x16x32_bf16 v[58:61], v[174:177], v[130:133], 0
	v_mfma_f32_16x16x32_bf16 v[62:65], v[166:169], v[130:133], 0
	s_nop 0
	s_nop 0
	v_mfma_f32_16x16x32_bf16 v[34:37], v[170:173], v[206:209], v[34:37]
	v_mfma_f32_16x16x32_bf16 v[30:33], v[162:165], v[206:209], v[30:33]
	v_mfma_f32_16x16x32_bf16 v[42:45], v[170:173], v[198:201], v[42:45]
	v_mfma_f32_16x16x32_bf16 v[46:49], v[162:165], v[198:201], v[46:49]
	v_mfma_f32_16x16x32_bf16 v[50:53], v[170:173], v[142:145], v[50:53]
	v_mfma_f32_16x16x32_bf16 v[54:57], v[162:165], v[142:145], v[54:57]
	v_mfma_f32_16x16x32_bf16 v[58:61], v[170:173], v[134:137], v[58:61]
	v_mfma_f32_16x16x32_bf16 v[62:65], v[162:165], v[134:137], v[62:65]
	s_setprio 0
	s_barrier
	s_add_i32 s2, 0, 0x18000
	v_add_u32_e32 v194, s2, v237
	v_add_u32_e32 v195, s2, v238
	s_add_i32 s2, 0, 0x1c000
	v_add_u32_e32 v196, s72, v237
	v_add_u32_e32 v198, s2, v237
	v_add_u32_e32 v200, s73, v237
	ds_read_b128 v[146:149], v194
	ds_read_b128 v[150:153], v195
	v_add_u32_e32 v197, s72, v238
	ds_read_b128 v[154:157], v196
	ds_read_b128 v[158:161], v197
	v_add_u32_e32 v199, s2, v238
	ds_read_b128 v[130:133], v198
	ds_read_b128 v[134:137], v199
	v_add_u32_e32 v201, s73, v238
	ds_read_b128 v[138:141], v200
	ds_read_b128 v[142:145], v201
	s_mov_b32 m0, s49
	s_add_i32 s2, s51, 0x100100
	s_mov_b32 s8, s70
	ds_read_b128 v[186:189], v247 offset:32768
	ds_read_b128 v[174:177], v247 offset:34816
	ds_read_b128 v[190:193], v248 offset:32768
	ds_read_b128 v[178:181], v248 offset:34816
	ds_read_b128 v[170:173], v247 offset:36864
	ds_read_b128 v[162:165], v247 offset:38912
	ds_read_b128 v[182:185], v248 offset:36864
	ds_read_b128 v[166:169], v248 offset:38912
	buffer_load_dwordx4 v230, s[8:11], s2 offen lds
	s_mov_b32 m0, s50
	s_and_b64 vcc, exec, s[0:1]
	buffer_load_dwordx4 v233, s[8:11], s2 offen lds
	s_mov_b64 s[2:3], -1
	s_cbranch_vccz .LBB0_1238
	s_waitcnt vmcnt(8)
	s_mov_b64 s[2:3], 0

.LBB0_1240:
	s_waitcnt lgkmcnt(0)
	s_add_i32 s2, s51, 0x180
	s_add_i32 s3, s46, 0x180
	s_barrier
	s_setprio 1
	s_waitcnt lgkmcnt(7)
	s_nop 0
	v_mfma_f32_16x16x32_bf16 v[74:77], v[146:149], v[186:189], v[74:77]
	v_mfma_f32_16x16x32_bf16 v[70:73], v[154:157], v[186:189], v[70:73]
	s_waitcnt lgkmcnt(6)
	s_nop 0
	v_mfma_f32_16x16x32_bf16 v[66:69], v[146:149], v[174:177], v[66:69]
	v_mfma_f32_16x16x32_bf16 v[82:85], v[154:157], v[174:177], v[82:85]
	s_waitcnt lgkmcnt(3)
	s_nop 0
	v_mfma_f32_16x16x32_bf16 v[78:81], v[146:149], v[170:173], v[78:81]
	v_mfma_f32_16x16x32_bf16 v[90:93], v[154:157], v[170:173], v[90:93]
	s_waitcnt lgkmcnt(2)
	s_nop 0
	v_mfma_f32_16x16x32_bf16 v[86:89], v[146:149], v[162:165], v[86:89]
	v_mfma_f32_16x16x32_bf16 v[102:105], v[154:157], v[162:165], v[102:105]
	v_mfma_f32_16x16x32_bf16 v[74:77], v[150:153], v[190:193], v[74:77]
	v_mfma_f32_16x16x32_bf16 v[70:73], v[158:161], v[190:193], v[70:73]
	v_mfma_f32_16x16x32_bf16 v[66:69], v[150:153], v[178:181], v[66:69]
	v_mfma_f32_16x16x32_bf16 v[82:85], v[158:161], v[178:181], v[82:85]
	s_waitcnt lgkmcnt(1)
	s_nop 0
	v_mfma_f32_16x16x32_bf16 v[78:81], v[150:153], v[182:185], v[78:81]
	v_mfma_f32_16x16x32_bf16 v[90:93], v[158:161], v[182:185], v[90:93]
	s_waitcnt lgkmcnt(0)
	s_nop 0
	v_mfma_f32_16x16x32_bf16 v[86:89], v[150:153], v[166:169], v[86:89]
	v_mfma_f32_16x16x32_bf16 v[102:105], v[158:161], v[166:169], v[102:105]
	s_setprio 0
	s_setprio 1
	v_mfma_f32_16x16x32_bf16 v[98:101], v[130:133], v[186:189], v[98:101]
	v_mfma_f32_16x16x32_bf16 v[94:97], v[138:141], v[186:189], v[94:97]
	v_mfma_f32_16x16x32_bf16 v[106:109], v[130:133], v[174:177], v[106:109]
	v_mfma_f32_16x16x32_bf16 v[110:113], v[138:141], v[174:177], v[110:113]
	v_mfma_f32_16x16x32_bf16 v[114:117], v[130:133], v[170:173], v[114:117]
	v_mfma_f32_16x16x32_bf16 v[118:121], v[138:141], v[170:173], v[118:121]
	v_mfma_f32_16x16x32_bf16 v[122:125], v[130:133], v[162:165], v[122:125]
	v_mfma_f32_16x16x32_bf16 v[126:129], v[138:141], v[162:165], v[126:129]
	v_mfma_f32_16x16x32_bf16 v[98:101], v[134:137], v[190:193], v[98:101]
	v_mfma_f32_16x16x32_bf16 v[94:97], v[142:145], v[190:193], v[94:97]
	v_mfma_f32_16x16x32_bf16 v[106:109], v[134:137], v[178:181], v[106:109]
	v_mfma_f32_16x16x32_bf16 v[110:113], v[142:145], v[178:181], v[110:113]
	v_mfma_f32_16x16x32_bf16 v[114:117], v[134:137], v[182:185], v[114:117]
	v_mfma_f32_16x16x32_bf16 v[118:121], v[142:145], v[182:185], v[118:121]
	v_mfma_f32_16x16x32_bf16 v[122:125], v[134:137], v[166:169], v[122:125]
	v_mfma_f32_16x16x32_bf16 v[126:129], v[142:145], v[166:169], v[126:129]
	s_setprio 0
	s_barrier
	s_mov_b32 m0, s53
	s_mov_b32 s8, s70
	ds_read_b128 v[186:189], v247 offset:49152
	ds_read_b128 v[174:177], v247 offset:51200
	ds_read_b128 v[190:193], v248 offset:49152
	ds_read_b128 v[178:181], v248 offset:51200
	ds_read_b128 v[170:173], v247 offset:53248
	ds_read_b128 v[162:165], v247 offset:55296
	ds_read_b128 v[182:185], v248 offset:53248
	ds_read_b128 v[166:169], v248 offset:55296
	buffer_load_dwordx4 v231, s[8:11], s3 offen lds
	s_mov_b32 m0, s54
	s_and_b64 vcc, exec, s[0:1]
	buffer_load_dwordx4 v234, s[8:11], s3 offen lds
	s_add_i32 s3, s46, 0x100180
	s_mov_b32 m0, s57
	s_nop 0
	buffer_load_dwordx4 v231, s[8:11], s3 offen lds
	s_mov_b32 m0, s58
	s_nop 0
	buffer_load_dwordx4 v234, s[8:11], s3 offen lds
	s_mov_b32 m0, s55
	s_nop 0
	buffer_load_dwordx4 v230, s[8:11], s2 offen lds
	s_mov_b32 m0, s56
	s_nop 0
	buffer_load_dwordx4 v233, s[8:11], s2 offen lds
	s_mov_b64 s[2:3], -1
	s_cbranch_vccz .LBB0_1242
	s_waitcnt vmcnt(8)
	s_mov_b64 s[2:3], 0

.LBB0_1244:
	s_waitcnt lgkmcnt(0)
	s_barrier
	s_setprio 1
	s_waitcnt lgkmcnt(7)
	s_nop 0
	v_mfma_f32_16x16x32_bf16 v[10:13], v[146:149], v[186:189], v[10:13]
	v_mfma_f32_16x16x32_bf16 v[4:7], v[154:157], v[186:189], v[6:9]
	s_waitcnt lgkmcnt(6)
	s_nop 0
	v_mfma_f32_16x16x32_bf16 v[0:3], v[146:149], v[174:177], v[0:3]
	v_mfma_f32_16x16x32_bf16 v[18:21], v[154:157], v[174:177], v[18:21]
	s_waitcnt lgkmcnt(3)
	s_nop 0
	v_mfma_f32_16x16x32_bf16 v[14:17], v[146:149], v[170:173], v[14:17]
	v_mfma_f32_16x16x32_bf16 v[26:29], v[154:157], v[170:173], v[26:29]
	s_waitcnt lgkmcnt(2)
	s_nop 0
	v_mfma_f32_16x16x32_bf16 v[22:25], v[146:149], v[162:165], v[22:25]
	v_mfma_f32_16x16x32_bf16 v[38:41], v[154:157], v[162:165], v[38:41]
	v_mfma_f32_16x16x32_bf16 v[10:13], v[150:153], v[190:193], v[10:13]
	v_mfma_f32_16x16x32_bf16 v[6:9], v[158:161], v[190:193], v[4:7]
	v_mfma_f32_16x16x32_bf16 v[2:5], v[150:153], v[178:181], v[0:3]
	v_mfma_f32_16x16x32_bf16 v[18:21], v[158:161], v[178:181], v[18:21]
	s_waitcnt lgkmcnt(1)
	s_nop 0
	v_mfma_f32_16x16x32_bf16 v[14:17], v[150:153], v[182:185], v[14:17]
	v_mfma_f32_16x16x32_bf16 v[26:29], v[158:161], v[182:185], v[26:29]
	s_waitcnt lgkmcnt(0)
	s_nop 0
	v_mfma_f32_16x16x32_bf16 v[22:25], v[150:153], v[166:169], v[22:25]
	v_mfma_f32_16x16x32_bf16 v[38:41], v[158:161], v[166:169], v[38:41]
	s_setprio 0
	s_setprio 1
	v_mfma_f32_16x16x32_bf16 v[34:37], v[130:133], v[186:189], v[34:37]
	v_mfma_f32_16x16x32_bf16 v[30:33], v[138:141], v[186:189], v[30:33]
	v_mfma_f32_16x16x32_bf16 v[42:45], v[130:133], v[174:177], v[42:45]
	v_mfma_f32_16x16x32_bf16 v[46:49], v[138:141], v[174:177], v[46:49]
	v_mfma_f32_16x16x32_bf16 v[50:53], v[130:133], v[170:173], v[50:53]
	v_mfma_f32_16x16x32_bf16 v[54:57], v[138:141], v[170:173], v[54:57]
	v_mfma_f32_16x16x32_bf16 v[58:61], v[130:133], v[162:165], v[58:61]
	v_mfma_f32_16x16x32_bf16 v[62:65], v[138:141], v[162:165], v[62:65]
	v_mfma_f32_16x16x32_bf16 v[34:37], v[134:137], v[190:193], v[34:37]
	v_mfma_f32_16x16x32_bf16 v[30:33], v[142:145], v[190:193], v[30:33]
	v_mfma_f32_16x16x32_bf16 v[42:45], v[134:137], v[178:181], v[42:45]
	v_mfma_f32_16x16x32_bf16 v[46:49], v[142:145], v[178:181], v[46:49]
	v_mfma_f32_16x16x32_bf16 v[50:53], v[134:137], v[182:185], v[50:53]
	v_mfma_f32_16x16x32_bf16 v[54:57], v[142:145], v[182:185], v[54:57]
	v_mfma_f32_16x16x32_bf16 v[58:61], v[134:137], v[166:169], v[58:61]
	v_mfma_f32_16x16x32_bf16 v[62:65], v[142:145], v[166:169], v[62:65]
	s_setprio 0
	s_barrier
	s_add_i32 s82, s52, 1
	s_mul_i32 s0, s82, s94
	s_mul_hi_i32 s1, s82, s94
	s_add_u32 s0, s0, s95
	s_addc_u32 s1, s1, s65
	v_cmp_gt_i64_e64 s[2:3], s[0:1], v[226:227]
	s_and_b64 vcc, exec, s[2:3]
	s_cbranch_vccnz .LBB0_1250
	s_ashr_i32 s4, s0, 31
	s_lshr_b32 s4, s4, 29
	s_add_i32 s8, s0, s4
	s_and_b32 s4, s8, -8
	s_sub_i32 s30, s0, s4
	s_cmp_gt_i32 s30, -1
	s_mov_b64 s[4:5], -1
	s_cbranch_scc0 .LBB0_1247
	s_lshl_b32 s31, s30, 7
	s_mov_b64 s[4:5], 0

.LBB0_1251:
	ds_read_b128 v[130:133], v239
	ds_read_b128 v[134:137], v240
	ds_read_b128 v[138:141], v241
	ds_read_b128 v[142:145], v242
	ds_read_b128 v[146:149], v243
	ds_read_b128 v[150:153], v244
	ds_read_b128 v[154:157], v245
	ds_read_b128 v[158:161], v246
	s_add_i32 s8, s51, s5
	s_add_i32 s31, s46, s5
	s_add_i32 s30, s8, 0x2000
	s_addk_i32 s31, 0x2000
	s_cmp_eq_u32 s5, 0
	s_cselect_b32 s33, s0, s30
	s_cselect_b32 s31, s1, s31
	s_add_i32 s30, s33, 0x80
	s_add_i32 s34, s8, 0x101f80
	s_mov_b32 s8, s70
	s_mov_b32 m0, s61
	ds_read_b128 v[162:165], v247
	ds_read_b128 v[166:169], v247 offset:2048
	ds_read_b128 v[170:173], v248
	ds_read_b128 v[174:177], v248 offset:2048
	ds_read_b128 v[178:181], v247 offset:4096
	ds_read_b128 v[182:185], v247 offset:6144
	ds_read_b128 v[186:189], v248 offset:4096
	ds_read_b128 v[190:193], v248 offset:6144
	buffer_load_dwordx4 v230, s[8:11], s34 offen lds
	s_mov_b32 m0, s64
	s_nop 0
	buffer_load_dwordx4 v233, s[8:11], s34 offen lds
	s_waitcnt vmcnt(8)
	s_waitcnt lgkmcnt(0)
	s_barrier
	s_setprio 1
	s_waitcnt lgkmcnt(7)
	v_mfma_f32_16x16x32_bf16 v[74:77], v[130:133], v[162:165], v[74:77]
	v_mfma_f32_16x16x32_bf16 v[70:73], v[138:141], v[162:165], v[70:73]
	s_waitcnt lgkmcnt(6)
	s_nop 0
	v_mfma_f32_16x16x32_bf16 v[66:69], v[130:133], v[166:169], v[66:69]
	v_mfma_f32_16x16x32_bf16 v[82:85], v[138:141], v[166:169], v[82:85]
	s_waitcnt lgkmcnt(3)
	s_nop 0
	v_mfma_f32_16x16x32_bf16 v[78:81], v[130:133], v[178:181], v[78:81]
	v_mfma_f32_16x16x32_bf16 v[90:93], v[138:141], v[178:181], v[90:93]
	s_waitcnt lgkmcnt(2)
	s_nop 0
	v_mfma_f32_16x16x32_bf16 v[86:89], v[130:133], v[182:185], v[86:89]
	v_mfma_f32_16x16x32_bf16 v[102:105], v[138:141], v[182:185], v[102:105]
	v_mfma_f32_16x16x32_bf16 v[74:77], v[134:137], v[170:173], v[74:77]
	v_mfma_f32_16x16x32_bf16 v[70:73], v[142:145], v[170:173], v[70:73]
	v_mfma_f32_16x16x32_bf16 v[66:69], v[134:137], v[174:177], v[66:69]
	v_mfma_f32_16x16x32_bf16 v[82:85], v[142:145], v[174:177], v[82:85]
	s_waitcnt lgkmcnt(1)
	s_nop 0
	v_mfma_f32_16x16x32_bf16 v[78:81], v[134:137], v[186:189], v[78:81]
	v_mfma_f32_16x16x32_bf16 v[90:93], v[142:145], v[186:189], v[90:93]
	s_waitcnt lgkmcnt(0)
	s_nop 0
	v_mfma_f32_16x16x32_bf16 v[86:89], v[134:137], v[190:193], v[86:89]
	v_mfma_f32_16x16x32_bf16 v[102:105], v[142:145], v[190:193], v[102:105]
	s_setprio 0
	s_setprio 1
	v_mfma_f32_16x16x32_bf16 v[98:101], v[146:149], v[162:165], v[98:101]
	v_mfma_f32_16x16x32_bf16 v[94:97], v[154:157], v[162:165], v[94:97]
	v_mfma_f32_16x16x32_bf16 v[106:109], v[146:149], v[166:169], v[106:109]
	v_mfma_f32_16x16x32_bf16 v[110:113], v[154:157], v[166:169], v[110:113]
	v_mfma_f32_16x16x32_bf16 v[114:117], v[146:149], v[178:181], v[114:117]
	v_mfma_f32_16x16x32_bf16 v[118:121], v[154:157], v[178:181], v[118:121]
	v_mfma_f32_16x16x32_bf16 v[122:125], v[146:149], v[182:185], v[122:125]
	v_mfma_f32_16x16x32_bf16 v[126:129], v[154:157], v[182:185], v[126:129]
	v_mfma_f32_16x16x32_bf16 v[98:101], v[150:153], v[170:173], v[98:101]
	v_mfma_f32_16x16x32_bf16 v[94:97], v[158:161], v[170:173], v[94:97]
	v_mfma_f32_16x16x32_bf16 v[106:109], v[150:153], v[174:177], v[106:109]
	v_mfma_f32_16x16x32_bf16 v[110:113], v[158:161], v[174:177], v[110:113]
	v_mfma_f32_16x16x32_bf16 v[114:117], v[150:153], v[186:189], v[114:117]
	v_mfma_f32_16x16x32_bf16 v[118:121], v[158:161], v[186:189], v[118:121]
	v_mfma_f32_16x16x32_bf16 v[122:125], v[150:153], v[190:193], v[122:125]
	v_mfma_f32_16x16x32_bf16 v[126:129], v[158:161], v[190:193], v[126:129]
	s_setprio 0
	s_barrier
	s_mov_b32 m0, s43
	ds_read_b128 v[162:165], v247 offset:16384
	ds_read_b128 v[166:169], v247 offset:18432
	ds_read_b128 v[170:173], v248 offset:16384
	ds_read_b128 v[174:177], v248 offset:18432
	ds_read_b128 v[178:181], v247 offset:20480
	ds_read_b128 v[182:185], v247 offset:22528
	ds_read_b128 v[186:189], v248 offset:20480
	ds_read_b128 v[190:193], v248 offset:22528
	buffer_load_dwordx4 v231, s[8:11], s31 offen lds
	s_mov_b32 m0, s44
	s_add_i32 s34, s31, 0x100000
	buffer_load_dwordx4 v234, s[8:11], s31 offen lds
	s_mov_b32 m0, s45
	s_nop 0
	buffer_load_dwordx4 v231, s[8:11], s34 offen lds
	s_mov_b32 m0, s47
	s_nop 0
	buffer_load_dwordx4 v234, s[8:11], s34 offen lds
	s_mov_b32 m0, s42
	s_nop 0
	buffer_load_dwordx4 v230, s[8:11], s33 offen lds
	s_mov_b32 m0, s48
	s_nop 0
	buffer_load_dwordx4 v233, s[8:11], s33 offen lds
	s_waitcnt vmcnt(8)
	s_waitcnt lgkmcnt(0)
	s_barrier
	s_setprio 1
	s_waitcnt lgkmcnt(7)
	s_nop 0
	v_mfma_f32_16x16x32_bf16 v[10:13], v[130:133], v[162:165], v[10:13]
	v_mfma_f32_16x16x32_bf16 v[6:9], v[138:141], v[162:165], v[6:9]
	s_waitcnt lgkmcnt(6)
	s_nop 0
	v_mfma_f32_16x16x32_bf16 v[0:3], v[130:133], v[166:169], v[2:5]
	v_mfma_f32_16x16x32_bf16 v[18:21], v[138:141], v[166:169], v[18:21]
	s_waitcnt lgkmcnt(3)
	s_nop 0
	v_mfma_f32_16x16x32_bf16 v[14:17], v[130:133], v[178:181], v[14:17]
	v_mfma_f32_16x16x32_bf16 v[26:29], v[138:141], v[178:181], v[26:29]
	s_waitcnt lgkmcnt(2)
	s_nop 0
	v_mfma_f32_16x16x32_bf16 v[22:25], v[130:133], v[182:185], v[22:25]
	v_mfma_f32_16x16x32_bf16 v[38:41], v[138:141], v[182:185], v[38:41]
	v_mfma_f32_16x16x32_bf16 v[10:13], v[134:137], v[170:173], v[10:13]
	v_mfma_f32_16x16x32_bf16 v[6:9], v[142:145], v[170:173], v[6:9]
	v_mfma_f32_16x16x32_bf16 v[0:3], v[134:137], v[174:177], v[0:3]
	v_mfma_f32_16x16x32_bf16 v[18:21], v[142:145], v[174:177], v[18:21]
	s_waitcnt lgkmcnt(1)
	s_nop 0
	v_mfma_f32_16x16x32_bf16 v[14:17], v[134:137], v[186:189], v[14:17]
	v_mfma_f32_16x16x32_bf16 v[26:29], v[142:145], v[186:189], v[26:29]
	s_waitcnt lgkmcnt(0)
	s_nop 0
	v_mfma_f32_16x16x32_bf16 v[22:25], v[134:137], v[190:193], v[22:25]
	v_mfma_f32_16x16x32_bf16 v[38:41], v[142:145], v[190:193], v[38:41]
	s_setprio 0
	s_setprio 1
	v_mfma_f32_16x16x32_bf16 v[34:37], v[146:149], v[162:165], v[34:37]
	v_mfma_f32_16x16x32_bf16 v[30:33], v[154:157], v[162:165], v[30:33]
	v_mfma_f32_16x16x32_bf16 v[42:45], v[146:149], v[166:169], v[42:45]
	v_mfma_f32_16x16x32_bf16 v[46:49], v[154:157], v[166:169], v[46:49]
	v_mfma_f32_16x16x32_bf16 v[50:53], v[146:149], v[178:181], v[50:53]
	v_mfma_f32_16x16x32_bf16 v[54:57], v[154:157], v[178:181], v[54:57]
	v_mfma_f32_16x16x32_bf16 v[58:61], v[146:149], v[182:185], v[58:61]
	v_mfma_f32_16x16x32_bf16 v[62:65], v[154:157], v[182:185], v[62:65]
	v_mfma_f32_16x16x32_bf16 v[34:37], v[150:153], v[170:173], v[34:37]
	v_mfma_f32_16x16x32_bf16 v[30:33], v[158:161], v[170:173], v[30:33]
	v_mfma_f32_16x16x32_bf16 v[42:45], v[150:153], v[174:177], v[42:45]
	v_mfma_f32_16x16x32_bf16 v[46:49], v[158:161], v[174:177], v[46:49]
	v_mfma_f32_16x16x32_bf16 v[50:53], v[150:153], v[186:189], v[50:53]
	v_mfma_f32_16x16x32_bf16 v[54:57], v[158:161], v[186:189], v[54:57]
	v_mfma_f32_16x16x32_bf16 v[58:61], v[150:153], v[190:193], v[58:61]
	v_mfma_f32_16x16x32_bf16 v[62:65], v[158:161], v[190:193], v[62:65]
	s_setprio 0
	s_barrier
	ds_read_b128 v[130:133], v194
	ds_read_b128 v[134:137], v195
	ds_read_b128 v[138:141], v196
	ds_read_b128 v[142:145], v197
	ds_read_b128 v[146:149], v198
	ds_read_b128 v[150:153], v199
	ds_read_b128 v[154:157], v200
	ds_read_b128 v[158:161], v201
	s_add_i32 s33, s33, 0x100000
	s_mov_b32 m0, s49
	ds_read_b128 v[162:165], v247 offset:32768
	ds_read_b128 v[166:169], v247 offset:34816
	ds_read_b128 v[170:173], v248 offset:32768
	ds_read_b128 v[174:177], v248 offset:34816
	ds_read_b128 v[178:181], v247 offset:36864
	ds_read_b128 v[182:185], v247 offset:38912
	ds_read_b128 v[186:189], v248 offset:36864
	ds_read_b128 v[190:193], v248 offset:38912
	buffer_load_dwordx4 v230, s[8:11], s33 offen lds
	s_mov_b32 m0, s50
	s_nop 0
	buffer_load_dwordx4 v233, s[8:11], s33 offen lds
	s_waitcnt vmcnt(8)
	s_waitcnt lgkmcnt(0)
	s_barrier
	s_setprio 1
	s_waitcnt lgkmcnt(7)
	v_mfma_f32_16x16x32_bf16 v[74:77], v[130:133], v[162:165], v[74:77]
	v_mfma_f32_16x16x32_bf16 v[70:73], v[138:141], v[162:165], v[70:73]
	s_waitcnt lgkmcnt(6)
	s_nop 0
	v_mfma_f32_16x16x32_bf16 v[66:69], v[130:133], v[166:169], v[66:69]
	v_mfma_f32_16x16x32_bf16 v[82:85], v[138:141], v[166:169], v[82:85]
	s_waitcnt lgkmcnt(3)
	s_nop 0
	v_mfma_f32_16x16x32_bf16 v[78:81], v[130:133], v[178:181], v[78:81]
	v_mfma_f32_16x16x32_bf16 v[90:93], v[138:141], v[178:181], v[90:93]
	s_waitcnt lgkmcnt(2)
	s_nop 0
	v_mfma_f32_16x16x32_bf16 v[86:89], v[130:133], v[182:185], v[86:89]
	v_mfma_f32_16x16x32_bf16 v[102:105], v[138:141], v[182:185], v[102:105]
	v_mfma_f32_16x16x32_bf16 v[74:77], v[134:137], v[170:173], v[74:77]
	v_mfma_f32_16x16x32_bf16 v[70:73], v[142:145], v[170:173], v[70:73]
	v_mfma_f32_16x16x32_bf16 v[66:69], v[134:137], v[174:177], v[66:69]
	v_mfma_f32_16x16x32_bf16 v[82:85], v[142:145], v[174:177], v[82:85]
	s_waitcnt lgkmcnt(1)
	s_nop 0
	v_mfma_f32_16x16x32_bf16 v[78:81], v[134:137], v[186:189], v[78:81]
	v_mfma_f32_16x16x32_bf16 v[90:93], v[142:145], v[186:189], v[90:93]
	s_waitcnt lgkmcnt(0)
	s_nop 0
	v_mfma_f32_16x16x32_bf16 v[86:89], v[134:137], v[190:193], v[86:89]
	v_mfma_f32_16x16x32_bf16 v[102:105], v[142:145], v[190:193], v[102:105]
	s_setprio 0
	s_setprio 1
	v_mfma_f32_16x16x32_bf16 v[98:101], v[146:149], v[162:165], v[98:101]
	v_mfma_f32_16x16x32_bf16 v[94:97], v[154:157], v[162:165], v[94:97]
	v_mfma_f32_16x16x32_bf16 v[106:109], v[146:149], v[166:169], v[106:109]
	v_mfma_f32_16x16x32_bf16 v[110:113], v[154:157], v[166:169], v[110:113]
	v_mfma_f32_16x16x32_bf16 v[114:117], v[146:149], v[178:181], v[114:117]
	v_mfma_f32_16x16x32_bf16 v[118:121], v[154:157], v[178:181], v[118:121]
	v_mfma_f32_16x16x32_bf16 v[122:125], v[146:149], v[182:185], v[122:125]
	v_mfma_f32_16x16x32_bf16 v[126:129], v[154:157], v[182:185], v[126:129]
	v_mfma_f32_16x16x32_bf16 v[98:101], v[150:153], v[170:173], v[98:101]
	v_mfma_f32_16x16x32_bf16 v[94:97], v[158:161], v[170:173], v[94:97]
	v_mfma_f32_16x16x32_bf16 v[106:109], v[150:153], v[174:177], v[106:109]
	v_mfma_f32_16x16x32_bf16 v[110:113], v[158:161], v[174:177], v[110:113]
	v_mfma_f32_16x16x32_bf16 v[114:117], v[150:153], v[186:189], v[114:117]
	v_mfma_f32_16x16x32_bf16 v[118:121], v[158:161], v[186:189], v[118:121]
	v_mfma_f32_16x16x32_bf16 v[122:125], v[150:153], v[190:193], v[122:125]
	v_mfma_f32_16x16x32_bf16 v[126:129], v[158:161], v[190:193], v[126:129]
	s_setprio 0
	s_barrier
	s_mov_b32 m0, s53
	s_add_i32 s33, s31, 0x80
	ds_read_b128 v[162:165], v247 offset:49152
	ds_read_b128 v[166:169], v247 offset:51200
	ds_read_b128 v[170:173], v248 offset:49152
	ds_read_b128 v[174:177], v248 offset:51200
	ds_read_b128 v[178:181], v247 offset:53248
	ds_read_b128 v[182:185], v247 offset:55296
	ds_read_b128 v[186:189], v248 offset:53248
	ds_read_b128 v[190:193], v248 offset:55296
	buffer_load_dwordx4 v231, s[8:11], s33 offen lds
	s_mov_b32 m0, s54
	s_add_i32 s31, s31, 0x100080
	buffer_load_dwordx4 v234, s[8:11], s33 offen lds
	s_mov_b32 m0, s57
	s_nop 0
	buffer_load_dwordx4 v231, s[8:11], s31 offen lds
	s_mov_b32 m0, s58
	s_nop 0
	buffer_load_dwordx4 v234, s[8:11], s31 offen lds
	s_mov_b32 m0, s55
	s_nop 0
	buffer_load_dwordx4 v230, s[8:11], s30 offen lds
	s_mov_b32 m0, s56
	s_nop 0
	buffer_load_dwordx4 v233, s[8:11], s30 offen lds
	s_waitcnt vmcnt(8)
	s_waitcnt lgkmcnt(0)
	s_barrier
	s_setprio 1
	s_waitcnt lgkmcnt(7)
	s_nop 0
	v_mfma_f32_16x16x32_bf16 v[10:13], v[130:133], v[162:165], v[10:13]
	v_mfma_f32_16x16x32_bf16 v[4:7], v[138:141], v[162:165], v[6:9]
	s_waitcnt lgkmcnt(6)
	s_nop 0
	v_mfma_f32_16x16x32_bf16 v[0:3], v[130:133], v[166:169], v[0:3]
	v_mfma_f32_16x16x32_bf16 v[18:21], v[138:141], v[166:169], v[18:21]
	s_waitcnt lgkmcnt(3)
	s_nop 0
	v_mfma_f32_16x16x32_bf16 v[14:17], v[130:133], v[178:181], v[14:17]
	v_mfma_f32_16x16x32_bf16 v[26:29], v[138:141], v[178:181], v[26:29]
	s_waitcnt lgkmcnt(2)
	s_nop 0
	v_mfma_f32_16x16x32_bf16 v[22:25], v[130:133], v[182:185], v[22:25]
	v_mfma_f32_16x16x32_bf16 v[38:41], v[138:141], v[182:185], v[38:41]
	v_mfma_f32_16x16x32_bf16 v[10:13], v[134:137], v[170:173], v[10:13]
	v_mfma_f32_16x16x32_bf16 v[6:9], v[142:145], v[170:173], v[4:7]
	v_mfma_f32_16x16x32_bf16 v[2:5], v[134:137], v[174:177], v[0:3]
	v_mfma_f32_16x16x32_bf16 v[18:21], v[142:145], v[174:177], v[18:21]
	s_waitcnt lgkmcnt(1)
	s_nop 0
	v_mfma_f32_16x16x32_bf16 v[14:17], v[134:137], v[186:189], v[14:17]
	v_mfma_f32_16x16x32_bf16 v[26:29], v[142:145], v[186:189], v[26:29]
	s_waitcnt lgkmcnt(0)
	s_nop 0
	v_mfma_f32_16x16x32_bf16 v[22:25], v[134:137], v[190:193], v[22:25]
	v_mfma_f32_16x16x32_bf16 v[38:41], v[142:145], v[190:193], v[38:41]
	s_setprio 0
	s_setprio 1
	v_mfma_f32_16x16x32_bf16 v[34:37], v[146:149], v[162:165], v[34:37]
	v_mfma_f32_16x16x32_bf16 v[30:33], v[154:157], v[162:165], v[30:33]
	v_mfma_f32_16x16x32_bf16 v[42:45], v[146:149], v[166:169], v[42:45]
	v_mfma_f32_16x16x32_bf16 v[46:49], v[154:157], v[166:169], v[46:49]
	v_mfma_f32_16x16x32_bf16 v[50:53], v[146:149], v[178:181], v[50:53]
	v_mfma_f32_16x16x32_bf16 v[54:57], v[154:157], v[178:181], v[54:57]
	v_mfma_f32_16x16x32_bf16 v[58:61], v[146:149], v[182:185], v[58:61]
	v_mfma_f32_16x16x32_bf16 v[62:65], v[154:157], v[182:185], v[62:65]
	v_mfma_f32_16x16x32_bf16 v[34:37], v[150:153], v[170:173], v[34:37]
	v_mfma_f32_16x16x32_bf16 v[30:33], v[158:161], v[170:173], v[30:33]
	v_mfma_f32_16x16x32_bf16 v[42:45], v[150:153], v[174:177], v[42:45]
	v_mfma_f32_16x16x32_bf16 v[46:49], v[158:161], v[174:177], v[46:49]
	v_mfma_f32_16x16x32_bf16 v[50:53], v[150:153], v[186:189], v[50:53]
	v_mfma_f32_16x16x32_bf16 v[54:57], v[158:161], v[186:189], v[54:57]
	v_mfma_f32_16x16x32_bf16 v[58:61], v[150:153], v[190:193], v[58:61]
	v_mfma_f32_16x16x32_bf16 v[62:65], v[158:161], v[190:193], v[62:65]
	s_setprio 0
	s_barrier
	s_add_i32 s4, s4, 2
	s_addk_i32 s5, 0x100
	s_cmp_gt_u32 s4, 61
	s_cbranch_scc0 .LBB0_1251
	s_and_b64 vcc, exec, s[18:19]
	s_cbranch_vccz .LBB0_1254
	s_barrier
